# GDN triangular solve: Am row elements read quad-distributed (ds_read2_b32, one element per lane) and broadcast inside the FMA with DPP quad_perm; same f32 FMA order
# speedup vs baseline: 1.1103x; 1.0045x over previous
; DI void phase_gdn_c1(const Ctx& c) {
;     ...
; #pragma unroll
;       for (int i = 1; i < 64; ++i) {
;         float s0 = sol[i], s1 = 0.f, s2 = 0.f, s3 = 0.f;
; #pragma unroll
;         for (int m = 0; m < i; ++m) {
;           const float t_ = Am[i * 68 + m] * sol[m];
;           if ((m & 3) == 0) s0 -= t_; else if ((m & 3) == 1) s1 -= t_; else if ((m & 3) == 2) s2 -= t_; else s3 -= t_;
;         }
;         sol[i] = (s0 + s1) + (s2 + s3);
;       }
.Lc1_noexp:
	s_or_b64 exec, exec, s[38:39]
	s_movk_i32 s38, 0x1000
	v_and_b32_e32 v250, 3, v189
	v_lshl_add_u32 v250, v250, 2, v56
	v_add_u32_e32 v251, 0x8910, v250
	ds_read2_b32 v[230:231], v251 offset0:0 offset1:0
	v_add_u32_e32 v251, 0x110, v251
	ds_read2_b32 v[232:233], v251 offset0:0 offset1:0
	v_add_u32_e32 v251, 0x110, v251
	ds_read2_b32 v[234:235], v251 offset0:0 offset1:0
	v_add_u32_e32 v251, 0x110, v251
	ds_read2_b32 v[236:237], v251 offset0:0 offset1:0
	v_add_u32_e32 v251, 0x110, v251
	ds_read2_b32 v[238:239], v251 offset0:0 offset1:4
	v_add_u32_e32 v251, 0x110, v251
	ds_read2_b32 v[240:241], v251 offset0:0 offset1:4
	v_add_u32_e32 v251, 0x110, v251
	ds_read2_b32 v[242:243], v251 offset0:0 offset1:4
	v_add_u32_e32 v251, 0x110, v251
	ds_read2_b32 v[244:245], v251 offset0:0 offset1:4
	v_mov_b32_e32 v2, v5
	s_waitcnt lgkmcnt(7)
	v_fmac_f32_dpp v2, -v230, v4 quad_perm:[0,0,0,0] row_mask:0xf bank_mask:0xf
	v_add_u32_e32 v251, 0x110, v251
	ds_read2_b32 v[230:231], v251 offset0:0 offset1:4
	v_mov_b32_e32 v3, v6
	s_waitcnt lgkmcnt(7)
	v_fmac_f32_dpp v3, -v232, v4 quad_perm:[0,0,0,0] row_mask:0xf bank_mask:0xf
	v_mul_f32_dpp v110, -v232, v2 quad_perm:[1,1,1,1] row_mask:0xf bank_mask:0xf
	ds_read2_b32 v[232:233], v251 offset0:8 offset1:8
	v_add_f32_e32 v3, v3, v110
	v_mov_b32_e32 v5, v7
	s_waitcnt lgkmcnt(7)
	v_fmac_f32_dpp v5, -v234, v4 quad_perm:[0,0,0,0] row_mask:0xf bank_mask:0xf
	v_mul_f32_dpp v110, -v234, v2 quad_perm:[1,1,1,1] row_mask:0xf bank_mask:0xf
	v_mul_f32_dpp v111, -v234, v3 quad_perm:[2,2,2,2] row_mask:0xf bank_mask:0xf
	v_add_u32_e32 v251, 0x110, v251
	ds_read2_b32 v[234:235], v251 offset0:0 offset1:4
	v_add_f32_e32 v5, v5, v110
	v_add_f32_e32 v5, v5, v111
	v_mov_b32_e32 v6, v8
	s_waitcnt lgkmcnt(7)
	v_fmac_f32_dpp v6, -v236, v4 quad_perm:[0,0,0,0] row_mask:0xf bank_mask:0xf
	v_mul_f32_dpp v110, -v236, v2 quad_perm:[1,1,1,1] row_mask:0xf bank_mask:0xf
	v_mul_f32_dpp v111, -v236, v3 quad_perm:[2,2,2,2] row_mask:0xf bank_mask:0xf
	v_mul_f32_dpp v112, -v236, v5 quad_perm:[3,3,3,3] row_mask:0xf bank_mask:0xf
	ds_read2_b32 v[236:237], v251 offset0:8 offset1:8
	v_add_f32_e32 v6, v6, v110
	v_add_f32_e32 v111, v111, v112
	v_add_f32_e32 v6, v6, v111
	v_mov_b32_e32 v7, v9
	s_waitcnt lgkmcnt(7)
	v_fmac_f32_dpp v7, -v238, v4 quad_perm:[0,0,0,0] row_mask:0xf bank_mask:0xf
	v_mul_f32_dpp v110, -v238, v2 quad_perm:[1,1,1,1] row_mask:0xf bank_mask:0xf
	v_mul_f32_dpp v111, -v238, v3 quad_perm:[2,2,2,2] row_mask:0xf bank_mask:0xf
	v_mul_f32_dpp v112, -v238, v5 quad_perm:[3,3,3,3] row_mask:0xf bank_mask:0xf
	v_fmac_f32_dpp v7, -v239, v6 quad_perm:[0,0,0,0] row_mask:0xf bank_mask:0xf
	v_add_u32_e32 v251, 0x110, v251
	ds_read2_b32 v[238:239], v251 offset0:0 offset1:4
	v_add_f32_e32 v7, v7, v110
	v_add_f32_e32 v111, v111, v112
	v_add_f32_e32 v7, v7, v111
	v_mov_b32_e32 v8, v10
	s_waitcnt lgkmcnt(7)
	v_fmac_f32_dpp v8, -v240, v4 quad_perm:[0,0,0,0] row_mask:0xf bank_mask:0xf
	v_mul_f32_dpp v110, -v240, v2 quad_perm:[1,1,1,1] row_mask:0xf bank_mask:0xf
	v_mul_f32_dpp v111, -v240, v3 quad_perm:[2,2,2,2] row_mask:0xf bank_mask:0xf
	v_mul_f32_dpp v112, -v240, v5 quad_perm:[3,3,3,3] row_mask:0xf bank_mask:0xf
	v_fmac_f32_dpp v8, -v241, v6 quad_perm:[0,0,0,0] row_mask:0xf bank_mask:0xf
	v_fmac_f32_dpp v110, -v241, v7 quad_perm:[1,1,1,1] row_mask:0xf bank_mask:0xf
	ds_read2_b32 v[240:241], v251 offset0:8 offset1:8
	v_add_f32_e32 v8, v8, v110
	v_add_f32_e32 v111, v111, v112
	v_add_f32_e32 v8, v8, v111
	v_mov_b32_e32 v9, v12
	s_waitcnt lgkmcnt(7)
	v_fmac_f32_dpp v9, -v242, v4 quad_perm:[0,0,0,0] row_mask:0xf bank_mask:0xf
	v_mul_f32_dpp v110, -v242, v2 quad_perm:[1,1,1,1] row_mask:0xf bank_mask:0xf
	v_mul_f32_dpp v111, -v242, v3 quad_perm:[2,2,2,2] row_mask:0xf bank_mask:0xf
	v_mul_f32_dpp v112, -v242, v5 quad_perm:[3,3,3,3] row_mask:0xf bank_mask:0xf
	v_fmac_f32_dpp v9, -v243, v6 quad_perm:[0,0,0,0] row_mask:0xf bank_mask:0xf
	v_fmac_f32_dpp v110, -v243, v7 quad_perm:[1,1,1,1] row_mask:0xf bank_mask:0xf
	v_fmac_f32_dpp v111, -v243, v8 quad_perm:[2,2,2,2] row_mask:0xf bank_mask:0xf
	v_add_u32_e32 v251, 0x110, v251
	ds_read2_b32 v[242:243], v251 offset0:0 offset1:4
	v_add_f32_e32 v9, v9, v110
	v_add_f32_e32 v111, v111, v112
	v_add_f32_e32 v9, v9, v111
	v_mov_b32_e32 v10, v13
	s_waitcnt lgkmcnt(7)
	v_fmac_f32_dpp v10, -v244, v4 quad_perm:[0,0,0,0] row_mask:0xf bank_mask:0xf
	v_mul_f32_dpp v110, -v244, v2 quad_perm:[1,1,1,1] row_mask:0xf bank_mask:0xf
	v_mul_f32_dpp v111, -v244, v3 quad_perm:[2,2,2,2] row_mask:0xf bank_mask:0xf
	v_mul_f32_dpp v112, -v244, v5 quad_perm:[3,3,3,3] row_mask:0xf bank_mask:0xf
	v_fmac_f32_dpp v10, -v245, v6 quad_perm:[0,0,0,0] row_mask:0xf bank_mask:0xf
	v_fmac_f32_dpp v110, -v245, v7 quad_perm:[1,1,1,1] row_mask:0xf bank_mask:0xf
	v_fmac_f32_dpp v111, -v245, v8 quad_perm:[2,2,2,2] row_mask:0xf bank_mask:0xf
	v_fmac_f32_dpp v112, -v245, v9 quad_perm:[3,3,3,3] row_mask:0xf bank_mask:0xf
	ds_read2_b32 v[244:245], v251 offset0:8 offset1:8
	v_add_f32_e32 v10, v10, v110
	v_add_f32_e32 v111, v111, v112
	v_add_f32_e32 v10, v10, v111
	v_mov_b32_e32 v12, v15
	s_waitcnt lgkmcnt(7)
	v_fmac_f32_dpp v12, -v230, v4 quad_perm:[0,0,0,0] row_mask:0xf bank_mask:0xf
	v_mul_f32_dpp v110, -v230, v2 quad_perm:[1,1,1,1] row_mask:0xf bank_mask:0xf
	v_mul_f32_dpp v111, -v230, v3 quad_perm:[2,2,2,2] row_mask:0xf bank_mask:0xf
	v_mul_f32_dpp v112, -v230, v5 quad_perm:[3,3,3,3] row_mask:0xf bank_mask:0xf
	v_fmac_f32_dpp v12, -v231, v6 quad_perm:[0,0,0,0] row_mask:0xf bank_mask:0xf
	v_fmac_f32_dpp v110, -v231, v7 quad_perm:[1,1,1,1] row_mask:0xf bank_mask:0xf
	v_fmac_f32_dpp v111, -v231, v8 quad_perm:[2,2,2,2] row_mask:0xf bank_mask:0xf
	v_fmac_f32_dpp v112, -v231, v9 quad_perm:[3,3,3,3] row_mask:0xf bank_mask:0xf
	v_add_u32_e32 v251, 0x110, v251
	ds_read2_b32 v[230:231], v251 offset0:0 offset1:4
	s_waitcnt lgkmcnt(7)
; DI void phase_gdn_c1(const Ctx& c) {
;     ...
; #pragma unroll
;       for (int i = 1; i < 64; ++i) {
;         float s0 = sol[i], s1 = 0.f, s2 = 0.f, s3 = 0.f;
; #pragma unroll
;         for (int m = 0; m < i; ++m) {
;           const float t_ = Am[i * 68 + m] * sol[m];
;           if ((m & 3) == 0) s0 -= t_; else if ((m & 3) == 1) s1 -= t_; else if ((m & 3) == 2) s2 -= t_; else s3 -= t_;
;         }
;         sol[i] = (s0 + s1) + (s2 + s3);
;       }
	v_fmac_f32_dpp v12, -v232, v10 quad_perm:[0,0,0,0] row_mask:0xf bank_mask:0xf
	ds_read2_b32 v[232:233], v251 offset0:8 offset1:12
	v_add_f32_e32 v12, v12, v110
	v_add_f32_e32 v111, v111, v112
	v_add_f32_e32 v12, v12, v111
	v_mov_b32_e32 v13, v14
	s_waitcnt lgkmcnt(7)
	v_fmac_f32_dpp v13, -v234, v4 quad_perm:[0,0,0,0] row_mask:0xf bank_mask:0xf
	v_mul_f32_dpp v110, -v234, v2 quad_perm:[1,1,1,1] row_mask:0xf bank_mask:0xf
	v_mul_f32_dpp v111, -v234, v3 quad_perm:[2,2,2,2] row_mask:0xf bank_mask:0xf
	v_mul_f32_dpp v112, -v234, v5 quad_perm:[3,3,3,3] row_mask:0xf bank_mask:0xf
	v_fmac_f32_dpp v13, -v235, v6 quad_perm:[0,0,0,0] row_mask:0xf bank_mask:0xf
	v_fmac_f32_dpp v110, -v235, v7 quad_perm:[1,1,1,1] row_mask:0xf bank_mask:0xf
	v_fmac_f32_dpp v111, -v235, v8 quad_perm:[2,2,2,2] row_mask:0xf bank_mask:0xf
	v_fmac_f32_dpp v112, -v235, v9 quad_perm:[3,3,3,3] row_mask:0xf bank_mask:0xf
	v_add_u32_e32 v251, 0x110, v251
	ds_read2_b32 v[234:235], v251 offset0:0 offset1:4
	s_waitcnt lgkmcnt(7)
	v_fmac_f32_dpp v13, -v236, v10 quad_perm:[0,0,0,0] row_mask:0xf bank_mask:0xf
	v_fmac_f32_dpp v110, -v236, v12 quad_perm:[1,1,1,1] row_mask:0xf bank_mask:0xf
	ds_read2_b32 v[236:237], v251 offset0:8 offset1:12
	v_add_f32_e32 v13, v13, v110
	v_add_f32_e32 v111, v111, v112
	v_add_f32_e32 v13, v13, v111
	v_mov_b32_e32 v14, v109
	s_waitcnt lgkmcnt(7)
	v_fmac_f32_dpp v14, -v238, v4 quad_perm:[0,0,0,0] row_mask:0xf bank_mask:0xf
	v_mul_f32_dpp v110, -v238, v2 quad_perm:[1,1,1,1] row_mask:0xf bank_mask:0xf
	v_mul_f32_dpp v111, -v238, v3 quad_perm:[2,2,2,2] row_mask:0xf bank_mask:0xf
	v_mul_f32_dpp v112, -v238, v5 quad_perm:[3,3,3,3] row_mask:0xf bank_mask:0xf
	v_fmac_f32_dpp v14, -v239, v6 quad_perm:[0,0,0,0] row_mask:0xf bank_mask:0xf
	v_fmac_f32_dpp v110, -v239, v7 quad_perm:[1,1,1,1] row_mask:0xf bank_mask:0xf
	v_fmac_f32_dpp v111, -v239, v8 quad_perm:[2,2,2,2] row_mask:0xf bank_mask:0xf
	v_fmac_f32_dpp v112, -v239, v9 quad_perm:[3,3,3,3] row_mask:0xf bank_mask:0xf
	v_add_u32_e32 v251, 0x110, v251
	ds_read2_b32 v[238:239], v251 offset0:0 offset1:4
	s_waitcnt lgkmcnt(7)
	v_fmac_f32_dpp v14, -v240, v10 quad_perm:[0,0,0,0] row_mask:0xf bank_mask:0xf
	v_fmac_f32_dpp v110, -v240, v12 quad_perm:[1,1,1,1] row_mask:0xf bank_mask:0xf
	v_fmac_f32_dpp v111, -v240, v13 quad_perm:[2,2,2,2] row_mask:0xf bank_mask:0xf
	ds_read2_b32 v[240:241], v251 offset0:8 offset1:12
	v_add_f32_e32 v14, v14, v110
	v_add_f32_e32 v111, v111, v112
	v_add_f32_e32 v14, v14, v111
	v_mov_b32_e32 v15, v17
	s_waitcnt lgkmcnt(7)
	v_fmac_f32_dpp v15, -v242, v4 quad_perm:[0,0,0,0] row_mask:0xf bank_mask:0xf
	v_mul_f32_dpp v110, -v242, v2 quad_perm:[1,1,1,1] row_mask:0xf bank_mask:0xf
	v_mul_f32_dpp v111, -v242, v3 quad_perm:[2,2,2,2] row_mask:0xf bank_mask:0xf
	v_mul_f32_dpp v112, -v242, v5 quad_perm:[3,3,3,3] row_mask:0xf bank_mask:0xf
	v_fmac_f32_dpp v15, -v243, v6 quad_perm:[0,0,0,0] row_mask:0xf bank_mask:0xf
	v_fmac_f32_dpp v110, -v243, v7 quad_perm:[1,1,1,1] row_mask:0xf bank_mask:0xf
	v_fmac_f32_dpp v111, -v243, v8 quad_perm:[2,2,2,2] row_mask:0xf bank_mask:0xf
	v_fmac_f32_dpp v112, -v243, v9 quad_perm:[3,3,3,3] row_mask:0xf bank_mask:0xf
	v_add_u32_e32 v251, 0x110, v251
	ds_read2_b32 v[242:243], v251 offset0:0 offset1:4
	s_waitcnt lgkmcnt(7)
	v_fmac_f32_dpp v15, -v244, v10 quad_perm:[0,0,0,0] row_mask:0xf bank_mask:0xf
	v_fmac_f32_dpp v110, -v244, v12 quad_perm:[1,1,1,1] row_mask:0xf bank_mask:0xf
	v_fmac_f32_dpp v111, -v244, v13 quad_perm:[2,2,2,2] row_mask:0xf bank_mask:0xf
	v_fmac_f32_dpp v112, -v244, v14 quad_perm:[3,3,3,3] row_mask:0xf bank_mask:0xf
	ds_read2_b32 v[244:245], v251 offset0:8 offset1:12
	v_add_f32_e32 v15, v15, v110
	v_add_f32_e32 v111, v111, v112
	v_add_f32_e32 v15, v15, v111
	v_mov_b32_e32 v17, v108
	s_waitcnt lgkmcnt(7)
	v_fmac_f32_dpp v17, -v230, v4 quad_perm:[0,0,0,0] row_mask:0xf bank_mask:0xf
	v_mul_f32_dpp v110, -v230, v2 quad_perm:[1,1,1,1] row_mask:0xf bank_mask:0xf
	v_mul_f32_dpp v111, -v230, v3 quad_perm:[2,2,2,2] row_mask:0xf bank_mask:0xf
	v_mul_f32_dpp v112, -v230, v5 quad_perm:[3,3,3,3] row_mask:0xf bank_mask:0xf
	v_fmac_f32_dpp v17, -v231, v6 quad_perm:[0,0,0,0] row_mask:0xf bank_mask:0xf
	v_fmac_f32_dpp v110, -v231, v7 quad_perm:[1,1,1,1] row_mask:0xf bank_mask:0xf
	v_fmac_f32_dpp v111, -v231, v8 quad_perm:[2,2,2,2] row_mask:0xf bank_mask:0xf
	v_fmac_f32_dpp v112, -v231, v9 quad_perm:[3,3,3,3] row_mask:0xf bank_mask:0xf
	v_add_u32_e32 v251, 0x110, v251
	ds_read2_b32 v[230:231], v251 offset0:0 offset1:4
	s_waitcnt lgkmcnt(7)
	v_fmac_f32_dpp v17, -v232, v10 quad_perm:[0,0,0,0] row_mask:0xf bank_mask:0xf
	v_fmac_f32_dpp v110, -v232, v12 quad_perm:[1,1,1,1] row_mask:0xf bank_mask:0xf
	v_fmac_f32_dpp v111, -v232, v13 quad_perm:[2,2,2,2] row_mask:0xf bank_mask:0xf
	v_fmac_f32_dpp v112, -v232, v14 quad_perm:[3,3,3,3] row_mask:0xf bank_mask:0xf
	v_fmac_f32_dpp v17, -v233, v15 quad_perm:[0,0,0,0] row_mask:0xf bank_mask:0xf
	ds_read2_b32 v[232:233], v251 offset0:8 offset1:12
	v_add_f32_e32 v17, v17, v110
	v_add_f32_e32 v111, v111, v112
	v_add_f32_e32 v17, v17, v111
	s_waitcnt lgkmcnt(7)
	v_fmac_f32_dpp v18, -v234, v4 quad_perm:[0,0,0,0] row_mask:0xf bank_mask:0xf
	v_mul_f32_dpp v110, -v234, v2 quad_perm:[1,1,1,1] row_mask:0xf bank_mask:0xf
	v_mul_f32_dpp v111, -v234, v3 quad_perm:[2,2,2,2] row_mask:0xf bank_mask:0xf
	v_mul_f32_dpp v112, -v234, v5 quad_perm:[3,3,3,3] row_mask:0xf bank_mask:0xf
	v_fmac_f32_dpp v18, -v235, v6 quad_perm:[0,0,0,0] row_mask:0xf bank_mask:0xf
	v_fmac_f32_dpp v110, -v235, v7 quad_perm:[1,1,1,1] row_mask:0xf bank_mask:0xf
	v_fmac_f32_dpp v111, -v235, v8 quad_perm:[2,2,2,2] row_mask:0xf bank_mask:0xf
	v_fmac_f32_dpp v112, -v235, v9 quad_perm:[3,3,3,3] row_mask:0xf bank_mask:0xf
	ds_read2_b32 v[234:235], v251 offset0:16 offset1:16
	s_waitcnt lgkmcnt(7)
; DI void phase_gdn_c1(const Ctx& c) {
;     ...
; #pragma unroll
;       for (int i = 1; i < 64; ++i) {
;         float s0 = sol[i], s1 = 0.f, s2 = 0.f, s3 = 0.f;
; #pragma unroll
;         for (int m = 0; m < i; ++m) {
;           const float t_ = Am[i * 68 + m] * sol[m];
;           if ((m & 3) == 0) s0 -= t_; else if ((m & 3) == 1) s1 -= t_; else if ((m & 3) == 2) s2 -= t_; else s3 -= t_;
;         }
;         sol[i] = (s0 + s1) + (s2 + s3);
;       }
	v_fmac_f32_dpp v18, -v236, v10 quad_perm:[0,0,0,0] row_mask:0xf bank_mask:0xf
	v_fmac_f32_dpp v110, -v236, v12 quad_perm:[1,1,1,1] row_mask:0xf bank_mask:0xf
	v_fmac_f32_dpp v111, -v236, v13 quad_perm:[2,2,2,2] row_mask:0xf bank_mask:0xf
	v_fmac_f32_dpp v112, -v236, v14 quad_perm:[3,3,3,3] row_mask:0xf bank_mask:0xf
	v_fmac_f32_dpp v18, -v237, v15 quad_perm:[0,0,0,0] row_mask:0xf bank_mask:0xf
	v_fmac_f32_dpp v110, -v237, v17 quad_perm:[1,1,1,1] row_mask:0xf bank_mask:0xf
	v_add_u32_e32 v251, 0x110, v251
	ds_read2_b32 v[236:237], v251 offset0:0 offset1:4
	v_add_f32_e32 v18, v18, v110
	v_add_f32_e32 v111, v111, v112
	v_add_f32_e32 v18, v18, v111
	s_waitcnt lgkmcnt(7)
	v_fmac_f32_dpp v19, -v238, v4 quad_perm:[0,0,0,0] row_mask:0xf bank_mask:0xf
	v_mul_f32_dpp v110, -v238, v2 quad_perm:[1,1,1,1] row_mask:0xf bank_mask:0xf
	v_mul_f32_dpp v111, -v238, v3 quad_perm:[2,2,2,2] row_mask:0xf bank_mask:0xf
	v_mul_f32_dpp v112, -v238, v5 quad_perm:[3,3,3,3] row_mask:0xf bank_mask:0xf
	v_fmac_f32_dpp v19, -v239, v6 quad_perm:[0,0,0,0] row_mask:0xf bank_mask:0xf
	v_fmac_f32_dpp v110, -v239, v7 quad_perm:[1,1,1,1] row_mask:0xf bank_mask:0xf
	v_fmac_f32_dpp v111, -v239, v8 quad_perm:[2,2,2,2] row_mask:0xf bank_mask:0xf
	v_fmac_f32_dpp v112, -v239, v9 quad_perm:[3,3,3,3] row_mask:0xf bank_mask:0xf
	ds_read2_b32 v[238:239], v251 offset0:8 offset1:12
	s_waitcnt lgkmcnt(7)
	v_fmac_f32_dpp v19, -v240, v10 quad_perm:[0,0,0,0] row_mask:0xf bank_mask:0xf
	v_fmac_f32_dpp v110, -v240, v12 quad_perm:[1,1,1,1] row_mask:0xf bank_mask:0xf
	v_fmac_f32_dpp v111, -v240, v13 quad_perm:[2,2,2,2] row_mask:0xf bank_mask:0xf
	v_fmac_f32_dpp v112, -v240, v14 quad_perm:[3,3,3,3] row_mask:0xf bank_mask:0xf
	v_fmac_f32_dpp v19, -v241, v15 quad_perm:[0,0,0,0] row_mask:0xf bank_mask:0xf
	v_fmac_f32_dpp v110, -v241, v17 quad_perm:[1,1,1,1] row_mask:0xf bank_mask:0xf
	v_fmac_f32_dpp v111, -v241, v18 quad_perm:[2,2,2,2] row_mask:0xf bank_mask:0xf
	ds_read2_b32 v[240:241], v251 offset0:16 offset1:16
	v_add_f32_e32 v19, v19, v110
	v_add_f32_e32 v111, v111, v112
	v_add_f32_e32 v19, v19, v111
	s_waitcnt lgkmcnt(7)
	v_fmac_f32_dpp v21, -v242, v4 quad_perm:[0,0,0,0] row_mask:0xf bank_mask:0xf
	v_mul_f32_dpp v110, -v242, v2 quad_perm:[1,1,1,1] row_mask:0xf bank_mask:0xf
	v_mul_f32_dpp v111, -v242, v3 quad_perm:[2,2,2,2] row_mask:0xf bank_mask:0xf
	v_mul_f32_dpp v112, -v242, v5 quad_perm:[3,3,3,3] row_mask:0xf bank_mask:0xf
	v_fmac_f32_dpp v21, -v243, v6 quad_perm:[0,0,0,0] row_mask:0xf bank_mask:0xf
	v_fmac_f32_dpp v110, -v243, v7 quad_perm:[1,1,1,1] row_mask:0xf bank_mask:0xf
	v_fmac_f32_dpp v111, -v243, v8 quad_perm:[2,2,2,2] row_mask:0xf bank_mask:0xf
	v_fmac_f32_dpp v112, -v243, v9 quad_perm:[3,3,3,3] row_mask:0xf bank_mask:0xf
	v_add_u32_e32 v251, 0x110, v251
	ds_read2_b32 v[242:243], v251 offset0:0 offset1:4
	s_waitcnt lgkmcnt(7)
	v_fmac_f32_dpp v21, -v244, v10 quad_perm:[0,0,0,0] row_mask:0xf bank_mask:0xf
	v_fmac_f32_dpp v110, -v244, v12 quad_perm:[1,1,1,1] row_mask:0xf bank_mask:0xf
	v_fmac_f32_dpp v111, -v244, v13 quad_perm:[2,2,2,2] row_mask:0xf bank_mask:0xf
	v_fmac_f32_dpp v112, -v244, v14 quad_perm:[3,3,3,3] row_mask:0xf bank_mask:0xf
	v_fmac_f32_dpp v21, -v245, v15 quad_perm:[0,0,0,0] row_mask:0xf bank_mask:0xf
	v_fmac_f32_dpp v110, -v245, v17 quad_perm:[1,1,1,1] row_mask:0xf bank_mask:0xf
	v_fmac_f32_dpp v111, -v245, v18 quad_perm:[2,2,2,2] row_mask:0xf bank_mask:0xf
	v_fmac_f32_dpp v112, -v245, v19 quad_perm:[3,3,3,3] row_mask:0xf bank_mask:0xf
	ds_read2_b32 v[244:245], v251 offset0:8 offset1:12
	v_add_f32_e32 v21, v21, v110
	v_add_f32_e32 v111, v111, v112
	v_add_f32_e32 v21, v21, v111
	s_waitcnt lgkmcnt(7)
	v_fmac_f32_dpp v22, -v230, v4 quad_perm:[0,0,0,0] row_mask:0xf bank_mask:0xf
	v_mul_f32_dpp v110, -v230, v2 quad_perm:[1,1,1,1] row_mask:0xf bank_mask:0xf
	v_mul_f32_dpp v111, -v230, v3 quad_perm:[2,2,2,2] row_mask:0xf bank_mask:0xf
	v_mul_f32_dpp v112, -v230, v5 quad_perm:[3,3,3,3] row_mask:0xf bank_mask:0xf
	v_fmac_f32_dpp v22, -v231, v6 quad_perm:[0,0,0,0] row_mask:0xf bank_mask:0xf
	v_fmac_f32_dpp v110, -v231, v7 quad_perm:[1,1,1,1] row_mask:0xf bank_mask:0xf
	v_fmac_f32_dpp v111, -v231, v8 quad_perm:[2,2,2,2] row_mask:0xf bank_mask:0xf
	v_fmac_f32_dpp v112, -v231, v9 quad_perm:[3,3,3,3] row_mask:0xf bank_mask:0xf
	ds_read2_b32 v[230:231], v251 offset0:16 offset1:16
	s_waitcnt lgkmcnt(7)
	v_fmac_f32_dpp v22, -v232, v10 quad_perm:[0,0,0,0] row_mask:0xf bank_mask:0xf
	v_fmac_f32_dpp v110, -v232, v12 quad_perm:[1,1,1,1] row_mask:0xf bank_mask:0xf
	v_fmac_f32_dpp v111, -v232, v13 quad_perm:[2,2,2,2] row_mask:0xf bank_mask:0xf
	v_fmac_f32_dpp v112, -v232, v14 quad_perm:[3,3,3,3] row_mask:0xf bank_mask:0xf
	v_fmac_f32_dpp v22, -v233, v15 quad_perm:[0,0,0,0] row_mask:0xf bank_mask:0xf
	v_fmac_f32_dpp v110, -v233, v17 quad_perm:[1,1,1,1] row_mask:0xf bank_mask:0xf
	v_fmac_f32_dpp v111, -v233, v18 quad_perm:[2,2,2,2] row_mask:0xf bank_mask:0xf
	v_fmac_f32_dpp v112, -v233, v19 quad_perm:[3,3,3,3] row_mask:0xf bank_mask:0xf
	v_add_u32_e32 v251, 0x110, v251
	ds_read2_b32 v[232:233], v251 offset0:0 offset1:4
	s_waitcnt lgkmcnt(7)
	v_fmac_f32_dpp v22, -v234, v21 quad_perm:[0,0,0,0] row_mask:0xf bank_mask:0xf
	ds_read2_b32 v[234:235], v251 offset0:8 offset1:12
	v_add_f32_e32 v22, v22, v110
	v_add_f32_e32 v111, v111, v112
	v_add_f32_e32 v22, v22, v111
	s_waitcnt lgkmcnt(7)
; DI void phase_gdn_c1(const Ctx& c) {
;     ...
; #pragma unroll
;       for (int i = 1; i < 64; ++i) {
;         float s0 = sol[i], s1 = 0.f, s2 = 0.f, s3 = 0.f;
; #pragma unroll
;         for (int m = 0; m < i; ++m) {
;           const float t_ = Am[i * 68 + m] * sol[m];
;           if ((m & 3) == 0) s0 -= t_; else if ((m & 3) == 1) s1 -= t_; else if ((m & 3) == 2) s2 -= t_; else s3 -= t_;
;         }
;         sol[i] = (s0 + s1) + (s2 + s3);
;       }
	v_fmac_f32_dpp v23, -v236, v4 quad_perm:[0,0,0,0] row_mask:0xf bank_mask:0xf
	v_mul_f32_dpp v110, -v236, v2 quad_perm:[1,1,1,1] row_mask:0xf bank_mask:0xf
	v_mul_f32_dpp v111, -v236, v3 quad_perm:[2,2,2,2] row_mask:0xf bank_mask:0xf
	v_mul_f32_dpp v112, -v236, v5 quad_perm:[3,3,3,3] row_mask:0xf bank_mask:0xf
	v_fmac_f32_dpp v23, -v237, v6 quad_perm:[0,0,0,0] row_mask:0xf bank_mask:0xf
	v_fmac_f32_dpp v110, -v237, v7 quad_perm:[1,1,1,1] row_mask:0xf bank_mask:0xf
	v_fmac_f32_dpp v111, -v237, v8 quad_perm:[2,2,2,2] row_mask:0xf bank_mask:0xf
	v_fmac_f32_dpp v112, -v237, v9 quad_perm:[3,3,3,3] row_mask:0xf bank_mask:0xf
	ds_read2_b32 v[236:237], v251 offset0:16 offset1:16
	s_waitcnt lgkmcnt(7)
	v_fmac_f32_dpp v23, -v238, v10 quad_perm:[0,0,0,0] row_mask:0xf bank_mask:0xf
	v_fmac_f32_dpp v110, -v238, v12 quad_perm:[1,1,1,1] row_mask:0xf bank_mask:0xf
	v_fmac_f32_dpp v111, -v238, v13 quad_perm:[2,2,2,2] row_mask:0xf bank_mask:0xf
	v_fmac_f32_dpp v112, -v238, v14 quad_perm:[3,3,3,3] row_mask:0xf bank_mask:0xf
	v_fmac_f32_dpp v23, -v239, v15 quad_perm:[0,0,0,0] row_mask:0xf bank_mask:0xf
	v_fmac_f32_dpp v110, -v239, v17 quad_perm:[1,1,1,1] row_mask:0xf bank_mask:0xf
	v_fmac_f32_dpp v111, -v239, v18 quad_perm:[2,2,2,2] row_mask:0xf bank_mask:0xf
	v_fmac_f32_dpp v112, -v239, v19 quad_perm:[3,3,3,3] row_mask:0xf bank_mask:0xf
	v_add_u32_e32 v251, 0x110, v251
	ds_read2_b32 v[238:239], v251 offset0:0 offset1:4
	s_waitcnt lgkmcnt(7)
	v_fmac_f32_dpp v23, -v240, v21 quad_perm:[0,0,0,0] row_mask:0xf bank_mask:0xf
	v_fmac_f32_dpp v110, -v240, v22 quad_perm:[1,1,1,1] row_mask:0xf bank_mask:0xf
	ds_read2_b32 v[240:241], v251 offset0:8 offset1:12
	v_add_f32_e32 v23, v23, v110
	v_add_f32_e32 v111, v111, v112
	v_add_f32_e32 v23, v23, v111
	s_waitcnt lgkmcnt(7)
	v_fmac_f32_dpp v25, -v242, v4 quad_perm:[0,0,0,0] row_mask:0xf bank_mask:0xf
	v_mul_f32_dpp v110, -v242, v2 quad_perm:[1,1,1,1] row_mask:0xf bank_mask:0xf
	v_mul_f32_dpp v111, -v242, v3 quad_perm:[2,2,2,2] row_mask:0xf bank_mask:0xf
	v_mul_f32_dpp v112, -v242, v5 quad_perm:[3,3,3,3] row_mask:0xf bank_mask:0xf
	v_fmac_f32_dpp v25, -v243, v6 quad_perm:[0,0,0,0] row_mask:0xf bank_mask:0xf
	v_fmac_f32_dpp v110, -v243, v7 quad_perm:[1,1,1,1] row_mask:0xf bank_mask:0xf
	v_fmac_f32_dpp v111, -v243, v8 quad_perm:[2,2,2,2] row_mask:0xf bank_mask:0xf
	v_fmac_f32_dpp v112, -v243, v9 quad_perm:[3,3,3,3] row_mask:0xf bank_mask:0xf
	ds_read2_b32 v[242:243], v251 offset0:16 offset1:20
	s_waitcnt lgkmcnt(7)
	v_fmac_f32_dpp v25, -v244, v10 quad_perm:[0,0,0,0] row_mask:0xf bank_mask:0xf
	v_fmac_f32_dpp v110, -v244, v12 quad_perm:[1,1,1,1] row_mask:0xf bank_mask:0xf
	v_fmac_f32_dpp v111, -v244, v13 quad_perm:[2,2,2,2] row_mask:0xf bank_mask:0xf
	v_fmac_f32_dpp v112, -v244, v14 quad_perm:[3,3,3,3] row_mask:0xf bank_mask:0xf
	v_fmac_f32_dpp v25, -v245, v15 quad_perm:[0,0,0,0] row_mask:0xf bank_mask:0xf
	v_fmac_f32_dpp v110, -v245, v17 quad_perm:[1,1,1,1] row_mask:0xf bank_mask:0xf
	v_fmac_f32_dpp v111, -v245, v18 quad_perm:[2,2,2,2] row_mask:0xf bank_mask:0xf
	v_fmac_f32_dpp v112, -v245, v19 quad_perm:[3,3,3,3] row_mask:0xf bank_mask:0xf
	v_add_u32_e32 v251, 0x110, v251
	ds_read2_b32 v[244:245], v251 offset0:0 offset1:4
	s_waitcnt lgkmcnt(7)
	v_fmac_f32_dpp v25, -v230, v21 quad_perm:[0,0,0,0] row_mask:0xf bank_mask:0xf
	v_fmac_f32_dpp v110, -v230, v22 quad_perm:[1,1,1,1] row_mask:0xf bank_mask:0xf
	v_fmac_f32_dpp v111, -v230, v23 quad_perm:[2,2,2,2] row_mask:0xf bank_mask:0xf
	ds_read2_b32 v[230:231], v251 offset0:8 offset1:12
	v_add_f32_e32 v25, v25, v110
	v_add_f32_e32 v111, v111, v112
	v_add_f32_e32 v25, v25, v111
	s_waitcnt lgkmcnt(7)
	v_fmac_f32_dpp v26, -v232, v4 quad_perm:[0,0,0,0] row_mask:0xf bank_mask:0xf
	v_mul_f32_dpp v110, -v232, v2 quad_perm:[1,1,1,1] row_mask:0xf bank_mask:0xf
	v_mul_f32_dpp v111, -v232, v3 quad_perm:[2,2,2,2] row_mask:0xf bank_mask:0xf
	v_mul_f32_dpp v112, -v232, v5 quad_perm:[3,3,3,3] row_mask:0xf bank_mask:0xf
	v_fmac_f32_dpp v26, -v233, v6 quad_perm:[0,0,0,0] row_mask:0xf bank_mask:0xf
	v_fmac_f32_dpp v110, -v233, v7 quad_perm:[1,1,1,1] row_mask:0xf bank_mask:0xf
	v_fmac_f32_dpp v111, -v233, v8 quad_perm:[2,2,2,2] row_mask:0xf bank_mask:0xf
	v_fmac_f32_dpp v112, -v233, v9 quad_perm:[3,3,3,3] row_mask:0xf bank_mask:0xf
	ds_read2_b32 v[232:233], v251 offset0:16 offset1:20
	s_waitcnt lgkmcnt(7)
	v_fmac_f32_dpp v26, -v234, v10 quad_perm:[0,0,0,0] row_mask:0xf bank_mask:0xf
	v_fmac_f32_dpp v110, -v234, v12 quad_perm:[1,1,1,1] row_mask:0xf bank_mask:0xf
	v_fmac_f32_dpp v111, -v234, v13 quad_perm:[2,2,2,2] row_mask:0xf bank_mask:0xf
	v_fmac_f32_dpp v112, -v234, v14 quad_perm:[3,3,3,3] row_mask:0xf bank_mask:0xf
	v_fmac_f32_dpp v26, -v235, v15 quad_perm:[0,0,0,0] row_mask:0xf bank_mask:0xf
	v_fmac_f32_dpp v110, -v235, v17 quad_perm:[1,1,1,1] row_mask:0xf bank_mask:0xf
	v_fmac_f32_dpp v111, -v235, v18 quad_perm:[2,2,2,2] row_mask:0xf bank_mask:0xf
	v_fmac_f32_dpp v112, -v235, v19 quad_perm:[3,3,3,3] row_mask:0xf bank_mask:0xf
	v_add_u32_e32 v251, 0x110, v251
	ds_read2_b32 v[234:235], v251 offset0:0 offset1:4
	s_waitcnt lgkmcnt(7)
	v_fmac_f32_dpp v26, -v236, v21 quad_perm:[0,0,0,0] row_mask:0xf bank_mask:0xf
	v_fmac_f32_dpp v110, -v236, v22 quad_perm:[1,1,1,1] row_mask:0xf bank_mask:0xf
	v_fmac_f32_dpp v111, -v236, v23 quad_perm:[2,2,2,2] row_mask:0xf bank_mask:0xf
	v_fmac_f32_dpp v112, -v236, v25 quad_perm:[3,3,3,3] row_mask:0xf bank_mask:0xf
	ds_read2_b32 v[236:237], v251 offset0:8 offset1:12
	v_add_f32_e32 v26, v26, v110
	v_add_f32_e32 v111, v111, v112
	v_add_f32_e32 v26, v26, v111
	s_waitcnt lgkmcnt(7)
; DI void phase_gdn_c1(const Ctx& c) {
;     ...
; #pragma unroll
;       for (int i = 1; i < 64; ++i) {
;         float s0 = sol[i], s1 = 0.f, s2 = 0.f, s3 = 0.f;
; #pragma unroll
;         for (int m = 0; m < i; ++m) {
;           const float t_ = Am[i * 68 + m] * sol[m];
;           if ((m & 3) == 0) s0 -= t_; else if ((m & 3) == 1) s1 -= t_; else if ((m & 3) == 2) s2 -= t_; else s3 -= t_;
;         }
;         sol[i] = (s0 + s1) + (s2 + s3);
;       }
	v_fmac_f32_dpp v28, -v238, v4 quad_perm:[0,0,0,0] row_mask:0xf bank_mask:0xf
	v_mul_f32_dpp v110, -v238, v2 quad_perm:[1,1,1,1] row_mask:0xf bank_mask:0xf
	v_mul_f32_dpp v111, -v238, v3 quad_perm:[2,2,2,2] row_mask:0xf bank_mask:0xf
	v_mul_f32_dpp v112, -v238, v5 quad_perm:[3,3,3,3] row_mask:0xf bank_mask:0xf
	v_fmac_f32_dpp v28, -v239, v6 quad_perm:[0,0,0,0] row_mask:0xf bank_mask:0xf
	v_fmac_f32_dpp v110, -v239, v7 quad_perm:[1,1,1,1] row_mask:0xf bank_mask:0xf
	v_fmac_f32_dpp v111, -v239, v8 quad_perm:[2,2,2,2] row_mask:0xf bank_mask:0xf
	v_fmac_f32_dpp v112, -v239, v9 quad_perm:[3,3,3,3] row_mask:0xf bank_mask:0xf
	ds_read2_b32 v[238:239], v251 offset0:16 offset1:20
	s_waitcnt lgkmcnt(7)
	v_fmac_f32_dpp v28, -v240, v10 quad_perm:[0,0,0,0] row_mask:0xf bank_mask:0xf
	v_fmac_f32_dpp v110, -v240, v12 quad_perm:[1,1,1,1] row_mask:0xf bank_mask:0xf
	v_fmac_f32_dpp v111, -v240, v13 quad_perm:[2,2,2,2] row_mask:0xf bank_mask:0xf
	v_fmac_f32_dpp v112, -v240, v14 quad_perm:[3,3,3,3] row_mask:0xf bank_mask:0xf
	v_fmac_f32_dpp v28, -v241, v15 quad_perm:[0,0,0,0] row_mask:0xf bank_mask:0xf
	v_fmac_f32_dpp v110, -v241, v17 quad_perm:[1,1,1,1] row_mask:0xf bank_mask:0xf
	v_fmac_f32_dpp v111, -v241, v18 quad_perm:[2,2,2,2] row_mask:0xf bank_mask:0xf
	v_fmac_f32_dpp v112, -v241, v19 quad_perm:[3,3,3,3] row_mask:0xf bank_mask:0xf
	v_add_u32_e32 v251, 0x110, v251
	ds_read2_b32 v[240:241], v251 offset0:0 offset1:4
	s_waitcnt lgkmcnt(7)
	v_fmac_f32_dpp v28, -v242, v21 quad_perm:[0,0,0,0] row_mask:0xf bank_mask:0xf
	v_fmac_f32_dpp v110, -v242, v22 quad_perm:[1,1,1,1] row_mask:0xf bank_mask:0xf
	v_fmac_f32_dpp v111, -v242, v23 quad_perm:[2,2,2,2] row_mask:0xf bank_mask:0xf
	v_fmac_f32_dpp v112, -v242, v25 quad_perm:[3,3,3,3] row_mask:0xf bank_mask:0xf
	v_fmac_f32_dpp v28, -v243, v26 quad_perm:[0,0,0,0] row_mask:0xf bank_mask:0xf
	ds_read2_b32 v[242:243], v251 offset0:8 offset1:12
	v_add_f32_e32 v28, v28, v110
	v_add_f32_e32 v111, v111, v112
	v_add_f32_e32 v28, v28, v111
	s_waitcnt lgkmcnt(7)
	v_fmac_f32_dpp v29, -v244, v4 quad_perm:[0,0,0,0] row_mask:0xf bank_mask:0xf
	v_mul_f32_dpp v110, -v244, v2 quad_perm:[1,1,1,1] row_mask:0xf bank_mask:0xf
	v_mul_f32_dpp v111, -v244, v3 quad_perm:[2,2,2,2] row_mask:0xf bank_mask:0xf
	v_mul_f32_dpp v112, -v244, v5 quad_perm:[3,3,3,3] row_mask:0xf bank_mask:0xf
	v_fmac_f32_dpp v29, -v245, v6 quad_perm:[0,0,0,0] row_mask:0xf bank_mask:0xf
	v_fmac_f32_dpp v110, -v245, v7 quad_perm:[1,1,1,1] row_mask:0xf bank_mask:0xf
	v_fmac_f32_dpp v111, -v245, v8 quad_perm:[2,2,2,2] row_mask:0xf bank_mask:0xf
	v_fmac_f32_dpp v112, -v245, v9 quad_perm:[3,3,3,3] row_mask:0xf bank_mask:0xf
	ds_read2_b32 v[244:245], v251 offset0:16 offset1:20
	s_waitcnt lgkmcnt(7)
	v_fmac_f32_dpp v29, -v230, v10 quad_perm:[0,0,0,0] row_mask:0xf bank_mask:0xf
	v_fmac_f32_dpp v110, -v230, v12 quad_perm:[1,1,1,1] row_mask:0xf bank_mask:0xf
	v_fmac_f32_dpp v111, -v230, v13 quad_perm:[2,2,2,2] row_mask:0xf bank_mask:0xf
	v_fmac_f32_dpp v112, -v230, v14 quad_perm:[3,3,3,3] row_mask:0xf bank_mask:0xf
	v_fmac_f32_dpp v29, -v231, v15 quad_perm:[0,0,0,0] row_mask:0xf bank_mask:0xf
	v_fmac_f32_dpp v110, -v231, v17 quad_perm:[1,1,1,1] row_mask:0xf bank_mask:0xf
	v_fmac_f32_dpp v111, -v231, v18 quad_perm:[2,2,2,2] row_mask:0xf bank_mask:0xf
	v_fmac_f32_dpp v112, -v231, v19 quad_perm:[3,3,3,3] row_mask:0xf bank_mask:0xf
	v_add_u32_e32 v251, 0x110, v251
	ds_read2_b32 v[230:231], v251 offset0:0 offset1:4
	s_waitcnt lgkmcnt(7)
	v_fmac_f32_dpp v29, -v232, v21 quad_perm:[0,0,0,0] row_mask:0xf bank_mask:0xf
	v_fmac_f32_dpp v110, -v232, v22 quad_perm:[1,1,1,1] row_mask:0xf bank_mask:0xf
	v_fmac_f32_dpp v111, -v232, v23 quad_perm:[2,2,2,2] row_mask:0xf bank_mask:0xf
	v_fmac_f32_dpp v112, -v232, v25 quad_perm:[3,3,3,3] row_mask:0xf bank_mask:0xf
	v_fmac_f32_dpp v29, -v233, v26 quad_perm:[0,0,0,0] row_mask:0xf bank_mask:0xf
	v_fmac_f32_dpp v110, -v233, v28 quad_perm:[1,1,1,1] row_mask:0xf bank_mask:0xf
	ds_read2_b32 v[232:233], v251 offset0:8 offset1:12
	v_add_f32_e32 v29, v29, v110
	v_add_f32_e32 v111, v111, v112
	v_add_f32_e32 v29, v29, v111
	s_waitcnt lgkmcnt(7)
	v_fmac_f32_dpp v31, -v234, v4 quad_perm:[0,0,0,0] row_mask:0xf bank_mask:0xf
	v_mul_f32_dpp v110, -v234, v2 quad_perm:[1,1,1,1] row_mask:0xf bank_mask:0xf
	v_mul_f32_dpp v111, -v234, v3 quad_perm:[2,2,2,2] row_mask:0xf bank_mask:0xf
	v_mul_f32_dpp v112, -v234, v5 quad_perm:[3,3,3,3] row_mask:0xf bank_mask:0xf
	v_fmac_f32_dpp v31, -v235, v6 quad_perm:[0,0,0,0] row_mask:0xf bank_mask:0xf
	v_fmac_f32_dpp v110, -v235, v7 quad_perm:[1,1,1,1] row_mask:0xf bank_mask:0xf
	v_fmac_f32_dpp v111, -v235, v8 quad_perm:[2,2,2,2] row_mask:0xf bank_mask:0xf
	v_fmac_f32_dpp v112, -v235, v9 quad_perm:[3,3,3,3] row_mask:0xf bank_mask:0xf
	ds_read2_b32 v[234:235], v251 offset0:16 offset1:20
	s_waitcnt lgkmcnt(7)
	v_fmac_f32_dpp v31, -v236, v10 quad_perm:[0,0,0,0] row_mask:0xf bank_mask:0xf
	v_fmac_f32_dpp v110, -v236, v12 quad_perm:[1,1,1,1] row_mask:0xf bank_mask:0xf
	v_fmac_f32_dpp v111, -v236, v13 quad_perm:[2,2,2,2] row_mask:0xf bank_mask:0xf
	v_fmac_f32_dpp v112, -v236, v14 quad_perm:[3,3,3,3] row_mask:0xf bank_mask:0xf
	v_fmac_f32_dpp v31, -v237, v15 quad_perm:[0,0,0,0] row_mask:0xf bank_mask:0xf
	v_fmac_f32_dpp v110, -v237, v17 quad_perm:[1,1,1,1] row_mask:0xf bank_mask:0xf
	v_fmac_f32_dpp v111, -v237, v18 quad_perm:[2,2,2,2] row_mask:0xf bank_mask:0xf
	v_fmac_f32_dpp v112, -v237, v19 quad_perm:[3,3,3,3] row_mask:0xf bank_mask:0xf
	ds_read2_b32 v[236:237], v251 offset0:24 offset1:24
	s_waitcnt lgkmcnt(7)
; DI void phase_gdn_c1(const Ctx& c) {
;     ...
; #pragma unroll
;       for (int i = 1; i < 64; ++i) {
;         float s0 = sol[i], s1 = 0.f, s2 = 0.f, s3 = 0.f;
; #pragma unroll
;         for (int m = 0; m < i; ++m) {
;           const float t_ = Am[i * 68 + m] * sol[m];
;           if ((m & 3) == 0) s0 -= t_; else if ((m & 3) == 1) s1 -= t_; else if ((m & 3) == 2) s2 -= t_; else s3 -= t_;
;         }
;         sol[i] = (s0 + s1) + (s2 + s3);
;       }
	v_fmac_f32_dpp v31, -v238, v21 quad_perm:[0,0,0,0] row_mask:0xf bank_mask:0xf
	v_fmac_f32_dpp v110, -v238, v22 quad_perm:[1,1,1,1] row_mask:0xf bank_mask:0xf
	v_fmac_f32_dpp v111, -v238, v23 quad_perm:[2,2,2,2] row_mask:0xf bank_mask:0xf
	v_fmac_f32_dpp v112, -v238, v25 quad_perm:[3,3,3,3] row_mask:0xf bank_mask:0xf
	v_fmac_f32_dpp v31, -v239, v26 quad_perm:[0,0,0,0] row_mask:0xf bank_mask:0xf
	v_fmac_f32_dpp v110, -v239, v28 quad_perm:[1,1,1,1] row_mask:0xf bank_mask:0xf
	v_fmac_f32_dpp v111, -v239, v29 quad_perm:[2,2,2,2] row_mask:0xf bank_mask:0xf
	v_add_u32_e32 v251, 0x110, v251
	ds_read2_b32 v[238:239], v251 offset0:0 offset1:4
	v_add_f32_e32 v31, v31, v110
	v_add_f32_e32 v111, v111, v112
	v_add_f32_e32 v31, v31, v111
	s_waitcnt lgkmcnt(7)
	v_fmac_f32_dpp v32, -v240, v4 quad_perm:[0,0,0,0] row_mask:0xf bank_mask:0xf
	v_mul_f32_dpp v110, -v240, v2 quad_perm:[1,1,1,1] row_mask:0xf bank_mask:0xf
	v_mul_f32_dpp v111, -v240, v3 quad_perm:[2,2,2,2] row_mask:0xf bank_mask:0xf
	v_mul_f32_dpp v112, -v240, v5 quad_perm:[3,3,3,3] row_mask:0xf bank_mask:0xf
	v_fmac_f32_dpp v32, -v241, v6 quad_perm:[0,0,0,0] row_mask:0xf bank_mask:0xf
	v_fmac_f32_dpp v110, -v241, v7 quad_perm:[1,1,1,1] row_mask:0xf bank_mask:0xf
	v_fmac_f32_dpp v111, -v241, v8 quad_perm:[2,2,2,2] row_mask:0xf bank_mask:0xf
	v_fmac_f32_dpp v112, -v241, v9 quad_perm:[3,3,3,3] row_mask:0xf bank_mask:0xf
	ds_read2_b32 v[240:241], v251 offset0:8 offset1:12
	s_waitcnt lgkmcnt(7)
	v_fmac_f32_dpp v32, -v242, v10 quad_perm:[0,0,0,0] row_mask:0xf bank_mask:0xf
	v_fmac_f32_dpp v110, -v242, v12 quad_perm:[1,1,1,1] row_mask:0xf bank_mask:0xf
	v_fmac_f32_dpp v111, -v242, v13 quad_perm:[2,2,2,2] row_mask:0xf bank_mask:0xf
	v_fmac_f32_dpp v112, -v242, v14 quad_perm:[3,3,3,3] row_mask:0xf bank_mask:0xf
	v_fmac_f32_dpp v32, -v243, v15 quad_perm:[0,0,0,0] row_mask:0xf bank_mask:0xf
	v_fmac_f32_dpp v110, -v243, v17 quad_perm:[1,1,1,1] row_mask:0xf bank_mask:0xf
	v_fmac_f32_dpp v111, -v243, v18 quad_perm:[2,2,2,2] row_mask:0xf bank_mask:0xf
	v_fmac_f32_dpp v112, -v243, v19 quad_perm:[3,3,3,3] row_mask:0xf bank_mask:0xf
	ds_read2_b32 v[242:243], v251 offset0:16 offset1:20
	s_waitcnt lgkmcnt(7)
	v_fmac_f32_dpp v32, -v244, v21 quad_perm:[0,0,0,0] row_mask:0xf bank_mask:0xf
	v_fmac_f32_dpp v110, -v244, v22 quad_perm:[1,1,1,1] row_mask:0xf bank_mask:0xf
	v_fmac_f32_dpp v111, -v244, v23 quad_perm:[2,2,2,2] row_mask:0xf bank_mask:0xf
	v_fmac_f32_dpp v112, -v244, v25 quad_perm:[3,3,3,3] row_mask:0xf bank_mask:0xf
	v_fmac_f32_dpp v32, -v245, v26 quad_perm:[0,0,0,0] row_mask:0xf bank_mask:0xf
	v_fmac_f32_dpp v110, -v245, v28 quad_perm:[1,1,1,1] row_mask:0xf bank_mask:0xf
	v_fmac_f32_dpp v111, -v245, v29 quad_perm:[2,2,2,2] row_mask:0xf bank_mask:0xf
	v_fmac_f32_dpp v112, -v245, v31 quad_perm:[3,3,3,3] row_mask:0xf bank_mask:0xf
	ds_read2_b32 v[244:245], v251 offset0:24 offset1:24
	v_add_f32_e32 v32, v32, v110
	v_add_f32_e32 v111, v111, v112
	v_add_f32_e32 v32, v32, v111
	s_waitcnt lgkmcnt(7)
	v_fmac_f32_dpp v43, -v230, v4 quad_perm:[0,0,0,0] row_mask:0xf bank_mask:0xf
	v_mul_f32_dpp v110, -v230, v2 quad_perm:[1,1,1,1] row_mask:0xf bank_mask:0xf
	v_mul_f32_dpp v111, -v230, v3 quad_perm:[2,2,2,2] row_mask:0xf bank_mask:0xf
	v_mul_f32_dpp v112, -v230, v5 quad_perm:[3,3,3,3] row_mask:0xf bank_mask:0xf
	v_fmac_f32_dpp v43, -v231, v6 quad_perm:[0,0,0,0] row_mask:0xf bank_mask:0xf
	v_fmac_f32_dpp v110, -v231, v7 quad_perm:[1,1,1,1] row_mask:0xf bank_mask:0xf
	v_fmac_f32_dpp v111, -v231, v8 quad_perm:[2,2,2,2] row_mask:0xf bank_mask:0xf
	v_fmac_f32_dpp v112, -v231, v9 quad_perm:[3,3,3,3] row_mask:0xf bank_mask:0xf
	v_add_u32_e32 v251, 0x110, v251
	ds_read2_b32 v[230:231], v251 offset0:0 offset1:4
	s_waitcnt lgkmcnt(7)
	v_fmac_f32_dpp v43, -v232, v10 quad_perm:[0,0,0,0] row_mask:0xf bank_mask:0xf
	v_fmac_f32_dpp v110, -v232, v12 quad_perm:[1,1,1,1] row_mask:0xf bank_mask:0xf
	v_fmac_f32_dpp v111, -v232, v13 quad_perm:[2,2,2,2] row_mask:0xf bank_mask:0xf
	v_fmac_f32_dpp v112, -v232, v14 quad_perm:[3,3,3,3] row_mask:0xf bank_mask:0xf
	v_fmac_f32_dpp v43, -v233, v15 quad_perm:[0,0,0,0] row_mask:0xf bank_mask:0xf
	v_fmac_f32_dpp v110, -v233, v17 quad_perm:[1,1,1,1] row_mask:0xf bank_mask:0xf
	v_fmac_f32_dpp v111, -v233, v18 quad_perm:[2,2,2,2] row_mask:0xf bank_mask:0xf
	v_fmac_f32_dpp v112, -v233, v19 quad_perm:[3,3,3,3] row_mask:0xf bank_mask:0xf
	ds_read2_b32 v[232:233], v251 offset0:8 offset1:12
	s_waitcnt lgkmcnt(7)
	v_fmac_f32_dpp v43, -v234, v21 quad_perm:[0,0,0,0] row_mask:0xf bank_mask:0xf
	v_fmac_f32_dpp v110, -v234, v22 quad_perm:[1,1,1,1] row_mask:0xf bank_mask:0xf
	v_fmac_f32_dpp v111, -v234, v23 quad_perm:[2,2,2,2] row_mask:0xf bank_mask:0xf
	v_fmac_f32_dpp v112, -v234, v25 quad_perm:[3,3,3,3] row_mask:0xf bank_mask:0xf
	v_fmac_f32_dpp v43, -v235, v26 quad_perm:[0,0,0,0] row_mask:0xf bank_mask:0xf
	v_fmac_f32_dpp v110, -v235, v28 quad_perm:[1,1,1,1] row_mask:0xf bank_mask:0xf
	v_fmac_f32_dpp v111, -v235, v29 quad_perm:[2,2,2,2] row_mask:0xf bank_mask:0xf
	v_fmac_f32_dpp v112, -v235, v31 quad_perm:[3,3,3,3] row_mask:0xf bank_mask:0xf
	ds_read2_b32 v[234:235], v251 offset0:16 offset1:20
	s_waitcnt lgkmcnt(7)
	v_fmac_f32_dpp v43, -v236, v32 quad_perm:[0,0,0,0] row_mask:0xf bank_mask:0xf
	ds_read2_b32 v[236:237], v251 offset0:24 offset1:24
	v_add_f32_e32 v43, v43, v110
	v_add_f32_e32 v111, v111, v112
	v_add_f32_e32 v43, v43, v111
	s_waitcnt lgkmcnt(7)
; DI void phase_gdn_c1(const Ctx& c) {
;     ...
; #pragma unroll
;       for (int i = 1; i < 64; ++i) {
;         float s0 = sol[i], s1 = 0.f, s2 = 0.f, s3 = 0.f;
; #pragma unroll
;         for (int m = 0; m < i; ++m) {
;           const float t_ = Am[i * 68 + m] * sol[m];
;           if ((m & 3) == 0) s0 -= t_; else if ((m & 3) == 1) s1 -= t_; else if ((m & 3) == 2) s2 -= t_; else s3 -= t_;
;         }
;         sol[i] = (s0 + s1) + (s2 + s3);
;       }
	v_fmac_f32_dpp v47, -v238, v4 quad_perm:[0,0,0,0] row_mask:0xf bank_mask:0xf
	v_mul_f32_dpp v110, -v238, v2 quad_perm:[1,1,1,1] row_mask:0xf bank_mask:0xf
	v_mul_f32_dpp v111, -v238, v3 quad_perm:[2,2,2,2] row_mask:0xf bank_mask:0xf
	v_mul_f32_dpp v112, -v238, v5 quad_perm:[3,3,3,3] row_mask:0xf bank_mask:0xf
	v_fmac_f32_dpp v47, -v239, v6 quad_perm:[0,0,0,0] row_mask:0xf bank_mask:0xf
	v_fmac_f32_dpp v110, -v239, v7 quad_perm:[1,1,1,1] row_mask:0xf bank_mask:0xf
	v_fmac_f32_dpp v111, -v239, v8 quad_perm:[2,2,2,2] row_mask:0xf bank_mask:0xf
	v_fmac_f32_dpp v112, -v239, v9 quad_perm:[3,3,3,3] row_mask:0xf bank_mask:0xf
	v_add_u32_e32 v251, 0x110, v251
	ds_read2_b32 v[238:239], v251 offset0:0 offset1:4
	s_waitcnt lgkmcnt(7)
	v_fmac_f32_dpp v47, -v240, v10 quad_perm:[0,0,0,0] row_mask:0xf bank_mask:0xf
	v_fmac_f32_dpp v110, -v240, v12 quad_perm:[1,1,1,1] row_mask:0xf bank_mask:0xf
	v_fmac_f32_dpp v111, -v240, v13 quad_perm:[2,2,2,2] row_mask:0xf bank_mask:0xf
	v_fmac_f32_dpp v112, -v240, v14 quad_perm:[3,3,3,3] row_mask:0xf bank_mask:0xf
	v_fmac_f32_dpp v47, -v241, v15 quad_perm:[0,0,0,0] row_mask:0xf bank_mask:0xf
	v_fmac_f32_dpp v110, -v241, v17 quad_perm:[1,1,1,1] row_mask:0xf bank_mask:0xf
	v_fmac_f32_dpp v111, -v241, v18 quad_perm:[2,2,2,2] row_mask:0xf bank_mask:0xf
	v_fmac_f32_dpp v112, -v241, v19 quad_perm:[3,3,3,3] row_mask:0xf bank_mask:0xf
	ds_read2_b32 v[240:241], v251 offset0:8 offset1:12
	s_waitcnt lgkmcnt(7)
	v_fmac_f32_dpp v47, -v242, v21 quad_perm:[0,0,0,0] row_mask:0xf bank_mask:0xf
	v_fmac_f32_dpp v110, -v242, v22 quad_perm:[1,1,1,1] row_mask:0xf bank_mask:0xf
	v_fmac_f32_dpp v111, -v242, v23 quad_perm:[2,2,2,2] row_mask:0xf bank_mask:0xf
	v_fmac_f32_dpp v112, -v242, v25 quad_perm:[3,3,3,3] row_mask:0xf bank_mask:0xf
	v_fmac_f32_dpp v47, -v243, v26 quad_perm:[0,0,0,0] row_mask:0xf bank_mask:0xf
	v_fmac_f32_dpp v110, -v243, v28 quad_perm:[1,1,1,1] row_mask:0xf bank_mask:0xf
	v_fmac_f32_dpp v111, -v243, v29 quad_perm:[2,2,2,2] row_mask:0xf bank_mask:0xf
	v_fmac_f32_dpp v112, -v243, v31 quad_perm:[3,3,3,3] row_mask:0xf bank_mask:0xf
	ds_read2_b32 v[242:243], v251 offset0:16 offset1:20
	s_waitcnt lgkmcnt(7)
	v_fmac_f32_dpp v47, -v244, v32 quad_perm:[0,0,0,0] row_mask:0xf bank_mask:0xf
	v_fmac_f32_dpp v110, -v244, v43 quad_perm:[1,1,1,1] row_mask:0xf bank_mask:0xf
	ds_read2_b32 v[244:245], v251 offset0:24 offset1:24
	v_add_f32_e32 v47, v47, v110
	v_add_f32_e32 v111, v111, v112
	v_add_f32_e32 v47, v47, v111
	s_waitcnt lgkmcnt(7)
	v_fmac_f32_dpp v50, -v230, v4 quad_perm:[0,0,0,0] row_mask:0xf bank_mask:0xf
	v_mul_f32_dpp v110, -v230, v2 quad_perm:[1,1,1,1] row_mask:0xf bank_mask:0xf
	v_mul_f32_dpp v111, -v230, v3 quad_perm:[2,2,2,2] row_mask:0xf bank_mask:0xf
	v_mul_f32_dpp v112, -v230, v5 quad_perm:[3,3,3,3] row_mask:0xf bank_mask:0xf
	v_fmac_f32_dpp v50, -v231, v6 quad_perm:[0,0,0,0] row_mask:0xf bank_mask:0xf
	v_fmac_f32_dpp v110, -v231, v7 quad_perm:[1,1,1,1] row_mask:0xf bank_mask:0xf
	v_fmac_f32_dpp v111, -v231, v8 quad_perm:[2,2,2,2] row_mask:0xf bank_mask:0xf
	v_fmac_f32_dpp v112, -v231, v9 quad_perm:[3,3,3,3] row_mask:0xf bank_mask:0xf
	v_add_u32_e32 v251, 0x110, v251
	ds_read2_b32 v[230:231], v251 offset0:0 offset1:4
	s_waitcnt lgkmcnt(7)
	v_fmac_f32_dpp v50, -v232, v10 quad_perm:[0,0,0,0] row_mask:0xf bank_mask:0xf
	v_fmac_f32_dpp v110, -v232, v12 quad_perm:[1,1,1,1] row_mask:0xf bank_mask:0xf
	v_fmac_f32_dpp v111, -v232, v13 quad_perm:[2,2,2,2] row_mask:0xf bank_mask:0xf
	v_fmac_f32_dpp v112, -v232, v14 quad_perm:[3,3,3,3] row_mask:0xf bank_mask:0xf
	v_fmac_f32_dpp v50, -v233, v15 quad_perm:[0,0,0,0] row_mask:0xf bank_mask:0xf
	v_fmac_f32_dpp v110, -v233, v17 quad_perm:[1,1,1,1] row_mask:0xf bank_mask:0xf
	v_fmac_f32_dpp v111, -v233, v18 quad_perm:[2,2,2,2] row_mask:0xf bank_mask:0xf
	v_fmac_f32_dpp v112, -v233, v19 quad_perm:[3,3,3,3] row_mask:0xf bank_mask:0xf
	ds_read2_b32 v[232:233], v251 offset0:8 offset1:12
	s_waitcnt lgkmcnt(7)
	v_fmac_f32_dpp v50, -v234, v21 quad_perm:[0,0,0,0] row_mask:0xf bank_mask:0xf
	v_fmac_f32_dpp v110, -v234, v22 quad_perm:[1,1,1,1] row_mask:0xf bank_mask:0xf
	v_fmac_f32_dpp v111, -v234, v23 quad_perm:[2,2,2,2] row_mask:0xf bank_mask:0xf
	v_fmac_f32_dpp v112, -v234, v25 quad_perm:[3,3,3,3] row_mask:0xf bank_mask:0xf
	v_fmac_f32_dpp v50, -v235, v26 quad_perm:[0,0,0,0] row_mask:0xf bank_mask:0xf
	v_fmac_f32_dpp v110, -v235, v28 quad_perm:[1,1,1,1] row_mask:0xf bank_mask:0xf
	v_fmac_f32_dpp v111, -v235, v29 quad_perm:[2,2,2,2] row_mask:0xf bank_mask:0xf
	v_fmac_f32_dpp v112, -v235, v31 quad_perm:[3,3,3,3] row_mask:0xf bank_mask:0xf
	ds_read2_b32 v[234:235], v251 offset0:16 offset1:20
	s_waitcnt lgkmcnt(7)
	v_fmac_f32_dpp v50, -v236, v32 quad_perm:[0,0,0,0] row_mask:0xf bank_mask:0xf
	v_fmac_f32_dpp v110, -v236, v43 quad_perm:[1,1,1,1] row_mask:0xf bank_mask:0xf
	v_fmac_f32_dpp v111, -v236, v47 quad_perm:[2,2,2,2] row_mask:0xf bank_mask:0xf
	ds_read2_b32 v[236:237], v251 offset0:24 offset1:28
	v_add_f32_e32 v50, v50, v110
	v_add_f32_e32 v111, v111, v112
	v_add_f32_e32 v50, v50, v111
	s_waitcnt lgkmcnt(7)
	v_fmac_f32_dpp v52, -v238, v4 quad_perm:[0,0,0,0] row_mask:0xf bank_mask:0xf
	v_mul_f32_dpp v110, -v238, v2 quad_perm:[1,1,1,1] row_mask:0xf bank_mask:0xf
	v_mul_f32_dpp v111, -v238, v3 quad_perm:[2,2,2,2] row_mask:0xf bank_mask:0xf
	v_mul_f32_dpp v112, -v238, v5 quad_perm:[3,3,3,3] row_mask:0xf bank_mask:0xf
	v_fmac_f32_dpp v52, -v239, v6 quad_perm:[0,0,0,0] row_mask:0xf bank_mask:0xf
	v_fmac_f32_dpp v110, -v239, v7 quad_perm:[1,1,1,1] row_mask:0xf bank_mask:0xf
	v_fmac_f32_dpp v111, -v239, v8 quad_perm:[2,2,2,2] row_mask:0xf bank_mask:0xf
	v_fmac_f32_dpp v112, -v239, v9 quad_perm:[3,3,3,3] row_mask:0xf bank_mask:0xf
	v_add_u32_e32 v251, 0x110, v251
	ds_read2_b32 v[238:239], v251 offset0:0 offset1:4
	s_waitcnt lgkmcnt(7)
; DI void phase_gdn_c1(const Ctx& c) {
;     ...
; #pragma unroll
;       for (int i = 1; i < 64; ++i) {
;         float s0 = sol[i], s1 = 0.f, s2 = 0.f, s3 = 0.f;
; #pragma unroll
;         for (int m = 0; m < i; ++m) {
;           const float t_ = Am[i * 68 + m] * sol[m];
;           if ((m & 3) == 0) s0 -= t_; else if ((m & 3) == 1) s1 -= t_; else if ((m & 3) == 2) s2 -= t_; else s3 -= t_;
;         }
;         sol[i] = (s0 + s1) + (s2 + s3);
;       }
	v_fmac_f32_dpp v52, -v240, v10 quad_perm:[0,0,0,0] row_mask:0xf bank_mask:0xf
	v_fmac_f32_dpp v110, -v240, v12 quad_perm:[1,1,1,1] row_mask:0xf bank_mask:0xf
	v_fmac_f32_dpp v111, -v240, v13 quad_perm:[2,2,2,2] row_mask:0xf bank_mask:0xf
	v_fmac_f32_dpp v112, -v240, v14 quad_perm:[3,3,3,3] row_mask:0xf bank_mask:0xf
	v_fmac_f32_dpp v52, -v241, v15 quad_perm:[0,0,0,0] row_mask:0xf bank_mask:0xf
	v_fmac_f32_dpp v110, -v241, v17 quad_perm:[1,1,1,1] row_mask:0xf bank_mask:0xf
	v_fmac_f32_dpp v111, -v241, v18 quad_perm:[2,2,2,2] row_mask:0xf bank_mask:0xf
	v_fmac_f32_dpp v112, -v241, v19 quad_perm:[3,3,3,3] row_mask:0xf bank_mask:0xf
	ds_read2_b32 v[240:241], v251 offset0:8 offset1:12
	s_waitcnt lgkmcnt(7)
	v_fmac_f32_dpp v52, -v242, v21 quad_perm:[0,0,0,0] row_mask:0xf bank_mask:0xf
	v_fmac_f32_dpp v110, -v242, v22 quad_perm:[1,1,1,1] row_mask:0xf bank_mask:0xf
	v_fmac_f32_dpp v111, -v242, v23 quad_perm:[2,2,2,2] row_mask:0xf bank_mask:0xf
	v_fmac_f32_dpp v112, -v242, v25 quad_perm:[3,3,3,3] row_mask:0xf bank_mask:0xf
	v_fmac_f32_dpp v52, -v243, v26 quad_perm:[0,0,0,0] row_mask:0xf bank_mask:0xf
	v_fmac_f32_dpp v110, -v243, v28 quad_perm:[1,1,1,1] row_mask:0xf bank_mask:0xf
	v_fmac_f32_dpp v111, -v243, v29 quad_perm:[2,2,2,2] row_mask:0xf bank_mask:0xf
	v_fmac_f32_dpp v112, -v243, v31 quad_perm:[3,3,3,3] row_mask:0xf bank_mask:0xf
	ds_read2_b32 v[242:243], v251 offset0:16 offset1:20
	s_waitcnt lgkmcnt(7)
	v_fmac_f32_dpp v52, -v244, v32 quad_perm:[0,0,0,0] row_mask:0xf bank_mask:0xf
	v_fmac_f32_dpp v110, -v244, v43 quad_perm:[1,1,1,1] row_mask:0xf bank_mask:0xf
	v_fmac_f32_dpp v111, -v244, v47 quad_perm:[2,2,2,2] row_mask:0xf bank_mask:0xf
	v_fmac_f32_dpp v112, -v244, v50 quad_perm:[3,3,3,3] row_mask:0xf bank_mask:0xf
	ds_read2_b32 v[244:245], v251 offset0:24 offset1:28
	v_add_f32_e32 v52, v52, v110
	v_add_f32_e32 v111, v111, v112
	v_add_f32_e32 v52, v52, v111
	v_mov_b32_e32 v81, v107
	s_waitcnt lgkmcnt(7)
	v_fmac_f32_dpp v81, -v230, v4 quad_perm:[0,0,0,0] row_mask:0xf bank_mask:0xf
	v_mul_f32_dpp v110, -v230, v2 quad_perm:[1,1,1,1] row_mask:0xf bank_mask:0xf
	v_mul_f32_dpp v111, -v230, v3 quad_perm:[2,2,2,2] row_mask:0xf bank_mask:0xf
	v_mul_f32_dpp v112, -v230, v5 quad_perm:[3,3,3,3] row_mask:0xf bank_mask:0xf
	v_fmac_f32_dpp v81, -v231, v6 quad_perm:[0,0,0,0] row_mask:0xf bank_mask:0xf
	v_fmac_f32_dpp v110, -v231, v7 quad_perm:[1,1,1,1] row_mask:0xf bank_mask:0xf
	v_fmac_f32_dpp v111, -v231, v8 quad_perm:[2,2,2,2] row_mask:0xf bank_mask:0xf
	v_fmac_f32_dpp v112, -v231, v9 quad_perm:[3,3,3,3] row_mask:0xf bank_mask:0xf
	v_add_u32_e32 v251, 0x110, v251
	ds_read2_b32 v[230:231], v251 offset0:0 offset1:4
	s_waitcnt lgkmcnt(7)
	v_fmac_f32_dpp v81, -v232, v10 quad_perm:[0,0,0,0] row_mask:0xf bank_mask:0xf
	v_fmac_f32_dpp v110, -v232, v12 quad_perm:[1,1,1,1] row_mask:0xf bank_mask:0xf
	v_fmac_f32_dpp v111, -v232, v13 quad_perm:[2,2,2,2] row_mask:0xf bank_mask:0xf
	v_fmac_f32_dpp v112, -v232, v14 quad_perm:[3,3,3,3] row_mask:0xf bank_mask:0xf
	v_fmac_f32_dpp v81, -v233, v15 quad_perm:[0,0,0,0] row_mask:0xf bank_mask:0xf
	v_fmac_f32_dpp v110, -v233, v17 quad_perm:[1,1,1,1] row_mask:0xf bank_mask:0xf
	v_fmac_f32_dpp v111, -v233, v18 quad_perm:[2,2,2,2] row_mask:0xf bank_mask:0xf
	v_fmac_f32_dpp v112, -v233, v19 quad_perm:[3,3,3,3] row_mask:0xf bank_mask:0xf
	ds_read2_b32 v[232:233], v251 offset0:8 offset1:12
	s_waitcnt lgkmcnt(7)
	v_fmac_f32_dpp v81, -v234, v21 quad_perm:[0,0,0,0] row_mask:0xf bank_mask:0xf
	v_fmac_f32_dpp v110, -v234, v22 quad_perm:[1,1,1,1] row_mask:0xf bank_mask:0xf
	v_fmac_f32_dpp v111, -v234, v23 quad_perm:[2,2,2,2] row_mask:0xf bank_mask:0xf
	v_fmac_f32_dpp v112, -v234, v25 quad_perm:[3,3,3,3] row_mask:0xf bank_mask:0xf
	v_fmac_f32_dpp v81, -v235, v26 quad_perm:[0,0,0,0] row_mask:0xf bank_mask:0xf
	v_fmac_f32_dpp v110, -v235, v28 quad_perm:[1,1,1,1] row_mask:0xf bank_mask:0xf
	v_fmac_f32_dpp v111, -v235, v29 quad_perm:[2,2,2,2] row_mask:0xf bank_mask:0xf
	v_fmac_f32_dpp v112, -v235, v31 quad_perm:[3,3,3,3] row_mask:0xf bank_mask:0xf
	ds_read2_b32 v[234:235], v251 offset0:16 offset1:20
	s_waitcnt lgkmcnt(7)
	v_fmac_f32_dpp v81, -v236, v32 quad_perm:[0,0,0,0] row_mask:0xf bank_mask:0xf
	v_fmac_f32_dpp v110, -v236, v43 quad_perm:[1,1,1,1] row_mask:0xf bank_mask:0xf
	v_fmac_f32_dpp v111, -v236, v47 quad_perm:[2,2,2,2] row_mask:0xf bank_mask:0xf
	v_fmac_f32_dpp v112, -v236, v50 quad_perm:[3,3,3,3] row_mask:0xf bank_mask:0xf
	v_fmac_f32_dpp v81, -v237, v52 quad_perm:[0,0,0,0] row_mask:0xf bank_mask:0xf
	ds_read2_b32 v[236:237], v251 offset0:24 offset1:28
	v_add_f32_e32 v81, v81, v110
	v_add_f32_e32 v111, v111, v112
	v_add_f32_e32 v81, v81, v111
	v_mov_b32_e32 v82, v106
	s_waitcnt lgkmcnt(7)
	v_fmac_f32_dpp v82, -v238, v4 quad_perm:[0,0,0,0] row_mask:0xf bank_mask:0xf
	v_mul_f32_dpp v110, -v238, v2 quad_perm:[1,1,1,1] row_mask:0xf bank_mask:0xf
	v_mul_f32_dpp v111, -v238, v3 quad_perm:[2,2,2,2] row_mask:0xf bank_mask:0xf
	v_mul_f32_dpp v112, -v238, v5 quad_perm:[3,3,3,3] row_mask:0xf bank_mask:0xf
	v_fmac_f32_dpp v82, -v239, v6 quad_perm:[0,0,0,0] row_mask:0xf bank_mask:0xf
	v_fmac_f32_dpp v110, -v239, v7 quad_perm:[1,1,1,1] row_mask:0xf bank_mask:0xf
	v_fmac_f32_dpp v111, -v239, v8 quad_perm:[2,2,2,2] row_mask:0xf bank_mask:0xf
	v_fmac_f32_dpp v112, -v239, v9 quad_perm:[3,3,3,3] row_mask:0xf bank_mask:0xf
	v_add_u32_e32 v251, 0x110, v251
	ds_read2_b32 v[238:239], v251 offset0:0 offset1:4
	s_waitcnt lgkmcnt(7)
; DI void phase_gdn_c1(const Ctx& c) {
;     ...
; #pragma unroll
;       for (int i = 1; i < 64; ++i) {
;         float s0 = sol[i], s1 = 0.f, s2 = 0.f, s3 = 0.f;
; #pragma unroll
;         for (int m = 0; m < i; ++m) {
;           const float t_ = Am[i * 68 + m] * sol[m];
;           if ((m & 3) == 0) s0 -= t_; else if ((m & 3) == 1) s1 -= t_; else if ((m & 3) == 2) s2 -= t_; else s3 -= t_;
;         }
;         sol[i] = (s0 + s1) + (s2 + s3);
;       }
	v_fmac_f32_dpp v82, -v240, v10 quad_perm:[0,0,0,0] row_mask:0xf bank_mask:0xf
	v_fmac_f32_dpp v110, -v240, v12 quad_perm:[1,1,1,1] row_mask:0xf bank_mask:0xf
	v_fmac_f32_dpp v111, -v240, v13 quad_perm:[2,2,2,2] row_mask:0xf bank_mask:0xf
	v_fmac_f32_dpp v112, -v240, v14 quad_perm:[3,3,3,3] row_mask:0xf bank_mask:0xf
	v_fmac_f32_dpp v82, -v241, v15 quad_perm:[0,0,0,0] row_mask:0xf bank_mask:0xf
	v_fmac_f32_dpp v110, -v241, v17 quad_perm:[1,1,1,1] row_mask:0xf bank_mask:0xf
	v_fmac_f32_dpp v111, -v241, v18 quad_perm:[2,2,2,2] row_mask:0xf bank_mask:0xf
	v_fmac_f32_dpp v112, -v241, v19 quad_perm:[3,3,3,3] row_mask:0xf bank_mask:0xf
	ds_read2_b32 v[240:241], v251 offset0:8 offset1:12
	s_waitcnt lgkmcnt(7)
	v_fmac_f32_dpp v82, -v242, v21 quad_perm:[0,0,0,0] row_mask:0xf bank_mask:0xf
	v_fmac_f32_dpp v110, -v242, v22 quad_perm:[1,1,1,1] row_mask:0xf bank_mask:0xf
	v_fmac_f32_dpp v111, -v242, v23 quad_perm:[2,2,2,2] row_mask:0xf bank_mask:0xf
	v_fmac_f32_dpp v112, -v242, v25 quad_perm:[3,3,3,3] row_mask:0xf bank_mask:0xf
	v_fmac_f32_dpp v82, -v243, v26 quad_perm:[0,0,0,0] row_mask:0xf bank_mask:0xf
	v_fmac_f32_dpp v110, -v243, v28 quad_perm:[1,1,1,1] row_mask:0xf bank_mask:0xf
	v_fmac_f32_dpp v111, -v243, v29 quad_perm:[2,2,2,2] row_mask:0xf bank_mask:0xf
	v_fmac_f32_dpp v112, -v243, v31 quad_perm:[3,3,3,3] row_mask:0xf bank_mask:0xf
	ds_read2_b32 v[242:243], v251 offset0:16 offset1:20
	s_waitcnt lgkmcnt(7)
	v_fmac_f32_dpp v82, -v244, v32 quad_perm:[0,0,0,0] row_mask:0xf bank_mask:0xf
	v_fmac_f32_dpp v110, -v244, v43 quad_perm:[1,1,1,1] row_mask:0xf bank_mask:0xf
	v_fmac_f32_dpp v111, -v244, v47 quad_perm:[2,2,2,2] row_mask:0xf bank_mask:0xf
	v_fmac_f32_dpp v112, -v244, v50 quad_perm:[3,3,3,3] row_mask:0xf bank_mask:0xf
	v_fmac_f32_dpp v82, -v245, v52 quad_perm:[0,0,0,0] row_mask:0xf bank_mask:0xf
	v_fmac_f32_dpp v110, -v245, v81 quad_perm:[1,1,1,1] row_mask:0xf bank_mask:0xf
	ds_read2_b32 v[244:245], v251 offset0:24 offset1:28
	v_add_f32_e32 v82, v82, v110
	v_add_f32_e32 v111, v111, v112
	v_add_f32_e32 v82, v82, v111
	s_waitcnt lgkmcnt(7)
	v_fmac_f32_dpp v84, -v230, v4 quad_perm:[0,0,0,0] row_mask:0xf bank_mask:0xf
	v_mul_f32_dpp v110, -v230, v2 quad_perm:[1,1,1,1] row_mask:0xf bank_mask:0xf
	v_mul_f32_dpp v111, -v230, v3 quad_perm:[2,2,2,2] row_mask:0xf bank_mask:0xf
	v_mul_f32_dpp v112, -v230, v5 quad_perm:[3,3,3,3] row_mask:0xf bank_mask:0xf
	v_fmac_f32_dpp v84, -v231, v6 quad_perm:[0,0,0,0] row_mask:0xf bank_mask:0xf
	v_fmac_f32_dpp v110, -v231, v7 quad_perm:[1,1,1,1] row_mask:0xf bank_mask:0xf
	v_fmac_f32_dpp v111, -v231, v8 quad_perm:[2,2,2,2] row_mask:0xf bank_mask:0xf
	v_fmac_f32_dpp v112, -v231, v9 quad_perm:[3,3,3,3] row_mask:0xf bank_mask:0xf
	v_add_u32_e32 v251, 0x110, v251
	ds_read2_b32 v[230:231], v251 offset0:0 offset1:4
	s_waitcnt lgkmcnt(7)
	v_fmac_f32_dpp v84, -v232, v10 quad_perm:[0,0,0,0] row_mask:0xf bank_mask:0xf
	v_fmac_f32_dpp v110, -v232, v12 quad_perm:[1,1,1,1] row_mask:0xf bank_mask:0xf
	v_fmac_f32_dpp v111, -v232, v13 quad_perm:[2,2,2,2] row_mask:0xf bank_mask:0xf
	v_fmac_f32_dpp v112, -v232, v14 quad_perm:[3,3,3,3] row_mask:0xf bank_mask:0xf
	v_fmac_f32_dpp v84, -v233, v15 quad_perm:[0,0,0,0] row_mask:0xf bank_mask:0xf
	v_fmac_f32_dpp v110, -v233, v17 quad_perm:[1,1,1,1] row_mask:0xf bank_mask:0xf
	v_fmac_f32_dpp v111, -v233, v18 quad_perm:[2,2,2,2] row_mask:0xf bank_mask:0xf
	v_fmac_f32_dpp v112, -v233, v19 quad_perm:[3,3,3,3] row_mask:0xf bank_mask:0xf
	ds_read2_b32 v[232:233], v251 offset0:8 offset1:12
	s_waitcnt lgkmcnt(7)
	v_fmac_f32_dpp v84, -v234, v21 quad_perm:[0,0,0,0] row_mask:0xf bank_mask:0xf
	v_fmac_f32_dpp v110, -v234, v22 quad_perm:[1,1,1,1] row_mask:0xf bank_mask:0xf
	v_fmac_f32_dpp v111, -v234, v23 quad_perm:[2,2,2,2] row_mask:0xf bank_mask:0xf
	v_fmac_f32_dpp v112, -v234, v25 quad_perm:[3,3,3,3] row_mask:0xf bank_mask:0xf
	v_fmac_f32_dpp v84, -v235, v26 quad_perm:[0,0,0,0] row_mask:0xf bank_mask:0xf
	v_fmac_f32_dpp v110, -v235, v28 quad_perm:[1,1,1,1] row_mask:0xf bank_mask:0xf
	v_fmac_f32_dpp v111, -v235, v29 quad_perm:[2,2,2,2] row_mask:0xf bank_mask:0xf
	v_fmac_f32_dpp v112, -v235, v31 quad_perm:[3,3,3,3] row_mask:0xf bank_mask:0xf
	ds_read2_b32 v[234:235], v251 offset0:16 offset1:20
	s_waitcnt lgkmcnt(7)
	v_fmac_f32_dpp v84, -v236, v32 quad_perm:[0,0,0,0] row_mask:0xf bank_mask:0xf
	v_fmac_f32_dpp v110, -v236, v43 quad_perm:[1,1,1,1] row_mask:0xf bank_mask:0xf
	v_fmac_f32_dpp v111, -v236, v47 quad_perm:[2,2,2,2] row_mask:0xf bank_mask:0xf
	v_fmac_f32_dpp v112, -v236, v50 quad_perm:[3,3,3,3] row_mask:0xf bank_mask:0xf
	v_fmac_f32_dpp v84, -v237, v52 quad_perm:[0,0,0,0] row_mask:0xf bank_mask:0xf
	v_fmac_f32_dpp v110, -v237, v81 quad_perm:[1,1,1,1] row_mask:0xf bank_mask:0xf
	v_fmac_f32_dpp v111, -v237, v82 quad_perm:[2,2,2,2] row_mask:0xf bank_mask:0xf
	ds_read2_b32 v[236:237], v251 offset0:24 offset1:28
	v_add_f32_e32 v84, v84, v110
	v_add_f32_e32 v111, v111, v112
	v_add_f32_e32 v84, v84, v111
	s_waitcnt lgkmcnt(7)
	v_fmac_f32_dpp v86, -v238, v4 quad_perm:[0,0,0,0] row_mask:0xf bank_mask:0xf
	v_mul_f32_dpp v110, -v238, v2 quad_perm:[1,1,1,1] row_mask:0xf bank_mask:0xf
	v_mul_f32_dpp v111, -v238, v3 quad_perm:[2,2,2,2] row_mask:0xf bank_mask:0xf
	v_mul_f32_dpp v112, -v238, v5 quad_perm:[3,3,3,3] row_mask:0xf bank_mask:0xf
	v_fmac_f32_dpp v86, -v239, v6 quad_perm:[0,0,0,0] row_mask:0xf bank_mask:0xf
	v_fmac_f32_dpp v110, -v239, v7 quad_perm:[1,1,1,1] row_mask:0xf bank_mask:0xf
	v_fmac_f32_dpp v111, -v239, v8 quad_perm:[2,2,2,2] row_mask:0xf bank_mask:0xf
	v_fmac_f32_dpp v112, -v239, v9 quad_perm:[3,3,3,3] row_mask:0xf bank_mask:0xf
	ds_read2_b32 v[238:239], v251 offset0:32 offset1:32
	s_waitcnt lgkmcnt(7)
; DI void phase_gdn_c1(const Ctx& c) {
;     ...
; #pragma unroll
;       for (int i = 1; i < 64; ++i) {
;         float s0 = sol[i], s1 = 0.f, s2 = 0.f, s3 = 0.f;
; #pragma unroll
;         for (int m = 0; m < i; ++m) {
;           const float t_ = Am[i * 68 + m] * sol[m];
;           if ((m & 3) == 0) s0 -= t_; else if ((m & 3) == 1) s1 -= t_; else if ((m & 3) == 2) s2 -= t_; else s3 -= t_;
;         }
;         sol[i] = (s0 + s1) + (s2 + s3);
;       }
	v_fmac_f32_dpp v86, -v240, v10 quad_perm:[0,0,0,0] row_mask:0xf bank_mask:0xf
	v_fmac_f32_dpp v110, -v240, v12 quad_perm:[1,1,1,1] row_mask:0xf bank_mask:0xf
	v_fmac_f32_dpp v111, -v240, v13 quad_perm:[2,2,2,2] row_mask:0xf bank_mask:0xf
	v_fmac_f32_dpp v112, -v240, v14 quad_perm:[3,3,3,3] row_mask:0xf bank_mask:0xf
	v_fmac_f32_dpp v86, -v241, v15 quad_perm:[0,0,0,0] row_mask:0xf bank_mask:0xf
	v_fmac_f32_dpp v110, -v241, v17 quad_perm:[1,1,1,1] row_mask:0xf bank_mask:0xf
	v_fmac_f32_dpp v111, -v241, v18 quad_perm:[2,2,2,2] row_mask:0xf bank_mask:0xf
	v_fmac_f32_dpp v112, -v241, v19 quad_perm:[3,3,3,3] row_mask:0xf bank_mask:0xf
	v_add_u32_e32 v251, 0x110, v251
	ds_read2_b32 v[240:241], v251 offset0:0 offset1:4
	s_waitcnt lgkmcnt(7)
	v_fmac_f32_dpp v86, -v242, v21 quad_perm:[0,0,0,0] row_mask:0xf bank_mask:0xf
	v_fmac_f32_dpp v110, -v242, v22 quad_perm:[1,1,1,1] row_mask:0xf bank_mask:0xf
	v_fmac_f32_dpp v111, -v242, v23 quad_perm:[2,2,2,2] row_mask:0xf bank_mask:0xf
	v_fmac_f32_dpp v112, -v242, v25 quad_perm:[3,3,3,3] row_mask:0xf bank_mask:0xf
	v_fmac_f32_dpp v86, -v243, v26 quad_perm:[0,0,0,0] row_mask:0xf bank_mask:0xf
	v_fmac_f32_dpp v110, -v243, v28 quad_perm:[1,1,1,1] row_mask:0xf bank_mask:0xf
	v_fmac_f32_dpp v111, -v243, v29 quad_perm:[2,2,2,2] row_mask:0xf bank_mask:0xf
	v_fmac_f32_dpp v112, -v243, v31 quad_perm:[3,3,3,3] row_mask:0xf bank_mask:0xf
	ds_read2_b32 v[242:243], v251 offset0:8 offset1:12
	s_waitcnt lgkmcnt(7)
	v_fmac_f32_dpp v86, -v244, v32 quad_perm:[0,0,0,0] row_mask:0xf bank_mask:0xf
	v_fmac_f32_dpp v110, -v244, v43 quad_perm:[1,1,1,1] row_mask:0xf bank_mask:0xf
	v_fmac_f32_dpp v111, -v244, v47 quad_perm:[2,2,2,2] row_mask:0xf bank_mask:0xf
	v_fmac_f32_dpp v112, -v244, v50 quad_perm:[3,3,3,3] row_mask:0xf bank_mask:0xf
	v_fmac_f32_dpp v86, -v245, v52 quad_perm:[0,0,0,0] row_mask:0xf bank_mask:0xf
	v_fmac_f32_dpp v110, -v245, v81 quad_perm:[1,1,1,1] row_mask:0xf bank_mask:0xf
	v_fmac_f32_dpp v111, -v245, v82 quad_perm:[2,2,2,2] row_mask:0xf bank_mask:0xf
	v_fmac_f32_dpp v112, -v245, v84 quad_perm:[3,3,3,3] row_mask:0xf bank_mask:0xf
	ds_read2_b32 v[244:245], v251 offset0:16 offset1:20
	v_add_f32_e32 v86, v86, v110
	v_add_f32_e32 v111, v111, v112
	v_add_f32_e32 v86, v86, v111
	s_waitcnt lgkmcnt(7)
	v_fmac_f32_dpp v88, -v230, v4 quad_perm:[0,0,0,0] row_mask:0xf bank_mask:0xf
	v_mul_f32_dpp v110, -v230, v2 quad_perm:[1,1,1,1] row_mask:0xf bank_mask:0xf
	v_mul_f32_dpp v111, -v230, v3 quad_perm:[2,2,2,2] row_mask:0xf bank_mask:0xf
	v_mul_f32_dpp v112, -v230, v5 quad_perm:[3,3,3,3] row_mask:0xf bank_mask:0xf
	v_fmac_f32_dpp v88, -v231, v6 quad_perm:[0,0,0,0] row_mask:0xf bank_mask:0xf
	v_fmac_f32_dpp v110, -v231, v7 quad_perm:[1,1,1,1] row_mask:0xf bank_mask:0xf
	v_fmac_f32_dpp v111, -v231, v8 quad_perm:[2,2,2,2] row_mask:0xf bank_mask:0xf
	v_fmac_f32_dpp v112, -v231, v9 quad_perm:[3,3,3,3] row_mask:0xf bank_mask:0xf
	ds_read2_b32 v[230:231], v251 offset0:24 offset1:28
	s_waitcnt lgkmcnt(7)
	v_fmac_f32_dpp v88, -v232, v10 quad_perm:[0,0,0,0] row_mask:0xf bank_mask:0xf
	v_fmac_f32_dpp v110, -v232, v12 quad_perm:[1,1,1,1] row_mask:0xf bank_mask:0xf
	v_fmac_f32_dpp v111, -v232, v13 quad_perm:[2,2,2,2] row_mask:0xf bank_mask:0xf
	v_fmac_f32_dpp v112, -v232, v14 quad_perm:[3,3,3,3] row_mask:0xf bank_mask:0xf
	v_fmac_f32_dpp v88, -v233, v15 quad_perm:[0,0,0,0] row_mask:0xf bank_mask:0xf
	v_fmac_f32_dpp v110, -v233, v17 quad_perm:[1,1,1,1] row_mask:0xf bank_mask:0xf
	v_fmac_f32_dpp v111, -v233, v18 quad_perm:[2,2,2,2] row_mask:0xf bank_mask:0xf
	v_fmac_f32_dpp v112, -v233, v19 quad_perm:[3,3,3,3] row_mask:0xf bank_mask:0xf
	ds_read2_b32 v[232:233], v251 offset0:32 offset1:32
	s_waitcnt lgkmcnt(7)
	v_fmac_f32_dpp v88, -v234, v21 quad_perm:[0,0,0,0] row_mask:0xf bank_mask:0xf
	v_fmac_f32_dpp v110, -v234, v22 quad_perm:[1,1,1,1] row_mask:0xf bank_mask:0xf
	v_fmac_f32_dpp v111, -v234, v23 quad_perm:[2,2,2,2] row_mask:0xf bank_mask:0xf
	v_fmac_f32_dpp v112, -v234, v25 quad_perm:[3,3,3,3] row_mask:0xf bank_mask:0xf
	v_fmac_f32_dpp v88, -v235, v26 quad_perm:[0,0,0,0] row_mask:0xf bank_mask:0xf
	v_fmac_f32_dpp v110, -v235, v28 quad_perm:[1,1,1,1] row_mask:0xf bank_mask:0xf
	v_fmac_f32_dpp v111, -v235, v29 quad_perm:[2,2,2,2] row_mask:0xf bank_mask:0xf
	v_fmac_f32_dpp v112, -v235, v31 quad_perm:[3,3,3,3] row_mask:0xf bank_mask:0xf
	v_add_u32_e32 v251, 0x110, v251
	ds_read2_b32 v[234:235], v251 offset0:0 offset1:4
	s_waitcnt lgkmcnt(7)
	v_fmac_f32_dpp v88, -v236, v32 quad_perm:[0,0,0,0] row_mask:0xf bank_mask:0xf
	v_fmac_f32_dpp v110, -v236, v43 quad_perm:[1,1,1,1] row_mask:0xf bank_mask:0xf
	v_fmac_f32_dpp v111, -v236, v47 quad_perm:[2,2,2,2] row_mask:0xf bank_mask:0xf
	v_fmac_f32_dpp v112, -v236, v50 quad_perm:[3,3,3,3] row_mask:0xf bank_mask:0xf
	v_fmac_f32_dpp v88, -v237, v52 quad_perm:[0,0,0,0] row_mask:0xf bank_mask:0xf
	v_fmac_f32_dpp v110, -v237, v81 quad_perm:[1,1,1,1] row_mask:0xf bank_mask:0xf
	v_fmac_f32_dpp v111, -v237, v82 quad_perm:[2,2,2,2] row_mask:0xf bank_mask:0xf
	v_fmac_f32_dpp v112, -v237, v84 quad_perm:[3,3,3,3] row_mask:0xf bank_mask:0xf
	ds_read2_b32 v[236:237], v251 offset0:8 offset1:12
	s_waitcnt lgkmcnt(7)
	v_fmac_f32_dpp v88, -v238, v86 quad_perm:[0,0,0,0] row_mask:0xf bank_mask:0xf
	ds_read2_b32 v[238:239], v251 offset0:16 offset1:20
	v_add_f32_e32 v88, v88, v110
	v_add_f32_e32 v111, v111, v112
	v_add_f32_e32 v88, v88, v111
	s_waitcnt lgkmcnt(7)
; DI void phase_gdn_c1(const Ctx& c) {
;     ...
; #pragma unroll
;       for (int i = 1; i < 64; ++i) {
;         float s0 = sol[i], s1 = 0.f, s2 = 0.f, s3 = 0.f;
; #pragma unroll
;         for (int m = 0; m < i; ++m) {
;           const float t_ = Am[i * 68 + m] * sol[m];
;           if ((m & 3) == 0) s0 -= t_; else if ((m & 3) == 1) s1 -= t_; else if ((m & 3) == 2) s2 -= t_; else s3 -= t_;
;         }
;         sol[i] = (s0 + s1) + (s2 + s3);
;       }
	v_fmac_f32_dpp v90, -v240, v4 quad_perm:[0,0,0,0] row_mask:0xf bank_mask:0xf
	v_mul_f32_dpp v110, -v240, v2 quad_perm:[1,1,1,1] row_mask:0xf bank_mask:0xf
	v_mul_f32_dpp v111, -v240, v3 quad_perm:[2,2,2,2] row_mask:0xf bank_mask:0xf
	v_mul_f32_dpp v112, -v240, v5 quad_perm:[3,3,3,3] row_mask:0xf bank_mask:0xf
	v_fmac_f32_dpp v90, -v241, v6 quad_perm:[0,0,0,0] row_mask:0xf bank_mask:0xf
	v_fmac_f32_dpp v110, -v241, v7 quad_perm:[1,1,1,1] row_mask:0xf bank_mask:0xf
	v_fmac_f32_dpp v111, -v241, v8 quad_perm:[2,2,2,2] row_mask:0xf bank_mask:0xf
	v_fmac_f32_dpp v112, -v241, v9 quad_perm:[3,3,3,3] row_mask:0xf bank_mask:0xf
	ds_read2_b32 v[240:241], v251 offset0:24 offset1:28
	s_waitcnt lgkmcnt(7)
	v_fmac_f32_dpp v90, -v242, v10 quad_perm:[0,0,0,0] row_mask:0xf bank_mask:0xf
	v_fmac_f32_dpp v110, -v242, v12 quad_perm:[1,1,1,1] row_mask:0xf bank_mask:0xf
	v_fmac_f32_dpp v111, -v242, v13 quad_perm:[2,2,2,2] row_mask:0xf bank_mask:0xf
	v_fmac_f32_dpp v112, -v242, v14 quad_perm:[3,3,3,3] row_mask:0xf bank_mask:0xf
	v_fmac_f32_dpp v90, -v243, v15 quad_perm:[0,0,0,0] row_mask:0xf bank_mask:0xf
	v_fmac_f32_dpp v110, -v243, v17 quad_perm:[1,1,1,1] row_mask:0xf bank_mask:0xf
	v_fmac_f32_dpp v111, -v243, v18 quad_perm:[2,2,2,2] row_mask:0xf bank_mask:0xf
	v_fmac_f32_dpp v112, -v243, v19 quad_perm:[3,3,3,3] row_mask:0xf bank_mask:0xf
	ds_read2_b32 v[242:243], v251 offset0:32 offset1:32
	s_waitcnt lgkmcnt(7)
	v_fmac_f32_dpp v90, -v244, v21 quad_perm:[0,0,0,0] row_mask:0xf bank_mask:0xf
	v_fmac_f32_dpp v110, -v244, v22 quad_perm:[1,1,1,1] row_mask:0xf bank_mask:0xf
	v_fmac_f32_dpp v111, -v244, v23 quad_perm:[2,2,2,2] row_mask:0xf bank_mask:0xf
	v_fmac_f32_dpp v112, -v244, v25 quad_perm:[3,3,3,3] row_mask:0xf bank_mask:0xf
	v_fmac_f32_dpp v90, -v245, v26 quad_perm:[0,0,0,0] row_mask:0xf bank_mask:0xf
	v_fmac_f32_dpp v110, -v245, v28 quad_perm:[1,1,1,1] row_mask:0xf bank_mask:0xf
	v_fmac_f32_dpp v111, -v245, v29 quad_perm:[2,2,2,2] row_mask:0xf bank_mask:0xf
	v_fmac_f32_dpp v112, -v245, v31 quad_perm:[3,3,3,3] row_mask:0xf bank_mask:0xf
	v_add_u32_e32 v251, 0x110, v251
	ds_read2_b32 v[244:245], v251 offset0:0 offset1:4
	s_waitcnt lgkmcnt(7)
	v_fmac_f32_dpp v90, -v230, v32 quad_perm:[0,0,0,0] row_mask:0xf bank_mask:0xf
	v_fmac_f32_dpp v110, -v230, v43 quad_perm:[1,1,1,1] row_mask:0xf bank_mask:0xf
	v_fmac_f32_dpp v111, -v230, v47 quad_perm:[2,2,2,2] row_mask:0xf bank_mask:0xf
	v_fmac_f32_dpp v112, -v230, v50 quad_perm:[3,3,3,3] row_mask:0xf bank_mask:0xf
	v_fmac_f32_dpp v90, -v231, v52 quad_perm:[0,0,0,0] row_mask:0xf bank_mask:0xf
	v_fmac_f32_dpp v110, -v231, v81 quad_perm:[1,1,1,1] row_mask:0xf bank_mask:0xf
	v_fmac_f32_dpp v111, -v231, v82 quad_perm:[2,2,2,2] row_mask:0xf bank_mask:0xf
	v_fmac_f32_dpp v112, -v231, v84 quad_perm:[3,3,3,3] row_mask:0xf bank_mask:0xf
	ds_read2_b32 v[230:231], v251 offset0:8 offset1:12
	s_waitcnt lgkmcnt(7)
	v_fmac_f32_dpp v90, -v232, v86 quad_perm:[0,0,0,0] row_mask:0xf bank_mask:0xf
	v_fmac_f32_dpp v110, -v232, v88 quad_perm:[1,1,1,1] row_mask:0xf bank_mask:0xf
	ds_read2_b32 v[232:233], v251 offset0:16 offset1:20
	v_add_f32_e32 v90, v90, v110
	v_add_f32_e32 v111, v111, v112
	v_add_f32_e32 v90, v90, v111
	s_waitcnt lgkmcnt(7)
	v_fmac_f32_dpp v92, -v234, v4 quad_perm:[0,0,0,0] row_mask:0xf bank_mask:0xf
	v_mul_f32_dpp v110, -v234, v2 quad_perm:[1,1,1,1] row_mask:0xf bank_mask:0xf
	v_mul_f32_dpp v111, -v234, v3 quad_perm:[2,2,2,2] row_mask:0xf bank_mask:0xf
	v_mul_f32_dpp v112, -v234, v5 quad_perm:[3,3,3,3] row_mask:0xf bank_mask:0xf
	v_fmac_f32_dpp v92, -v235, v6 quad_perm:[0,0,0,0] row_mask:0xf bank_mask:0xf
	v_fmac_f32_dpp v110, -v235, v7 quad_perm:[1,1,1,1] row_mask:0xf bank_mask:0xf
	v_fmac_f32_dpp v111, -v235, v8 quad_perm:[2,2,2,2] row_mask:0xf bank_mask:0xf
	v_fmac_f32_dpp v112, -v235, v9 quad_perm:[3,3,3,3] row_mask:0xf bank_mask:0xf
	ds_read2_b32 v[234:235], v251 offset0:24 offset1:28
	s_waitcnt lgkmcnt(7)
	v_fmac_f32_dpp v92, -v236, v10 quad_perm:[0,0,0,0] row_mask:0xf bank_mask:0xf
	v_fmac_f32_dpp v110, -v236, v12 quad_perm:[1,1,1,1] row_mask:0xf bank_mask:0xf
	v_fmac_f32_dpp v111, -v236, v13 quad_perm:[2,2,2,2] row_mask:0xf bank_mask:0xf
	v_fmac_f32_dpp v112, -v236, v14 quad_perm:[3,3,3,3] row_mask:0xf bank_mask:0xf
	v_fmac_f32_dpp v92, -v237, v15 quad_perm:[0,0,0,0] row_mask:0xf bank_mask:0xf
	v_fmac_f32_dpp v110, -v237, v17 quad_perm:[1,1,1,1] row_mask:0xf bank_mask:0xf
	v_fmac_f32_dpp v111, -v237, v18 quad_perm:[2,2,2,2] row_mask:0xf bank_mask:0xf
	v_fmac_f32_dpp v112, -v237, v19 quad_perm:[3,3,3,3] row_mask:0xf bank_mask:0xf
	ds_read2_b32 v[236:237], v251 offset0:32 offset1:32
	s_waitcnt lgkmcnt(7)
	v_fmac_f32_dpp v92, -v238, v21 quad_perm:[0,0,0,0] row_mask:0xf bank_mask:0xf
	v_fmac_f32_dpp v110, -v238, v22 quad_perm:[1,1,1,1] row_mask:0xf bank_mask:0xf
	v_fmac_f32_dpp v111, -v238, v23 quad_perm:[2,2,2,2] row_mask:0xf bank_mask:0xf
	v_fmac_f32_dpp v112, -v238, v25 quad_perm:[3,3,3,3] row_mask:0xf bank_mask:0xf
	v_fmac_f32_dpp v92, -v239, v26 quad_perm:[0,0,0,0] row_mask:0xf bank_mask:0xf
	v_fmac_f32_dpp v110, -v239, v28 quad_perm:[1,1,1,1] row_mask:0xf bank_mask:0xf
	v_fmac_f32_dpp v111, -v239, v29 quad_perm:[2,2,2,2] row_mask:0xf bank_mask:0xf
	v_fmac_f32_dpp v112, -v239, v31 quad_perm:[3,3,3,3] row_mask:0xf bank_mask:0xf
	v_add_u32_e32 v251, 0x110, v251
	ds_read2_b32 v[238:239], v251 offset0:0 offset1:4
	s_waitcnt lgkmcnt(7)
; DI void phase_gdn_c1(const Ctx& c) {
;     ...
; #pragma unroll
;       for (int i = 1; i < 64; ++i) {
;         float s0 = sol[i], s1 = 0.f, s2 = 0.f, s3 = 0.f;
; #pragma unroll
;         for (int m = 0; m < i; ++m) {
;           const float t_ = Am[i * 68 + m] * sol[m];
;           if ((m & 3) == 0) s0 -= t_; else if ((m & 3) == 1) s1 -= t_; else if ((m & 3) == 2) s2 -= t_; else s3 -= t_;
;         }
;         sol[i] = (s0 + s1) + (s2 + s3);
;       }
	v_fmac_f32_dpp v92, -v240, v32 quad_perm:[0,0,0,0] row_mask:0xf bank_mask:0xf
	v_fmac_f32_dpp v110, -v240, v43 quad_perm:[1,1,1,1] row_mask:0xf bank_mask:0xf
	v_fmac_f32_dpp v111, -v240, v47 quad_perm:[2,2,2,2] row_mask:0xf bank_mask:0xf
	v_fmac_f32_dpp v112, -v240, v50 quad_perm:[3,3,3,3] row_mask:0xf bank_mask:0xf
	v_fmac_f32_dpp v92, -v241, v52 quad_perm:[0,0,0,0] row_mask:0xf bank_mask:0xf
	v_fmac_f32_dpp v110, -v241, v81 quad_perm:[1,1,1,1] row_mask:0xf bank_mask:0xf
	v_fmac_f32_dpp v111, -v241, v82 quad_perm:[2,2,2,2] row_mask:0xf bank_mask:0xf
	v_fmac_f32_dpp v112, -v241, v84 quad_perm:[3,3,3,3] row_mask:0xf bank_mask:0xf
	ds_read2_b32 v[240:241], v251 offset0:8 offset1:12
	s_waitcnt lgkmcnt(7)
	v_fmac_f32_dpp v92, -v242, v86 quad_perm:[0,0,0,0] row_mask:0xf bank_mask:0xf
	v_fmac_f32_dpp v110, -v242, v88 quad_perm:[1,1,1,1] row_mask:0xf bank_mask:0xf
	v_fmac_f32_dpp v111, -v242, v90 quad_perm:[2,2,2,2] row_mask:0xf bank_mask:0xf
	ds_read2_b32 v[242:243], v251 offset0:16 offset1:20
	v_add_f32_e32 v92, v92, v110
	v_add_f32_e32 v111, v111, v112
	v_add_f32_e32 v92, v92, v111
	s_waitcnt lgkmcnt(7)
	v_fmac_f32_dpp v94, -v244, v4 quad_perm:[0,0,0,0] row_mask:0xf bank_mask:0xf
	v_mul_f32_dpp v110, -v244, v2 quad_perm:[1,1,1,1] row_mask:0xf bank_mask:0xf
	v_mul_f32_dpp v111, -v244, v3 quad_perm:[2,2,2,2] row_mask:0xf bank_mask:0xf
	v_mul_f32_dpp v112, -v244, v5 quad_perm:[3,3,3,3] row_mask:0xf bank_mask:0xf
	v_fmac_f32_dpp v94, -v245, v6 quad_perm:[0,0,0,0] row_mask:0xf bank_mask:0xf
	v_fmac_f32_dpp v110, -v245, v7 quad_perm:[1,1,1,1] row_mask:0xf bank_mask:0xf
	v_fmac_f32_dpp v111, -v245, v8 quad_perm:[2,2,2,2] row_mask:0xf bank_mask:0xf
	v_fmac_f32_dpp v112, -v245, v9 quad_perm:[3,3,3,3] row_mask:0xf bank_mask:0xf
	ds_read2_b32 v[244:245], v251 offset0:24 offset1:28
	s_waitcnt lgkmcnt(7)
	v_fmac_f32_dpp v94, -v230, v10 quad_perm:[0,0,0,0] row_mask:0xf bank_mask:0xf
	v_fmac_f32_dpp v110, -v230, v12 quad_perm:[1,1,1,1] row_mask:0xf bank_mask:0xf
	v_fmac_f32_dpp v111, -v230, v13 quad_perm:[2,2,2,2] row_mask:0xf bank_mask:0xf
	v_fmac_f32_dpp v112, -v230, v14 quad_perm:[3,3,3,3] row_mask:0xf bank_mask:0xf
	v_fmac_f32_dpp v94, -v231, v15 quad_perm:[0,0,0,0] row_mask:0xf bank_mask:0xf
	v_fmac_f32_dpp v110, -v231, v17 quad_perm:[1,1,1,1] row_mask:0xf bank_mask:0xf
	v_fmac_f32_dpp v111, -v231, v18 quad_perm:[2,2,2,2] row_mask:0xf bank_mask:0xf
	v_fmac_f32_dpp v112, -v231, v19 quad_perm:[3,3,3,3] row_mask:0xf bank_mask:0xf
	ds_read2_b32 v[230:231], v251 offset0:32 offset1:36
	s_waitcnt lgkmcnt(7)
	v_fmac_f32_dpp v94, -v232, v21 quad_perm:[0,0,0,0] row_mask:0xf bank_mask:0xf
	v_fmac_f32_dpp v110, -v232, v22 quad_perm:[1,1,1,1] row_mask:0xf bank_mask:0xf
	v_fmac_f32_dpp v111, -v232, v23 quad_perm:[2,2,2,2] row_mask:0xf bank_mask:0xf
	v_fmac_f32_dpp v112, -v232, v25 quad_perm:[3,3,3,3] row_mask:0xf bank_mask:0xf
	v_fmac_f32_dpp v94, -v233, v26 quad_perm:[0,0,0,0] row_mask:0xf bank_mask:0xf
	v_fmac_f32_dpp v110, -v233, v28 quad_perm:[1,1,1,1] row_mask:0xf bank_mask:0xf
	v_fmac_f32_dpp v111, -v233, v29 quad_perm:[2,2,2,2] row_mask:0xf bank_mask:0xf
	v_fmac_f32_dpp v112, -v233, v31 quad_perm:[3,3,3,3] row_mask:0xf bank_mask:0xf
	v_add_u32_e32 v251, 0x110, v251
	ds_read2_b32 v[232:233], v251 offset0:0 offset1:4
	s_waitcnt lgkmcnt(7)
	v_fmac_f32_dpp v94, -v234, v32 quad_perm:[0,0,0,0] row_mask:0xf bank_mask:0xf
	v_fmac_f32_dpp v110, -v234, v43 quad_perm:[1,1,1,1] row_mask:0xf bank_mask:0xf
	v_fmac_f32_dpp v111, -v234, v47 quad_perm:[2,2,2,2] row_mask:0xf bank_mask:0xf
	v_fmac_f32_dpp v112, -v234, v50 quad_perm:[3,3,3,3] row_mask:0xf bank_mask:0xf
	v_fmac_f32_dpp v94, -v235, v52 quad_perm:[0,0,0,0] row_mask:0xf bank_mask:0xf
	v_fmac_f32_dpp v110, -v235, v81 quad_perm:[1,1,1,1] row_mask:0xf bank_mask:0xf
	v_fmac_f32_dpp v111, -v235, v82 quad_perm:[2,2,2,2] row_mask:0xf bank_mask:0xf
	v_fmac_f32_dpp v112, -v235, v84 quad_perm:[3,3,3,3] row_mask:0xf bank_mask:0xf
	ds_read2_b32 v[234:235], v251 offset0:8 offset1:12
	s_waitcnt lgkmcnt(7)
	v_fmac_f32_dpp v94, -v236, v86 quad_perm:[0,0,0,0] row_mask:0xf bank_mask:0xf
	v_fmac_f32_dpp v110, -v236, v88 quad_perm:[1,1,1,1] row_mask:0xf bank_mask:0xf
	v_fmac_f32_dpp v111, -v236, v90 quad_perm:[2,2,2,2] row_mask:0xf bank_mask:0xf
	v_fmac_f32_dpp v112, -v236, v92 quad_perm:[3,3,3,3] row_mask:0xf bank_mask:0xf
	ds_read2_b32 v[236:237], v251 offset0:16 offset1:20
	v_add_f32_e32 v94, v94, v110
	v_add_f32_e32 v111, v111, v112
	v_add_f32_e32 v94, v94, v111
	s_waitcnt lgkmcnt(7)
	v_fmac_f32_dpp v96, -v238, v4 quad_perm:[0,0,0,0] row_mask:0xf bank_mask:0xf
	v_mul_f32_dpp v110, -v238, v2 quad_perm:[1,1,1,1] row_mask:0xf bank_mask:0xf
	v_mul_f32_dpp v111, -v238, v3 quad_perm:[2,2,2,2] row_mask:0xf bank_mask:0xf
	v_mul_f32_dpp v112, -v238, v5 quad_perm:[3,3,3,3] row_mask:0xf bank_mask:0xf
	v_fmac_f32_dpp v96, -v239, v6 quad_perm:[0,0,0,0] row_mask:0xf bank_mask:0xf
	v_fmac_f32_dpp v110, -v239, v7 quad_perm:[1,1,1,1] row_mask:0xf bank_mask:0xf
	v_fmac_f32_dpp v111, -v239, v8 quad_perm:[2,2,2,2] row_mask:0xf bank_mask:0xf
	v_fmac_f32_dpp v112, -v239, v9 quad_perm:[3,3,3,3] row_mask:0xf bank_mask:0xf
	ds_read2_b32 v[238:239], v251 offset0:24 offset1:28
	s_waitcnt lgkmcnt(7)
	v_fmac_f32_dpp v96, -v240, v10 quad_perm:[0,0,0,0] row_mask:0xf bank_mask:0xf
	v_fmac_f32_dpp v110, -v240, v12 quad_perm:[1,1,1,1] row_mask:0xf bank_mask:0xf
	v_fmac_f32_dpp v111, -v240, v13 quad_perm:[2,2,2,2] row_mask:0xf bank_mask:0xf
	v_fmac_f32_dpp v112, -v240, v14 quad_perm:[3,3,3,3] row_mask:0xf bank_mask:0xf
	v_fmac_f32_dpp v96, -v241, v15 quad_perm:[0,0,0,0] row_mask:0xf bank_mask:0xf
	v_fmac_f32_dpp v110, -v241, v17 quad_perm:[1,1,1,1] row_mask:0xf bank_mask:0xf
	v_fmac_f32_dpp v111, -v241, v18 quad_perm:[2,2,2,2] row_mask:0xf bank_mask:0xf
	v_fmac_f32_dpp v112, -v241, v19 quad_perm:[3,3,3,3] row_mask:0xf bank_mask:0xf
	ds_read2_b32 v[240:241], v251 offset0:32 offset1:36
	s_waitcnt lgkmcnt(7)
; DI void phase_gdn_c1(const Ctx& c) {
;     ...
; #pragma unroll
;       for (int i = 1; i < 64; ++i) {
;         float s0 = sol[i], s1 = 0.f, s2 = 0.f, s3 = 0.f;
; #pragma unroll
;         for (int m = 0; m < i; ++m) {
;           const float t_ = Am[i * 68 + m] * sol[m];
;           if ((m & 3) == 0) s0 -= t_; else if ((m & 3) == 1) s1 -= t_; else if ((m & 3) == 2) s2 -= t_; else s3 -= t_;
;         }
;         sol[i] = (s0 + s1) + (s2 + s3);
;       }
	v_fmac_f32_dpp v96, -v242, v21 quad_perm:[0,0,0,0] row_mask:0xf bank_mask:0xf
	v_fmac_f32_dpp v110, -v242, v22 quad_perm:[1,1,1,1] row_mask:0xf bank_mask:0xf
	v_fmac_f32_dpp v111, -v242, v23 quad_perm:[2,2,2,2] row_mask:0xf bank_mask:0xf
	v_fmac_f32_dpp v112, -v242, v25 quad_perm:[3,3,3,3] row_mask:0xf bank_mask:0xf
	v_fmac_f32_dpp v96, -v243, v26 quad_perm:[0,0,0,0] row_mask:0xf bank_mask:0xf
	v_fmac_f32_dpp v110, -v243, v28 quad_perm:[1,1,1,1] row_mask:0xf bank_mask:0xf
	v_fmac_f32_dpp v111, -v243, v29 quad_perm:[2,2,2,2] row_mask:0xf bank_mask:0xf
	v_fmac_f32_dpp v112, -v243, v31 quad_perm:[3,3,3,3] row_mask:0xf bank_mask:0xf
	v_add_u32_e32 v251, 0x110, v251
	ds_read2_b32 v[242:243], v251 offset0:0 offset1:4
	s_waitcnt lgkmcnt(7)
	v_fmac_f32_dpp v96, -v244, v32 quad_perm:[0,0,0,0] row_mask:0xf bank_mask:0xf
	v_fmac_f32_dpp v110, -v244, v43 quad_perm:[1,1,1,1] row_mask:0xf bank_mask:0xf
	v_fmac_f32_dpp v111, -v244, v47 quad_perm:[2,2,2,2] row_mask:0xf bank_mask:0xf
	v_fmac_f32_dpp v112, -v244, v50 quad_perm:[3,3,3,3] row_mask:0xf bank_mask:0xf
	v_fmac_f32_dpp v96, -v245, v52 quad_perm:[0,0,0,0] row_mask:0xf bank_mask:0xf
	v_fmac_f32_dpp v110, -v245, v81 quad_perm:[1,1,1,1] row_mask:0xf bank_mask:0xf
	v_fmac_f32_dpp v111, -v245, v82 quad_perm:[2,2,2,2] row_mask:0xf bank_mask:0xf
	v_fmac_f32_dpp v112, -v245, v84 quad_perm:[3,3,3,3] row_mask:0xf bank_mask:0xf
	ds_read2_b32 v[244:245], v251 offset0:8 offset1:12
	s_waitcnt lgkmcnt(7)
	v_fmac_f32_dpp v96, -v230, v86 quad_perm:[0,0,0,0] row_mask:0xf bank_mask:0xf
	v_fmac_f32_dpp v110, -v230, v88 quad_perm:[1,1,1,1] row_mask:0xf bank_mask:0xf
	v_fmac_f32_dpp v111, -v230, v90 quad_perm:[2,2,2,2] row_mask:0xf bank_mask:0xf
	v_fmac_f32_dpp v112, -v230, v92 quad_perm:[3,3,3,3] row_mask:0xf bank_mask:0xf
	v_fmac_f32_dpp v96, -v231, v94 quad_perm:[0,0,0,0] row_mask:0xf bank_mask:0xf
	ds_read2_b32 v[230:231], v251 offset0:16 offset1:20
	v_add_f32_e32 v96, v96, v110
	v_add_f32_e32 v111, v111, v112
	v_add_f32_e32 v96, v96, v111
	s_waitcnt lgkmcnt(7)
	v_fmac_f32_dpp v98, -v232, v4 quad_perm:[0,0,0,0] row_mask:0xf bank_mask:0xf
	v_mul_f32_dpp v110, -v232, v2 quad_perm:[1,1,1,1] row_mask:0xf bank_mask:0xf
	v_mul_f32_dpp v111, -v232, v3 quad_perm:[2,2,2,2] row_mask:0xf bank_mask:0xf
	v_mul_f32_dpp v112, -v232, v5 quad_perm:[3,3,3,3] row_mask:0xf bank_mask:0xf
	v_fmac_f32_dpp v98, -v233, v6 quad_perm:[0,0,0,0] row_mask:0xf bank_mask:0xf
	v_fmac_f32_dpp v110, -v233, v7 quad_perm:[1,1,1,1] row_mask:0xf bank_mask:0xf
	v_fmac_f32_dpp v111, -v233, v8 quad_perm:[2,2,2,2] row_mask:0xf bank_mask:0xf
	v_fmac_f32_dpp v112, -v233, v9 quad_perm:[3,3,3,3] row_mask:0xf bank_mask:0xf
	ds_read2_b32 v[232:233], v251 offset0:24 offset1:28
	s_waitcnt lgkmcnt(7)
	v_fmac_f32_dpp v98, -v234, v10 quad_perm:[0,0,0,0] row_mask:0xf bank_mask:0xf
	v_fmac_f32_dpp v110, -v234, v12 quad_perm:[1,1,1,1] row_mask:0xf bank_mask:0xf
	v_fmac_f32_dpp v111, -v234, v13 quad_perm:[2,2,2,2] row_mask:0xf bank_mask:0xf
	v_fmac_f32_dpp v112, -v234, v14 quad_perm:[3,3,3,3] row_mask:0xf bank_mask:0xf
	v_fmac_f32_dpp v98, -v235, v15 quad_perm:[0,0,0,0] row_mask:0xf bank_mask:0xf
	v_fmac_f32_dpp v110, -v235, v17 quad_perm:[1,1,1,1] row_mask:0xf bank_mask:0xf
	v_fmac_f32_dpp v111, -v235, v18 quad_perm:[2,2,2,2] row_mask:0xf bank_mask:0xf
	v_fmac_f32_dpp v112, -v235, v19 quad_perm:[3,3,3,3] row_mask:0xf bank_mask:0xf
	ds_read2_b32 v[234:235], v251 offset0:32 offset1:36
	s_waitcnt lgkmcnt(7)
	v_fmac_f32_dpp v98, -v236, v21 quad_perm:[0,0,0,0] row_mask:0xf bank_mask:0xf
	v_fmac_f32_dpp v110, -v236, v22 quad_perm:[1,1,1,1] row_mask:0xf bank_mask:0xf
	v_fmac_f32_dpp v111, -v236, v23 quad_perm:[2,2,2,2] row_mask:0xf bank_mask:0xf
	v_fmac_f32_dpp v112, -v236, v25 quad_perm:[3,3,3,3] row_mask:0xf bank_mask:0xf
	v_fmac_f32_dpp v98, -v237, v26 quad_perm:[0,0,0,0] row_mask:0xf bank_mask:0xf
	v_fmac_f32_dpp v110, -v237, v28 quad_perm:[1,1,1,1] row_mask:0xf bank_mask:0xf
	v_fmac_f32_dpp v111, -v237, v29 quad_perm:[2,2,2,2] row_mask:0xf bank_mask:0xf
	v_fmac_f32_dpp v112, -v237, v31 quad_perm:[3,3,3,3] row_mask:0xf bank_mask:0xf
	v_add_u32_e32 v251, 0x110, v251
	ds_read2_b32 v[236:237], v251 offset0:0 offset1:4
	s_waitcnt lgkmcnt(7)
	v_fmac_f32_dpp v98, -v238, v32 quad_perm:[0,0,0,0] row_mask:0xf bank_mask:0xf
	v_fmac_f32_dpp v110, -v238, v43 quad_perm:[1,1,1,1] row_mask:0xf bank_mask:0xf
	v_fmac_f32_dpp v111, -v238, v47 quad_perm:[2,2,2,2] row_mask:0xf bank_mask:0xf
	v_fmac_f32_dpp v112, -v238, v50 quad_perm:[3,3,3,3] row_mask:0xf bank_mask:0xf
	v_fmac_f32_dpp v98, -v239, v52 quad_perm:[0,0,0,0] row_mask:0xf bank_mask:0xf
	v_fmac_f32_dpp v110, -v239, v81 quad_perm:[1,1,1,1] row_mask:0xf bank_mask:0xf
	v_fmac_f32_dpp v111, -v239, v82 quad_perm:[2,2,2,2] row_mask:0xf bank_mask:0xf
	v_fmac_f32_dpp v112, -v239, v84 quad_perm:[3,3,3,3] row_mask:0xf bank_mask:0xf
	ds_read2_b32 v[238:239], v251 offset0:8 offset1:12
	s_waitcnt lgkmcnt(7)
	v_fmac_f32_dpp v98, -v240, v86 quad_perm:[0,0,0,0] row_mask:0xf bank_mask:0xf
	v_fmac_f32_dpp v110, -v240, v88 quad_perm:[1,1,1,1] row_mask:0xf bank_mask:0xf
	v_fmac_f32_dpp v111, -v240, v90 quad_perm:[2,2,2,2] row_mask:0xf bank_mask:0xf
	v_fmac_f32_dpp v112, -v240, v92 quad_perm:[3,3,3,3] row_mask:0xf bank_mask:0xf
	v_fmac_f32_dpp v98, -v241, v94 quad_perm:[0,0,0,0] row_mask:0xf bank_mask:0xf
	v_fmac_f32_dpp v110, -v241, v96 quad_perm:[1,1,1,1] row_mask:0xf bank_mask:0xf
	ds_read2_b32 v[240:241], v251 offset0:16 offset1:20
	v_add_f32_e32 v98, v98, v110
	v_add_f32_e32 v111, v111, v112
	v_add_f32_e32 v98, v98, v111
	s_waitcnt lgkmcnt(7)
; DI void phase_gdn_c1(const Ctx& c) {
;     ...
; #pragma unroll
;       for (int i = 1; i < 64; ++i) {
;         float s0 = sol[i], s1 = 0.f, s2 = 0.f, s3 = 0.f;
; #pragma unroll
;         for (int m = 0; m < i; ++m) {
;           const float t_ = Am[i * 68 + m] * sol[m];
;           if ((m & 3) == 0) s0 -= t_; else if ((m & 3) == 1) s1 -= t_; else if ((m & 3) == 2) s2 -= t_; else s3 -= t_;
;         }
;         sol[i] = (s0 + s1) + (s2 + s3);
;       }
	v_fmac_f32_dpp v100, -v242, v4 quad_perm:[0,0,0,0] row_mask:0xf bank_mask:0xf
	v_mul_f32_dpp v110, -v242, v2 quad_perm:[1,1,1,1] row_mask:0xf bank_mask:0xf
	v_mul_f32_dpp v111, -v242, v3 quad_perm:[2,2,2,2] row_mask:0xf bank_mask:0xf
	v_mul_f32_dpp v112, -v242, v5 quad_perm:[3,3,3,3] row_mask:0xf bank_mask:0xf
	v_fmac_f32_dpp v100, -v243, v6 quad_perm:[0,0,0,0] row_mask:0xf bank_mask:0xf
	v_fmac_f32_dpp v110, -v243, v7 quad_perm:[1,1,1,1] row_mask:0xf bank_mask:0xf
	v_fmac_f32_dpp v111, -v243, v8 quad_perm:[2,2,2,2] row_mask:0xf bank_mask:0xf
	v_fmac_f32_dpp v112, -v243, v9 quad_perm:[3,3,3,3] row_mask:0xf bank_mask:0xf
	ds_read2_b32 v[242:243], v251 offset0:24 offset1:28
	s_waitcnt lgkmcnt(7)
	v_fmac_f32_dpp v100, -v244, v10 quad_perm:[0,0,0,0] row_mask:0xf bank_mask:0xf
	v_fmac_f32_dpp v110, -v244, v12 quad_perm:[1,1,1,1] row_mask:0xf bank_mask:0xf
	v_fmac_f32_dpp v111, -v244, v13 quad_perm:[2,2,2,2] row_mask:0xf bank_mask:0xf
	v_fmac_f32_dpp v112, -v244, v14 quad_perm:[3,3,3,3] row_mask:0xf bank_mask:0xf
	v_fmac_f32_dpp v100, -v245, v15 quad_perm:[0,0,0,0] row_mask:0xf bank_mask:0xf
	v_fmac_f32_dpp v110, -v245, v17 quad_perm:[1,1,1,1] row_mask:0xf bank_mask:0xf
	v_fmac_f32_dpp v111, -v245, v18 quad_perm:[2,2,2,2] row_mask:0xf bank_mask:0xf
	v_fmac_f32_dpp v112, -v245, v19 quad_perm:[3,3,3,3] row_mask:0xf bank_mask:0xf
	ds_read2_b32 v[244:245], v251 offset0:32 offset1:36
	s_waitcnt lgkmcnt(7)
	v_fmac_f32_dpp v100, -v230, v21 quad_perm:[0,0,0,0] row_mask:0xf bank_mask:0xf
	v_fmac_f32_dpp v110, -v230, v22 quad_perm:[1,1,1,1] row_mask:0xf bank_mask:0xf
	v_fmac_f32_dpp v111, -v230, v23 quad_perm:[2,2,2,2] row_mask:0xf bank_mask:0xf
	v_fmac_f32_dpp v112, -v230, v25 quad_perm:[3,3,3,3] row_mask:0xf bank_mask:0xf
	v_fmac_f32_dpp v100, -v231, v26 quad_perm:[0,0,0,0] row_mask:0xf bank_mask:0xf
	v_fmac_f32_dpp v110, -v231, v28 quad_perm:[1,1,1,1] row_mask:0xf bank_mask:0xf
	v_fmac_f32_dpp v111, -v231, v29 quad_perm:[2,2,2,2] row_mask:0xf bank_mask:0xf
	v_fmac_f32_dpp v112, -v231, v31 quad_perm:[3,3,3,3] row_mask:0xf bank_mask:0xf
	v_add_u32_e32 v251, 0x110, v251
	ds_read2_b32 v[230:231], v251 offset0:0 offset1:4
	s_waitcnt lgkmcnt(7)
	v_fmac_f32_dpp v100, -v232, v32 quad_perm:[0,0,0,0] row_mask:0xf bank_mask:0xf
	v_fmac_f32_dpp v110, -v232, v43 quad_perm:[1,1,1,1] row_mask:0xf bank_mask:0xf
	v_fmac_f32_dpp v111, -v232, v47 quad_perm:[2,2,2,2] row_mask:0xf bank_mask:0xf
	v_fmac_f32_dpp v112, -v232, v50 quad_perm:[3,3,3,3] row_mask:0xf bank_mask:0xf
	v_fmac_f32_dpp v100, -v233, v52 quad_perm:[0,0,0,0] row_mask:0xf bank_mask:0xf
	v_fmac_f32_dpp v110, -v233, v81 quad_perm:[1,1,1,1] row_mask:0xf bank_mask:0xf
	v_fmac_f32_dpp v111, -v233, v82 quad_perm:[2,2,2,2] row_mask:0xf bank_mask:0xf
	v_fmac_f32_dpp v112, -v233, v84 quad_perm:[3,3,3,3] row_mask:0xf bank_mask:0xf
	ds_read2_b32 v[232:233], v251 offset0:8 offset1:12
	s_waitcnt lgkmcnt(7)
	v_fmac_f32_dpp v100, -v234, v86 quad_perm:[0,0,0,0] row_mask:0xf bank_mask:0xf
	v_fmac_f32_dpp v110, -v234, v88 quad_perm:[1,1,1,1] row_mask:0xf bank_mask:0xf
	v_fmac_f32_dpp v111, -v234, v90 quad_perm:[2,2,2,2] row_mask:0xf bank_mask:0xf
	v_fmac_f32_dpp v112, -v234, v92 quad_perm:[3,3,3,3] row_mask:0xf bank_mask:0xf
	v_fmac_f32_dpp v100, -v235, v94 quad_perm:[0,0,0,0] row_mask:0xf bank_mask:0xf
	v_fmac_f32_dpp v110, -v235, v96 quad_perm:[1,1,1,1] row_mask:0xf bank_mask:0xf
	v_fmac_f32_dpp v111, -v235, v98 quad_perm:[2,2,2,2] row_mask:0xf bank_mask:0xf
	ds_read2_b32 v[234:235], v251 offset0:16 offset1:20
	v_add_f32_e32 v100, v100, v110
	v_add_f32_e32 v111, v111, v112
	v_add_f32_e32 v100, v100, v111
	s_waitcnt lgkmcnt(7)
	v_fmac_f32_dpp v103, -v236, v4 quad_perm:[0,0,0,0] row_mask:0xf bank_mask:0xf
	v_mul_f32_dpp v110, -v236, v2 quad_perm:[1,1,1,1] row_mask:0xf bank_mask:0xf
	v_mul_f32_dpp v111, -v236, v3 quad_perm:[2,2,2,2] row_mask:0xf bank_mask:0xf
	v_mul_f32_dpp v112, -v236, v5 quad_perm:[3,3,3,3] row_mask:0xf bank_mask:0xf
	v_fmac_f32_dpp v103, -v237, v6 quad_perm:[0,0,0,0] row_mask:0xf bank_mask:0xf
	v_fmac_f32_dpp v110, -v237, v7 quad_perm:[1,1,1,1] row_mask:0xf bank_mask:0xf
	v_fmac_f32_dpp v111, -v237, v8 quad_perm:[2,2,2,2] row_mask:0xf bank_mask:0xf
	v_fmac_f32_dpp v112, -v237, v9 quad_perm:[3,3,3,3] row_mask:0xf bank_mask:0xf
	ds_read2_b32 v[236:237], v251 offset0:24 offset1:28
	s_waitcnt lgkmcnt(7)
	v_fmac_f32_dpp v103, -v238, v10 quad_perm:[0,0,0,0] row_mask:0xf bank_mask:0xf
	v_fmac_f32_dpp v110, -v238, v12 quad_perm:[1,1,1,1] row_mask:0xf bank_mask:0xf
	v_fmac_f32_dpp v111, -v238, v13 quad_perm:[2,2,2,2] row_mask:0xf bank_mask:0xf
	v_fmac_f32_dpp v112, -v238, v14 quad_perm:[3,3,3,3] row_mask:0xf bank_mask:0xf
	v_fmac_f32_dpp v103, -v239, v15 quad_perm:[0,0,0,0] row_mask:0xf bank_mask:0xf
	v_fmac_f32_dpp v110, -v239, v17 quad_perm:[1,1,1,1] row_mask:0xf bank_mask:0xf
	v_fmac_f32_dpp v111, -v239, v18 quad_perm:[2,2,2,2] row_mask:0xf bank_mask:0xf
	v_fmac_f32_dpp v112, -v239, v19 quad_perm:[3,3,3,3] row_mask:0xf bank_mask:0xf
	ds_read2_b32 v[238:239], v251 offset0:32 offset1:36
	s_waitcnt lgkmcnt(7)
	v_fmac_f32_dpp v103, -v240, v21 quad_perm:[0,0,0,0] row_mask:0xf bank_mask:0xf
	v_fmac_f32_dpp v110, -v240, v22 quad_perm:[1,1,1,1] row_mask:0xf bank_mask:0xf
	v_fmac_f32_dpp v111, -v240, v23 quad_perm:[2,2,2,2] row_mask:0xf bank_mask:0xf
	v_fmac_f32_dpp v112, -v240, v25 quad_perm:[3,3,3,3] row_mask:0xf bank_mask:0xf
	v_fmac_f32_dpp v103, -v241, v26 quad_perm:[0,0,0,0] row_mask:0xf bank_mask:0xf
	v_fmac_f32_dpp v110, -v241, v28 quad_perm:[1,1,1,1] row_mask:0xf bank_mask:0xf
	v_fmac_f32_dpp v111, -v241, v29 quad_perm:[2,2,2,2] row_mask:0xf bank_mask:0xf
	v_fmac_f32_dpp v112, -v241, v31 quad_perm:[3,3,3,3] row_mask:0xf bank_mask:0xf
	ds_read2_b32 v[240:241], v251 offset0:40 offset1:40
	s_waitcnt lgkmcnt(7)
; DI void phase_gdn_c1(const Ctx& c) {
;     ...
; #pragma unroll
;       for (int i = 1; i < 64; ++i) {
;         float s0 = sol[i], s1 = 0.f, s2 = 0.f, s3 = 0.f;
; #pragma unroll
;         for (int m = 0; m < i; ++m) {
;           const float t_ = Am[i * 68 + m] * sol[m];
;           if ((m & 3) == 0) s0 -= t_; else if ((m & 3) == 1) s1 -= t_; else if ((m & 3) == 2) s2 -= t_; else s3 -= t_;
;         }
;         sol[i] = (s0 + s1) + (s2 + s3);
;       }
	v_fmac_f32_dpp v103, -v242, v32 quad_perm:[0,0,0,0] row_mask:0xf bank_mask:0xf
	v_fmac_f32_dpp v110, -v242, v43 quad_perm:[1,1,1,1] row_mask:0xf bank_mask:0xf
	v_fmac_f32_dpp v111, -v242, v47 quad_perm:[2,2,2,2] row_mask:0xf bank_mask:0xf
	v_fmac_f32_dpp v112, -v242, v50 quad_perm:[3,3,3,3] row_mask:0xf bank_mask:0xf
	v_fmac_f32_dpp v103, -v243, v52 quad_perm:[0,0,0,0] row_mask:0xf bank_mask:0xf
	v_fmac_f32_dpp v110, -v243, v81 quad_perm:[1,1,1,1] row_mask:0xf bank_mask:0xf
	v_fmac_f32_dpp v111, -v243, v82 quad_perm:[2,2,2,2] row_mask:0xf bank_mask:0xf
	v_fmac_f32_dpp v112, -v243, v84 quad_perm:[3,3,3,3] row_mask:0xf bank_mask:0xf
	v_add_u32_e32 v251, 0x110, v251
	ds_read2_b32 v[242:243], v251 offset0:0 offset1:4
	s_waitcnt lgkmcnt(7)
	v_fmac_f32_dpp v103, -v244, v86 quad_perm:[0,0,0,0] row_mask:0xf bank_mask:0xf
	v_fmac_f32_dpp v110, -v244, v88 quad_perm:[1,1,1,1] row_mask:0xf bank_mask:0xf
	v_fmac_f32_dpp v111, -v244, v90 quad_perm:[2,2,2,2] row_mask:0xf bank_mask:0xf
	v_fmac_f32_dpp v112, -v244, v92 quad_perm:[3,3,3,3] row_mask:0xf bank_mask:0xf
	v_fmac_f32_dpp v103, -v245, v94 quad_perm:[0,0,0,0] row_mask:0xf bank_mask:0xf
	v_fmac_f32_dpp v110, -v245, v96 quad_perm:[1,1,1,1] row_mask:0xf bank_mask:0xf
	v_fmac_f32_dpp v111, -v245, v98 quad_perm:[2,2,2,2] row_mask:0xf bank_mask:0xf
	v_fmac_f32_dpp v112, -v245, v100 quad_perm:[3,3,3,3] row_mask:0xf bank_mask:0xf
	ds_read2_b32 v[244:245], v251 offset0:8 offset1:12
	v_add_f32_e32 v103, v103, v110
	v_add_f32_e32 v111, v111, v112
	v_add_f32_e32 v103, v103, v111
	s_waitcnt lgkmcnt(7)
	v_fmac_f32_dpp v105, -v230, v4 quad_perm:[0,0,0,0] row_mask:0xf bank_mask:0xf
	v_mul_f32_dpp v110, -v230, v2 quad_perm:[1,1,1,1] row_mask:0xf bank_mask:0xf
	v_mul_f32_dpp v111, -v230, v3 quad_perm:[2,2,2,2] row_mask:0xf bank_mask:0xf
	v_mul_f32_dpp v112, -v230, v5 quad_perm:[3,3,3,3] row_mask:0xf bank_mask:0xf
	v_fmac_f32_dpp v105, -v231, v6 quad_perm:[0,0,0,0] row_mask:0xf bank_mask:0xf
	v_fmac_f32_dpp v110, -v231, v7 quad_perm:[1,1,1,1] row_mask:0xf bank_mask:0xf
	v_fmac_f32_dpp v111, -v231, v8 quad_perm:[2,2,2,2] row_mask:0xf bank_mask:0xf
	v_fmac_f32_dpp v112, -v231, v9 quad_perm:[3,3,3,3] row_mask:0xf bank_mask:0xf
	ds_read2_b32 v[230:231], v251 offset0:16 offset1:20
	s_waitcnt lgkmcnt(7)
	v_fmac_f32_dpp v105, -v232, v10 quad_perm:[0,0,0,0] row_mask:0xf bank_mask:0xf
	v_fmac_f32_dpp v110, -v232, v12 quad_perm:[1,1,1,1] row_mask:0xf bank_mask:0xf
	v_fmac_f32_dpp v111, -v232, v13 quad_perm:[2,2,2,2] row_mask:0xf bank_mask:0xf
	v_fmac_f32_dpp v112, -v232, v14 quad_perm:[3,3,3,3] row_mask:0xf bank_mask:0xf
	v_fmac_f32_dpp v105, -v233, v15 quad_perm:[0,0,0,0] row_mask:0xf bank_mask:0xf
	v_fmac_f32_dpp v110, -v233, v17 quad_perm:[1,1,1,1] row_mask:0xf bank_mask:0xf
	v_fmac_f32_dpp v111, -v233, v18 quad_perm:[2,2,2,2] row_mask:0xf bank_mask:0xf
	v_fmac_f32_dpp v112, -v233, v19 quad_perm:[3,3,3,3] row_mask:0xf bank_mask:0xf
	ds_read2_b32 v[232:233], v251 offset0:24 offset1:28
	s_waitcnt lgkmcnt(7)
	v_fmac_f32_dpp v105, -v234, v21 quad_perm:[0,0,0,0] row_mask:0xf bank_mask:0xf
	v_fmac_f32_dpp v110, -v234, v22 quad_perm:[1,1,1,1] row_mask:0xf bank_mask:0xf
	v_fmac_f32_dpp v111, -v234, v23 quad_perm:[2,2,2,2] row_mask:0xf bank_mask:0xf
	v_fmac_f32_dpp v112, -v234, v25 quad_perm:[3,3,3,3] row_mask:0xf bank_mask:0xf
	v_fmac_f32_dpp v105, -v235, v26 quad_perm:[0,0,0,0] row_mask:0xf bank_mask:0xf
	v_fmac_f32_dpp v110, -v235, v28 quad_perm:[1,1,1,1] row_mask:0xf bank_mask:0xf
	v_fmac_f32_dpp v111, -v235, v29 quad_perm:[2,2,2,2] row_mask:0xf bank_mask:0xf
	v_fmac_f32_dpp v112, -v235, v31 quad_perm:[3,3,3,3] row_mask:0xf bank_mask:0xf
	ds_read2_b32 v[234:235], v251 offset0:32 offset1:36
	s_waitcnt lgkmcnt(7)
	v_fmac_f32_dpp v105, -v236, v32 quad_perm:[0,0,0,0] row_mask:0xf bank_mask:0xf
	v_fmac_f32_dpp v110, -v236, v43 quad_perm:[1,1,1,1] row_mask:0xf bank_mask:0xf
	v_fmac_f32_dpp v111, -v236, v47 quad_perm:[2,2,2,2] row_mask:0xf bank_mask:0xf
	v_fmac_f32_dpp v112, -v236, v50 quad_perm:[3,3,3,3] row_mask:0xf bank_mask:0xf
	v_fmac_f32_dpp v105, -v237, v52 quad_perm:[0,0,0,0] row_mask:0xf bank_mask:0xf
	v_fmac_f32_dpp v110, -v237, v81 quad_perm:[1,1,1,1] row_mask:0xf bank_mask:0xf
	v_fmac_f32_dpp v111, -v237, v82 quad_perm:[2,2,2,2] row_mask:0xf bank_mask:0xf
	v_fmac_f32_dpp v112, -v237, v84 quad_perm:[3,3,3,3] row_mask:0xf bank_mask:0xf
	ds_read2_b32 v[236:237], v251 offset0:40 offset1:40
	s_waitcnt lgkmcnt(7)
	v_fmac_f32_dpp v105, -v238, v86 quad_perm:[0,0,0,0] row_mask:0xf bank_mask:0xf
	v_fmac_f32_dpp v110, -v238, v88 quad_perm:[1,1,1,1] row_mask:0xf bank_mask:0xf
	v_fmac_f32_dpp v111, -v238, v90 quad_perm:[2,2,2,2] row_mask:0xf bank_mask:0xf
	v_fmac_f32_dpp v112, -v238, v92 quad_perm:[3,3,3,3] row_mask:0xf bank_mask:0xf
	v_fmac_f32_dpp v105, -v239, v94 quad_perm:[0,0,0,0] row_mask:0xf bank_mask:0xf
	v_fmac_f32_dpp v110, -v239, v96 quad_perm:[1,1,1,1] row_mask:0xf bank_mask:0xf
	v_fmac_f32_dpp v111, -v239, v98 quad_perm:[2,2,2,2] row_mask:0xf bank_mask:0xf
	v_fmac_f32_dpp v112, -v239, v100 quad_perm:[3,3,3,3] row_mask:0xf bank_mask:0xf
	v_add_u32_e32 v251, 0x110, v251
	ds_read2_b32 v[238:239], v251 offset0:0 offset1:4
	s_waitcnt lgkmcnt(7)
	v_fmac_f32_dpp v105, -v240, v103 quad_perm:[0,0,0,0] row_mask:0xf bank_mask:0xf
	ds_read2_b32 v[240:241], v251 offset0:8 offset1:12
	v_add_f32_e32 v105, v105, v110
	v_add_f32_e32 v111, v111, v112
	v_add_f32_e32 v105, v105, v111
	s_waitcnt lgkmcnt(7)
; DI void phase_gdn_c1(const Ctx& c) {
;     ...
; #pragma unroll
;       for (int i = 1; i < 64; ++i) {
;         float s0 = sol[i], s1 = 0.f, s2 = 0.f, s3 = 0.f;
; #pragma unroll
;         for (int m = 0; m < i; ++m) {
;           const float t_ = Am[i * 68 + m] * sol[m];
;           if ((m & 3) == 0) s0 -= t_; else if ((m & 3) == 1) s1 -= t_; else if ((m & 3) == 2) s2 -= t_; else s3 -= t_;
;         }
;         sol[i] = (s0 + s1) + (s2 + s3);
;       }
	v_fmac_f32_dpp v104, -v242, v4 quad_perm:[0,0,0,0] row_mask:0xf bank_mask:0xf
	v_mul_f32_dpp v110, -v242, v2 quad_perm:[1,1,1,1] row_mask:0xf bank_mask:0xf
	v_mul_f32_dpp v111, -v242, v3 quad_perm:[2,2,2,2] row_mask:0xf bank_mask:0xf
	v_mul_f32_dpp v112, -v242, v5 quad_perm:[3,3,3,3] row_mask:0xf bank_mask:0xf
	v_fmac_f32_dpp v104, -v243, v6 quad_perm:[0,0,0,0] row_mask:0xf bank_mask:0xf
	v_fmac_f32_dpp v110, -v243, v7 quad_perm:[1,1,1,1] row_mask:0xf bank_mask:0xf
	v_fmac_f32_dpp v111, -v243, v8 quad_perm:[2,2,2,2] row_mask:0xf bank_mask:0xf
	v_fmac_f32_dpp v112, -v243, v9 quad_perm:[3,3,3,3] row_mask:0xf bank_mask:0xf
	ds_read2_b32 v[242:243], v251 offset0:16 offset1:20
	s_waitcnt lgkmcnt(7)
	v_fmac_f32_dpp v104, -v244, v10 quad_perm:[0,0,0,0] row_mask:0xf bank_mask:0xf
	v_fmac_f32_dpp v110, -v244, v12 quad_perm:[1,1,1,1] row_mask:0xf bank_mask:0xf
	v_fmac_f32_dpp v111, -v244, v13 quad_perm:[2,2,2,2] row_mask:0xf bank_mask:0xf
	v_fmac_f32_dpp v112, -v244, v14 quad_perm:[3,3,3,3] row_mask:0xf bank_mask:0xf
	v_fmac_f32_dpp v104, -v245, v15 quad_perm:[0,0,0,0] row_mask:0xf bank_mask:0xf
	v_fmac_f32_dpp v110, -v245, v17 quad_perm:[1,1,1,1] row_mask:0xf bank_mask:0xf
	v_fmac_f32_dpp v111, -v245, v18 quad_perm:[2,2,2,2] row_mask:0xf bank_mask:0xf
	v_fmac_f32_dpp v112, -v245, v19 quad_perm:[3,3,3,3] row_mask:0xf bank_mask:0xf
	ds_read2_b32 v[244:245], v251 offset0:24 offset1:28
	s_waitcnt lgkmcnt(7)
	v_fmac_f32_dpp v104, -v230, v21 quad_perm:[0,0,0,0] row_mask:0xf bank_mask:0xf
	v_fmac_f32_dpp v110, -v230, v22 quad_perm:[1,1,1,1] row_mask:0xf bank_mask:0xf
	v_fmac_f32_dpp v111, -v230, v23 quad_perm:[2,2,2,2] row_mask:0xf bank_mask:0xf
	v_fmac_f32_dpp v112, -v230, v25 quad_perm:[3,3,3,3] row_mask:0xf bank_mask:0xf
	v_fmac_f32_dpp v104, -v231, v26 quad_perm:[0,0,0,0] row_mask:0xf bank_mask:0xf
	v_fmac_f32_dpp v110, -v231, v28 quad_perm:[1,1,1,1] row_mask:0xf bank_mask:0xf
	v_fmac_f32_dpp v111, -v231, v29 quad_perm:[2,2,2,2] row_mask:0xf bank_mask:0xf
	v_fmac_f32_dpp v112, -v231, v31 quad_perm:[3,3,3,3] row_mask:0xf bank_mask:0xf
	ds_read2_b32 v[230:231], v251 offset0:32 offset1:36
	s_waitcnt lgkmcnt(7)
	v_fmac_f32_dpp v104, -v232, v32 quad_perm:[0,0,0,0] row_mask:0xf bank_mask:0xf
	v_fmac_f32_dpp v110, -v232, v43 quad_perm:[1,1,1,1] row_mask:0xf bank_mask:0xf
	v_fmac_f32_dpp v111, -v232, v47 quad_perm:[2,2,2,2] row_mask:0xf bank_mask:0xf
	v_fmac_f32_dpp v112, -v232, v50 quad_perm:[3,3,3,3] row_mask:0xf bank_mask:0xf
	v_fmac_f32_dpp v104, -v233, v52 quad_perm:[0,0,0,0] row_mask:0xf bank_mask:0xf
	v_fmac_f32_dpp v110, -v233, v81 quad_perm:[1,1,1,1] row_mask:0xf bank_mask:0xf
	v_fmac_f32_dpp v111, -v233, v82 quad_perm:[2,2,2,2] row_mask:0xf bank_mask:0xf
	v_fmac_f32_dpp v112, -v233, v84 quad_perm:[3,3,3,3] row_mask:0xf bank_mask:0xf
	ds_read2_b32 v[232:233], v251 offset0:40 offset1:40
	s_waitcnt lgkmcnt(7)
	v_fmac_f32_dpp v104, -v234, v86 quad_perm:[0,0,0,0] row_mask:0xf bank_mask:0xf
	v_fmac_f32_dpp v110, -v234, v88 quad_perm:[1,1,1,1] row_mask:0xf bank_mask:0xf
	v_fmac_f32_dpp v111, -v234, v90 quad_perm:[2,2,2,2] row_mask:0xf bank_mask:0xf
	v_fmac_f32_dpp v112, -v234, v92 quad_perm:[3,3,3,3] row_mask:0xf bank_mask:0xf
	v_fmac_f32_dpp v104, -v235, v94 quad_perm:[0,0,0,0] row_mask:0xf bank_mask:0xf
	v_fmac_f32_dpp v110, -v235, v96 quad_perm:[1,1,1,1] row_mask:0xf bank_mask:0xf
	v_fmac_f32_dpp v111, -v235, v98 quad_perm:[2,2,2,2] row_mask:0xf bank_mask:0xf
	v_fmac_f32_dpp v112, -v235, v100 quad_perm:[3,3,3,3] row_mask:0xf bank_mask:0xf
	v_add_u32_e32 v251, 0x110, v251
	ds_read2_b32 v[234:235], v251 offset0:0 offset1:4
	s_waitcnt lgkmcnt(7)
	v_fmac_f32_dpp v104, -v236, v103 quad_perm:[0,0,0,0] row_mask:0xf bank_mask:0xf
	v_fmac_f32_dpp v110, -v236, v105 quad_perm:[1,1,1,1] row_mask:0xf bank_mask:0xf
	ds_read2_b32 v[236:237], v251 offset0:8 offset1:12
	v_add_f32_e32 v104, v104, v110
	v_add_f32_e32 v111, v111, v112
	v_add_f32_e32 v104, v104, v111
	s_waitcnt lgkmcnt(7)
	v_fmac_f32_dpp v102, -v238, v4 quad_perm:[0,0,0,0] row_mask:0xf bank_mask:0xf
	v_mul_f32_dpp v110, -v238, v2 quad_perm:[1,1,1,1] row_mask:0xf bank_mask:0xf
	v_mul_f32_dpp v111, -v238, v3 quad_perm:[2,2,2,2] row_mask:0xf bank_mask:0xf
	v_mul_f32_dpp v112, -v238, v5 quad_perm:[3,3,3,3] row_mask:0xf bank_mask:0xf
	v_fmac_f32_dpp v102, -v239, v6 quad_perm:[0,0,0,0] row_mask:0xf bank_mask:0xf
	v_fmac_f32_dpp v110, -v239, v7 quad_perm:[1,1,1,1] row_mask:0xf bank_mask:0xf
	v_fmac_f32_dpp v111, -v239, v8 quad_perm:[2,2,2,2] row_mask:0xf bank_mask:0xf
	v_fmac_f32_dpp v112, -v239, v9 quad_perm:[3,3,3,3] row_mask:0xf bank_mask:0xf
	ds_read2_b32 v[238:239], v251 offset0:16 offset1:20
	s_waitcnt lgkmcnt(7)
	v_fmac_f32_dpp v102, -v240, v10 quad_perm:[0,0,0,0] row_mask:0xf bank_mask:0xf
	v_fmac_f32_dpp v110, -v240, v12 quad_perm:[1,1,1,1] row_mask:0xf bank_mask:0xf
	v_fmac_f32_dpp v111, -v240, v13 quad_perm:[2,2,2,2] row_mask:0xf bank_mask:0xf
	v_fmac_f32_dpp v112, -v240, v14 quad_perm:[3,3,3,3] row_mask:0xf bank_mask:0xf
	v_fmac_f32_dpp v102, -v241, v15 quad_perm:[0,0,0,0] row_mask:0xf bank_mask:0xf
	v_fmac_f32_dpp v110, -v241, v17 quad_perm:[1,1,1,1] row_mask:0xf bank_mask:0xf
	v_fmac_f32_dpp v111, -v241, v18 quad_perm:[2,2,2,2] row_mask:0xf bank_mask:0xf
	v_fmac_f32_dpp v112, -v241, v19 quad_perm:[3,3,3,3] row_mask:0xf bank_mask:0xf
	ds_read2_b32 v[240:241], v251 offset0:24 offset1:28
	s_waitcnt lgkmcnt(7)
; DI void phase_gdn_c1(const Ctx& c) {
;     ...
; #pragma unroll
;       for (int i = 1; i < 64; ++i) {
;         float s0 = sol[i], s1 = 0.f, s2 = 0.f, s3 = 0.f;
; #pragma unroll
;         for (int m = 0; m < i; ++m) {
;           const float t_ = Am[i * 68 + m] * sol[m];
;           if ((m & 3) == 0) s0 -= t_; else if ((m & 3) == 1) s1 -= t_; else if ((m & 3) == 2) s2 -= t_; else s3 -= t_;
;         }
;         sol[i] = (s0 + s1) + (s2 + s3);
;       }
	v_fmac_f32_dpp v102, -v242, v21 quad_perm:[0,0,0,0] row_mask:0xf bank_mask:0xf
	v_fmac_f32_dpp v110, -v242, v22 quad_perm:[1,1,1,1] row_mask:0xf bank_mask:0xf
	v_fmac_f32_dpp v111, -v242, v23 quad_perm:[2,2,2,2] row_mask:0xf bank_mask:0xf
	v_fmac_f32_dpp v112, -v242, v25 quad_perm:[3,3,3,3] row_mask:0xf bank_mask:0xf
	v_fmac_f32_dpp v102, -v243, v26 quad_perm:[0,0,0,0] row_mask:0xf bank_mask:0xf
	v_fmac_f32_dpp v110, -v243, v28 quad_perm:[1,1,1,1] row_mask:0xf bank_mask:0xf
	v_fmac_f32_dpp v111, -v243, v29 quad_perm:[2,2,2,2] row_mask:0xf bank_mask:0xf
	v_fmac_f32_dpp v112, -v243, v31 quad_perm:[3,3,3,3] row_mask:0xf bank_mask:0xf
	ds_read2_b32 v[242:243], v251 offset0:32 offset1:36
	s_waitcnt lgkmcnt(7)
	v_fmac_f32_dpp v102, -v244, v32 quad_perm:[0,0,0,0] row_mask:0xf bank_mask:0xf
	v_fmac_f32_dpp v110, -v244, v43 quad_perm:[1,1,1,1] row_mask:0xf bank_mask:0xf
	v_fmac_f32_dpp v111, -v244, v47 quad_perm:[2,2,2,2] row_mask:0xf bank_mask:0xf
	v_fmac_f32_dpp v112, -v244, v50 quad_perm:[3,3,3,3] row_mask:0xf bank_mask:0xf
	v_fmac_f32_dpp v102, -v245, v52 quad_perm:[0,0,0,0] row_mask:0xf bank_mask:0xf
	v_fmac_f32_dpp v110, -v245, v81 quad_perm:[1,1,1,1] row_mask:0xf bank_mask:0xf
	v_fmac_f32_dpp v111, -v245, v82 quad_perm:[2,2,2,2] row_mask:0xf bank_mask:0xf
	v_fmac_f32_dpp v112, -v245, v84 quad_perm:[3,3,3,3] row_mask:0xf bank_mask:0xf
	ds_read2_b32 v[244:245], v251 offset0:40 offset1:40
	s_waitcnt lgkmcnt(7)
	v_fmac_f32_dpp v102, -v230, v86 quad_perm:[0,0,0,0] row_mask:0xf bank_mask:0xf
	v_fmac_f32_dpp v110, -v230, v88 quad_perm:[1,1,1,1] row_mask:0xf bank_mask:0xf
	v_fmac_f32_dpp v111, -v230, v90 quad_perm:[2,2,2,2] row_mask:0xf bank_mask:0xf
	v_fmac_f32_dpp v112, -v230, v92 quad_perm:[3,3,3,3] row_mask:0xf bank_mask:0xf
	v_fmac_f32_dpp v102, -v231, v94 quad_perm:[0,0,0,0] row_mask:0xf bank_mask:0xf
	v_fmac_f32_dpp v110, -v231, v96 quad_perm:[1,1,1,1] row_mask:0xf bank_mask:0xf
	v_fmac_f32_dpp v111, -v231, v98 quad_perm:[2,2,2,2] row_mask:0xf bank_mask:0xf
	v_fmac_f32_dpp v112, -v231, v100 quad_perm:[3,3,3,3] row_mask:0xf bank_mask:0xf
	v_add_u32_e32 v251, 0x110, v251
	ds_read2_b32 v[230:231], v251 offset0:0 offset1:4
	s_waitcnt lgkmcnt(7)
	v_fmac_f32_dpp v102, -v232, v103 quad_perm:[0,0,0,0] row_mask:0xf bank_mask:0xf
	v_fmac_f32_dpp v110, -v232, v105 quad_perm:[1,1,1,1] row_mask:0xf bank_mask:0xf
	v_fmac_f32_dpp v111, -v232, v104 quad_perm:[2,2,2,2] row_mask:0xf bank_mask:0xf
	ds_read2_b32 v[232:233], v251 offset0:8 offset1:12
	v_add_f32_e32 v102, v102, v110
	v_add_f32_e32 v111, v111, v112
	v_add_f32_e32 v102, v102, v111
	s_waitcnt lgkmcnt(7)
	v_fmac_f32_dpp v101, -v234, v4 quad_perm:[0,0,0,0] row_mask:0xf bank_mask:0xf
	v_mul_f32_dpp v110, -v234, v2 quad_perm:[1,1,1,1] row_mask:0xf bank_mask:0xf
	v_mul_f32_dpp v111, -v234, v3 quad_perm:[2,2,2,2] row_mask:0xf bank_mask:0xf
	v_mul_f32_dpp v112, -v234, v5 quad_perm:[3,3,3,3] row_mask:0xf bank_mask:0xf
	v_fmac_f32_dpp v101, -v235, v6 quad_perm:[0,0,0,0] row_mask:0xf bank_mask:0xf
	v_fmac_f32_dpp v110, -v235, v7 quad_perm:[1,1,1,1] row_mask:0xf bank_mask:0xf
	v_fmac_f32_dpp v111, -v235, v8 quad_perm:[2,2,2,2] row_mask:0xf bank_mask:0xf
	v_fmac_f32_dpp v112, -v235, v9 quad_perm:[3,3,3,3] row_mask:0xf bank_mask:0xf
	ds_read2_b32 v[234:235], v251 offset0:16 offset1:20
	s_waitcnt lgkmcnt(7)
	v_fmac_f32_dpp v101, -v236, v10 quad_perm:[0,0,0,0] row_mask:0xf bank_mask:0xf
	v_fmac_f32_dpp v110, -v236, v12 quad_perm:[1,1,1,1] row_mask:0xf bank_mask:0xf
	v_fmac_f32_dpp v111, -v236, v13 quad_perm:[2,2,2,2] row_mask:0xf bank_mask:0xf
	v_fmac_f32_dpp v112, -v236, v14 quad_perm:[3,3,3,3] row_mask:0xf bank_mask:0xf
	v_fmac_f32_dpp v101, -v237, v15 quad_perm:[0,0,0,0] row_mask:0xf bank_mask:0xf
	v_fmac_f32_dpp v110, -v237, v17 quad_perm:[1,1,1,1] row_mask:0xf bank_mask:0xf
	v_fmac_f32_dpp v111, -v237, v18 quad_perm:[2,2,2,2] row_mask:0xf bank_mask:0xf
	v_fmac_f32_dpp v112, -v237, v19 quad_perm:[3,3,3,3] row_mask:0xf bank_mask:0xf
	ds_read2_b32 v[236:237], v251 offset0:24 offset1:28
	s_waitcnt lgkmcnt(7)
	v_fmac_f32_dpp v101, -v238, v21 quad_perm:[0,0,0,0] row_mask:0xf bank_mask:0xf
	v_fmac_f32_dpp v110, -v238, v22 quad_perm:[1,1,1,1] row_mask:0xf bank_mask:0xf
	v_fmac_f32_dpp v111, -v238, v23 quad_perm:[2,2,2,2] row_mask:0xf bank_mask:0xf
	v_fmac_f32_dpp v112, -v238, v25 quad_perm:[3,3,3,3] row_mask:0xf bank_mask:0xf
	v_fmac_f32_dpp v101, -v239, v26 quad_perm:[0,0,0,0] row_mask:0xf bank_mask:0xf
	v_fmac_f32_dpp v110, -v239, v28 quad_perm:[1,1,1,1] row_mask:0xf bank_mask:0xf
	v_fmac_f32_dpp v111, -v239, v29 quad_perm:[2,2,2,2] row_mask:0xf bank_mask:0xf
	v_fmac_f32_dpp v112, -v239, v31 quad_perm:[3,3,3,3] row_mask:0xf bank_mask:0xf
	ds_read2_b32 v[238:239], v251 offset0:32 offset1:36
	s_waitcnt lgkmcnt(7)
	v_fmac_f32_dpp v101, -v240, v32 quad_perm:[0,0,0,0] row_mask:0xf bank_mask:0xf
	v_fmac_f32_dpp v110, -v240, v43 quad_perm:[1,1,1,1] row_mask:0xf bank_mask:0xf
	v_fmac_f32_dpp v111, -v240, v47 quad_perm:[2,2,2,2] row_mask:0xf bank_mask:0xf
	v_fmac_f32_dpp v112, -v240, v50 quad_perm:[3,3,3,3] row_mask:0xf bank_mask:0xf
	v_fmac_f32_dpp v101, -v241, v52 quad_perm:[0,0,0,0] row_mask:0xf bank_mask:0xf
	v_fmac_f32_dpp v110, -v241, v81 quad_perm:[1,1,1,1] row_mask:0xf bank_mask:0xf
	v_fmac_f32_dpp v111, -v241, v82 quad_perm:[2,2,2,2] row_mask:0xf bank_mask:0xf
	v_fmac_f32_dpp v112, -v241, v84 quad_perm:[3,3,3,3] row_mask:0xf bank_mask:0xf
	ds_read2_b32 v[240:241], v251 offset0:40 offset1:44
	s_waitcnt lgkmcnt(7)
; DI void phase_gdn_c1(const Ctx& c) {
;     ...
; #pragma unroll
;       for (int i = 1; i < 64; ++i) {
;         float s0 = sol[i], s1 = 0.f, s2 = 0.f, s3 = 0.f;
; #pragma unroll
;         for (int m = 0; m < i; ++m) {
;           const float t_ = Am[i * 68 + m] * sol[m];
;           if ((m & 3) == 0) s0 -= t_; else if ((m & 3) == 1) s1 -= t_; else if ((m & 3) == 2) s2 -= t_; else s3 -= t_;
;         }
;         sol[i] = (s0 + s1) + (s2 + s3);
;       }
	v_fmac_f32_dpp v101, -v242, v86 quad_perm:[0,0,0,0] row_mask:0xf bank_mask:0xf
	v_fmac_f32_dpp v110, -v242, v88 quad_perm:[1,1,1,1] row_mask:0xf bank_mask:0xf
	v_fmac_f32_dpp v111, -v242, v90 quad_perm:[2,2,2,2] row_mask:0xf bank_mask:0xf
	v_fmac_f32_dpp v112, -v242, v92 quad_perm:[3,3,3,3] row_mask:0xf bank_mask:0xf
	v_fmac_f32_dpp v101, -v243, v94 quad_perm:[0,0,0,0] row_mask:0xf bank_mask:0xf
	v_fmac_f32_dpp v110, -v243, v96 quad_perm:[1,1,1,1] row_mask:0xf bank_mask:0xf
	v_fmac_f32_dpp v111, -v243, v98 quad_perm:[2,2,2,2] row_mask:0xf bank_mask:0xf
	v_fmac_f32_dpp v112, -v243, v100 quad_perm:[3,3,3,3] row_mask:0xf bank_mask:0xf
	v_add_u32_e32 v251, 0x110, v251
	ds_read2_b32 v[242:243], v251 offset0:0 offset1:4
	s_waitcnt lgkmcnt(7)
	v_fmac_f32_dpp v101, -v244, v103 quad_perm:[0,0,0,0] row_mask:0xf bank_mask:0xf
	v_fmac_f32_dpp v110, -v244, v105 quad_perm:[1,1,1,1] row_mask:0xf bank_mask:0xf
	v_fmac_f32_dpp v111, -v244, v104 quad_perm:[2,2,2,2] row_mask:0xf bank_mask:0xf
	v_fmac_f32_dpp v112, -v244, v102 quad_perm:[3,3,3,3] row_mask:0xf bank_mask:0xf
	ds_read2_b32 v[244:245], v251 offset0:8 offset1:12
	v_add_f32_e32 v101, v101, v110
	v_add_f32_e32 v111, v111, v112
	v_add_f32_e32 v101, v101, v111
	s_waitcnt lgkmcnt(7)
	v_fmac_f32_dpp v99, -v230, v4 quad_perm:[0,0,0,0] row_mask:0xf bank_mask:0xf
	v_mul_f32_dpp v110, -v230, v2 quad_perm:[1,1,1,1] row_mask:0xf bank_mask:0xf
	v_mul_f32_dpp v111, -v230, v3 quad_perm:[2,2,2,2] row_mask:0xf bank_mask:0xf
	v_mul_f32_dpp v112, -v230, v5 quad_perm:[3,3,3,3] row_mask:0xf bank_mask:0xf
	v_fmac_f32_dpp v99, -v231, v6 quad_perm:[0,0,0,0] row_mask:0xf bank_mask:0xf
	v_fmac_f32_dpp v110, -v231, v7 quad_perm:[1,1,1,1] row_mask:0xf bank_mask:0xf
	v_fmac_f32_dpp v111, -v231, v8 quad_perm:[2,2,2,2] row_mask:0xf bank_mask:0xf
	v_fmac_f32_dpp v112, -v231, v9 quad_perm:[3,3,3,3] row_mask:0xf bank_mask:0xf
	ds_read2_b32 v[230:231], v251 offset0:16 offset1:20
	s_waitcnt lgkmcnt(7)
	v_fmac_f32_dpp v99, -v232, v10 quad_perm:[0,0,0,0] row_mask:0xf bank_mask:0xf
	v_fmac_f32_dpp v110, -v232, v12 quad_perm:[1,1,1,1] row_mask:0xf bank_mask:0xf
	v_fmac_f32_dpp v111, -v232, v13 quad_perm:[2,2,2,2] row_mask:0xf bank_mask:0xf
	v_fmac_f32_dpp v112, -v232, v14 quad_perm:[3,3,3,3] row_mask:0xf bank_mask:0xf
	v_fmac_f32_dpp v99, -v233, v15 quad_perm:[0,0,0,0] row_mask:0xf bank_mask:0xf
	v_fmac_f32_dpp v110, -v233, v17 quad_perm:[1,1,1,1] row_mask:0xf bank_mask:0xf
	v_fmac_f32_dpp v111, -v233, v18 quad_perm:[2,2,2,2] row_mask:0xf bank_mask:0xf
	v_fmac_f32_dpp v112, -v233, v19 quad_perm:[3,3,3,3] row_mask:0xf bank_mask:0xf
	ds_read2_b32 v[232:233], v251 offset0:24 offset1:28
	s_waitcnt lgkmcnt(7)
	v_fmac_f32_dpp v99, -v234, v21 quad_perm:[0,0,0,0] row_mask:0xf bank_mask:0xf
	v_fmac_f32_dpp v110, -v234, v22 quad_perm:[1,1,1,1] row_mask:0xf bank_mask:0xf
	v_fmac_f32_dpp v111, -v234, v23 quad_perm:[2,2,2,2] row_mask:0xf bank_mask:0xf
	v_fmac_f32_dpp v112, -v234, v25 quad_perm:[3,3,3,3] row_mask:0xf bank_mask:0xf
	v_fmac_f32_dpp v99, -v235, v26 quad_perm:[0,0,0,0] row_mask:0xf bank_mask:0xf
	v_fmac_f32_dpp v110, -v235, v28 quad_perm:[1,1,1,1] row_mask:0xf bank_mask:0xf
	v_fmac_f32_dpp v111, -v235, v29 quad_perm:[2,2,2,2] row_mask:0xf bank_mask:0xf
	v_fmac_f32_dpp v112, -v235, v31 quad_perm:[3,3,3,3] row_mask:0xf bank_mask:0xf
	ds_read2_b32 v[234:235], v251 offset0:32 offset1:36
	s_waitcnt lgkmcnt(7)
	v_fmac_f32_dpp v99, -v236, v32 quad_perm:[0,0,0,0] row_mask:0xf bank_mask:0xf
	v_fmac_f32_dpp v110, -v236, v43 quad_perm:[1,1,1,1] row_mask:0xf bank_mask:0xf
	v_fmac_f32_dpp v111, -v236, v47 quad_perm:[2,2,2,2] row_mask:0xf bank_mask:0xf
	v_fmac_f32_dpp v112, -v236, v50 quad_perm:[3,3,3,3] row_mask:0xf bank_mask:0xf
	v_fmac_f32_dpp v99, -v237, v52 quad_perm:[0,0,0,0] row_mask:0xf bank_mask:0xf
	v_fmac_f32_dpp v110, -v237, v81 quad_perm:[1,1,1,1] row_mask:0xf bank_mask:0xf
	v_fmac_f32_dpp v111, -v237, v82 quad_perm:[2,2,2,2] row_mask:0xf bank_mask:0xf
	v_fmac_f32_dpp v112, -v237, v84 quad_perm:[3,3,3,3] row_mask:0xf bank_mask:0xf
	ds_read2_b32 v[236:237], v251 offset0:40 offset1:44
	s_waitcnt lgkmcnt(7)
	v_fmac_f32_dpp v99, -v238, v86 quad_perm:[0,0,0,0] row_mask:0xf bank_mask:0xf
	v_fmac_f32_dpp v110, -v238, v88 quad_perm:[1,1,1,1] row_mask:0xf bank_mask:0xf
	v_fmac_f32_dpp v111, -v238, v90 quad_perm:[2,2,2,2] row_mask:0xf bank_mask:0xf
	v_fmac_f32_dpp v112, -v238, v92 quad_perm:[3,3,3,3] row_mask:0xf bank_mask:0xf
	v_fmac_f32_dpp v99, -v239, v94 quad_perm:[0,0,0,0] row_mask:0xf bank_mask:0xf
	v_fmac_f32_dpp v110, -v239, v96 quad_perm:[1,1,1,1] row_mask:0xf bank_mask:0xf
	v_fmac_f32_dpp v111, -v239, v98 quad_perm:[2,2,2,2] row_mask:0xf bank_mask:0xf
	v_fmac_f32_dpp v112, -v239, v100 quad_perm:[3,3,3,3] row_mask:0xf bank_mask:0xf
	v_add_u32_e32 v251, 0x110, v251
	ds_read2_b32 v[238:239], v251 offset0:0 offset1:4
	s_waitcnt lgkmcnt(7)
	v_fmac_f32_dpp v99, -v240, v103 quad_perm:[0,0,0,0] row_mask:0xf bank_mask:0xf
	v_fmac_f32_dpp v110, -v240, v105 quad_perm:[1,1,1,1] row_mask:0xf bank_mask:0xf
	v_fmac_f32_dpp v111, -v240, v104 quad_perm:[2,2,2,2] row_mask:0xf bank_mask:0xf
	v_fmac_f32_dpp v112, -v240, v102 quad_perm:[3,3,3,3] row_mask:0xf bank_mask:0xf
	v_fmac_f32_dpp v99, -v241, v101 quad_perm:[0,0,0,0] row_mask:0xf bank_mask:0xf
	ds_read2_b32 v[240:241], v251 offset0:8 offset1:12
	v_add_f32_e32 v99, v99, v110
	v_add_f32_e32 v111, v111, v112
	v_add_f32_e32 v99, v99, v111
	s_waitcnt lgkmcnt(7)
; DI void phase_gdn_c1(const Ctx& c) {
;     ...
; #pragma unroll
;       for (int i = 1; i < 64; ++i) {
;         float s0 = sol[i], s1 = 0.f, s2 = 0.f, s3 = 0.f;
; #pragma unroll
;         for (int m = 0; m < i; ++m) {
;           const float t_ = Am[i * 68 + m] * sol[m];
;           if ((m & 3) == 0) s0 -= t_; else if ((m & 3) == 1) s1 -= t_; else if ((m & 3) == 2) s2 -= t_; else s3 -= t_;
;         }
;         sol[i] = (s0 + s1) + (s2 + s3);
;       }
	v_fmac_f32_dpp v97, -v242, v4 quad_perm:[0,0,0,0] row_mask:0xf bank_mask:0xf
	v_mul_f32_dpp v110, -v242, v2 quad_perm:[1,1,1,1] row_mask:0xf bank_mask:0xf
	v_mul_f32_dpp v111, -v242, v3 quad_perm:[2,2,2,2] row_mask:0xf bank_mask:0xf
	v_mul_f32_dpp v112, -v242, v5 quad_perm:[3,3,3,3] row_mask:0xf bank_mask:0xf
	v_fmac_f32_dpp v97, -v243, v6 quad_perm:[0,0,0,0] row_mask:0xf bank_mask:0xf
	v_fmac_f32_dpp v110, -v243, v7 quad_perm:[1,1,1,1] row_mask:0xf bank_mask:0xf
	v_fmac_f32_dpp v111, -v243, v8 quad_perm:[2,2,2,2] row_mask:0xf bank_mask:0xf
	v_fmac_f32_dpp v112, -v243, v9 quad_perm:[3,3,3,3] row_mask:0xf bank_mask:0xf
	ds_read2_b32 v[242:243], v251 offset0:16 offset1:20
	s_waitcnt lgkmcnt(7)
	v_fmac_f32_dpp v97, -v244, v10 quad_perm:[0,0,0,0] row_mask:0xf bank_mask:0xf
	v_fmac_f32_dpp v110, -v244, v12 quad_perm:[1,1,1,1] row_mask:0xf bank_mask:0xf
	v_fmac_f32_dpp v111, -v244, v13 quad_perm:[2,2,2,2] row_mask:0xf bank_mask:0xf
	v_fmac_f32_dpp v112, -v244, v14 quad_perm:[3,3,3,3] row_mask:0xf bank_mask:0xf
	v_fmac_f32_dpp v97, -v245, v15 quad_perm:[0,0,0,0] row_mask:0xf bank_mask:0xf
	v_fmac_f32_dpp v110, -v245, v17 quad_perm:[1,1,1,1] row_mask:0xf bank_mask:0xf
	v_fmac_f32_dpp v111, -v245, v18 quad_perm:[2,2,2,2] row_mask:0xf bank_mask:0xf
	v_fmac_f32_dpp v112, -v245, v19 quad_perm:[3,3,3,3] row_mask:0xf bank_mask:0xf
	ds_read2_b32 v[244:245], v251 offset0:24 offset1:28
	s_waitcnt lgkmcnt(7)
	v_fmac_f32_dpp v97, -v230, v21 quad_perm:[0,0,0,0] row_mask:0xf bank_mask:0xf
	v_fmac_f32_dpp v110, -v230, v22 quad_perm:[1,1,1,1] row_mask:0xf bank_mask:0xf
	v_fmac_f32_dpp v111, -v230, v23 quad_perm:[2,2,2,2] row_mask:0xf bank_mask:0xf
	v_fmac_f32_dpp v112, -v230, v25 quad_perm:[3,3,3,3] row_mask:0xf bank_mask:0xf
	v_fmac_f32_dpp v97, -v231, v26 quad_perm:[0,0,0,0] row_mask:0xf bank_mask:0xf
	v_fmac_f32_dpp v110, -v231, v28 quad_perm:[1,1,1,1] row_mask:0xf bank_mask:0xf
	v_fmac_f32_dpp v111, -v231, v29 quad_perm:[2,2,2,2] row_mask:0xf bank_mask:0xf
	v_fmac_f32_dpp v112, -v231, v31 quad_perm:[3,3,3,3] row_mask:0xf bank_mask:0xf
	ds_read2_b32 v[230:231], v251 offset0:32 offset1:36
	s_waitcnt lgkmcnt(7)
	v_fmac_f32_dpp v97, -v232, v32 quad_perm:[0,0,0,0] row_mask:0xf bank_mask:0xf
	v_fmac_f32_dpp v110, -v232, v43 quad_perm:[1,1,1,1] row_mask:0xf bank_mask:0xf
	v_fmac_f32_dpp v111, -v232, v47 quad_perm:[2,2,2,2] row_mask:0xf bank_mask:0xf
	v_fmac_f32_dpp v112, -v232, v50 quad_perm:[3,3,3,3] row_mask:0xf bank_mask:0xf
	v_fmac_f32_dpp v97, -v233, v52 quad_perm:[0,0,0,0] row_mask:0xf bank_mask:0xf
	v_fmac_f32_dpp v110, -v233, v81 quad_perm:[1,1,1,1] row_mask:0xf bank_mask:0xf
	v_fmac_f32_dpp v111, -v233, v82 quad_perm:[2,2,2,2] row_mask:0xf bank_mask:0xf
	v_fmac_f32_dpp v112, -v233, v84 quad_perm:[3,3,3,3] row_mask:0xf bank_mask:0xf
	ds_read2_b32 v[232:233], v251 offset0:40 offset1:44
	s_waitcnt lgkmcnt(7)
	v_fmac_f32_dpp v97, -v234, v86 quad_perm:[0,0,0,0] row_mask:0xf bank_mask:0xf
	v_fmac_f32_dpp v110, -v234, v88 quad_perm:[1,1,1,1] row_mask:0xf bank_mask:0xf
	v_fmac_f32_dpp v111, -v234, v90 quad_perm:[2,2,2,2] row_mask:0xf bank_mask:0xf
	v_fmac_f32_dpp v112, -v234, v92 quad_perm:[3,3,3,3] row_mask:0xf bank_mask:0xf
	v_fmac_f32_dpp v97, -v235, v94 quad_perm:[0,0,0,0] row_mask:0xf bank_mask:0xf
	v_fmac_f32_dpp v110, -v235, v96 quad_perm:[1,1,1,1] row_mask:0xf bank_mask:0xf
	v_fmac_f32_dpp v111, -v235, v98 quad_perm:[2,2,2,2] row_mask:0xf bank_mask:0xf
	v_fmac_f32_dpp v112, -v235, v100 quad_perm:[3,3,3,3] row_mask:0xf bank_mask:0xf
	v_add_u32_e32 v251, 0x110, v251
	ds_read2_b32 v[234:235], v251 offset0:0 offset1:4
	s_waitcnt lgkmcnt(7)
	v_fmac_f32_dpp v97, -v236, v103 quad_perm:[0,0,0,0] row_mask:0xf bank_mask:0xf
	v_fmac_f32_dpp v110, -v236, v105 quad_perm:[1,1,1,1] row_mask:0xf bank_mask:0xf
	v_fmac_f32_dpp v111, -v236, v104 quad_perm:[2,2,2,2] row_mask:0xf bank_mask:0xf
	v_fmac_f32_dpp v112, -v236, v102 quad_perm:[3,3,3,3] row_mask:0xf bank_mask:0xf
	v_fmac_f32_dpp v97, -v237, v101 quad_perm:[0,0,0,0] row_mask:0xf bank_mask:0xf
	v_fmac_f32_dpp v110, -v237, v99 quad_perm:[1,1,1,1] row_mask:0xf bank_mask:0xf
	ds_read2_b32 v[236:237], v251 offset0:8 offset1:12
	v_add_f32_e32 v97, v97, v110
	v_add_f32_e32 v111, v111, v112
	v_add_f32_e32 v97, v97, v111
	s_waitcnt lgkmcnt(7)
	v_fmac_f32_dpp v95, -v238, v4 quad_perm:[0,0,0,0] row_mask:0xf bank_mask:0xf
	v_mul_f32_dpp v110, -v238, v2 quad_perm:[1,1,1,1] row_mask:0xf bank_mask:0xf
	v_mul_f32_dpp v111, -v238, v3 quad_perm:[2,2,2,2] row_mask:0xf bank_mask:0xf
	v_mul_f32_dpp v112, -v238, v5 quad_perm:[3,3,3,3] row_mask:0xf bank_mask:0xf
	v_fmac_f32_dpp v95, -v239, v6 quad_perm:[0,0,0,0] row_mask:0xf bank_mask:0xf
	v_fmac_f32_dpp v110, -v239, v7 quad_perm:[1,1,1,1] row_mask:0xf bank_mask:0xf
	v_fmac_f32_dpp v111, -v239, v8 quad_perm:[2,2,2,2] row_mask:0xf bank_mask:0xf
	v_fmac_f32_dpp v112, -v239, v9 quad_perm:[3,3,3,3] row_mask:0xf bank_mask:0xf
	ds_read2_b32 v[238:239], v251 offset0:16 offset1:20
	s_waitcnt lgkmcnt(7)
	v_fmac_f32_dpp v95, -v240, v10 quad_perm:[0,0,0,0] row_mask:0xf bank_mask:0xf
	v_fmac_f32_dpp v110, -v240, v12 quad_perm:[1,1,1,1] row_mask:0xf bank_mask:0xf
	v_fmac_f32_dpp v111, -v240, v13 quad_perm:[2,2,2,2] row_mask:0xf bank_mask:0xf
	v_fmac_f32_dpp v112, -v240, v14 quad_perm:[3,3,3,3] row_mask:0xf bank_mask:0xf
	v_fmac_f32_dpp v95, -v241, v15 quad_perm:[0,0,0,0] row_mask:0xf bank_mask:0xf
	v_fmac_f32_dpp v110, -v241, v17 quad_perm:[1,1,1,1] row_mask:0xf bank_mask:0xf
	v_fmac_f32_dpp v111, -v241, v18 quad_perm:[2,2,2,2] row_mask:0xf bank_mask:0xf
	v_fmac_f32_dpp v112, -v241, v19 quad_perm:[3,3,3,3] row_mask:0xf bank_mask:0xf
	ds_read2_b32 v[240:241], v251 offset0:24 offset1:28
	s_waitcnt lgkmcnt(7)
; DI void phase_gdn_c1(const Ctx& c) {
;     ...
; #pragma unroll
;       for (int i = 1; i < 64; ++i) {
;         float s0 = sol[i], s1 = 0.f, s2 = 0.f, s3 = 0.f;
; #pragma unroll
;         for (int m = 0; m < i; ++m) {
;           const float t_ = Am[i * 68 + m] * sol[m];
;           if ((m & 3) == 0) s0 -= t_; else if ((m & 3) == 1) s1 -= t_; else if ((m & 3) == 2) s2 -= t_; else s3 -= t_;
;         }
;         sol[i] = (s0 + s1) + (s2 + s3);
;       }
	v_fmac_f32_dpp v95, -v242, v21 quad_perm:[0,0,0,0] row_mask:0xf bank_mask:0xf
	v_fmac_f32_dpp v110, -v242, v22 quad_perm:[1,1,1,1] row_mask:0xf bank_mask:0xf
	v_fmac_f32_dpp v111, -v242, v23 quad_perm:[2,2,2,2] row_mask:0xf bank_mask:0xf
	v_fmac_f32_dpp v112, -v242, v25 quad_perm:[3,3,3,3] row_mask:0xf bank_mask:0xf
	v_fmac_f32_dpp v95, -v243, v26 quad_perm:[0,0,0,0] row_mask:0xf bank_mask:0xf
	v_fmac_f32_dpp v110, -v243, v28 quad_perm:[1,1,1,1] row_mask:0xf bank_mask:0xf
	v_fmac_f32_dpp v111, -v243, v29 quad_perm:[2,2,2,2] row_mask:0xf bank_mask:0xf
	v_fmac_f32_dpp v112, -v243, v31 quad_perm:[3,3,3,3] row_mask:0xf bank_mask:0xf
	ds_read2_b32 v[242:243], v251 offset0:32 offset1:36
	s_waitcnt lgkmcnt(7)
	v_fmac_f32_dpp v95, -v244, v32 quad_perm:[0,0,0,0] row_mask:0xf bank_mask:0xf
	v_fmac_f32_dpp v110, -v244, v43 quad_perm:[1,1,1,1] row_mask:0xf bank_mask:0xf
	v_fmac_f32_dpp v111, -v244, v47 quad_perm:[2,2,2,2] row_mask:0xf bank_mask:0xf
	v_fmac_f32_dpp v112, -v244, v50 quad_perm:[3,3,3,3] row_mask:0xf bank_mask:0xf
	v_fmac_f32_dpp v95, -v245, v52 quad_perm:[0,0,0,0] row_mask:0xf bank_mask:0xf
	v_fmac_f32_dpp v110, -v245, v81 quad_perm:[1,1,1,1] row_mask:0xf bank_mask:0xf
	v_fmac_f32_dpp v111, -v245, v82 quad_perm:[2,2,2,2] row_mask:0xf bank_mask:0xf
	v_fmac_f32_dpp v112, -v245, v84 quad_perm:[3,3,3,3] row_mask:0xf bank_mask:0xf
	ds_read2_b32 v[244:245], v251 offset0:40 offset1:44
	s_waitcnt lgkmcnt(7)
	v_fmac_f32_dpp v95, -v230, v86 quad_perm:[0,0,0,0] row_mask:0xf bank_mask:0xf
	v_fmac_f32_dpp v110, -v230, v88 quad_perm:[1,1,1,1] row_mask:0xf bank_mask:0xf
	v_fmac_f32_dpp v111, -v230, v90 quad_perm:[2,2,2,2] row_mask:0xf bank_mask:0xf
	v_fmac_f32_dpp v112, -v230, v92 quad_perm:[3,3,3,3] row_mask:0xf bank_mask:0xf
	v_fmac_f32_dpp v95, -v231, v94 quad_perm:[0,0,0,0] row_mask:0xf bank_mask:0xf
	v_fmac_f32_dpp v110, -v231, v96 quad_perm:[1,1,1,1] row_mask:0xf bank_mask:0xf
	v_fmac_f32_dpp v111, -v231, v98 quad_perm:[2,2,2,2] row_mask:0xf bank_mask:0xf
	v_fmac_f32_dpp v112, -v231, v100 quad_perm:[3,3,3,3] row_mask:0xf bank_mask:0xf
	v_add_u32_e32 v251, 0x110, v251
	ds_read2_b32 v[230:231], v251 offset0:0 offset1:4
	s_waitcnt lgkmcnt(7)
	v_fmac_f32_dpp v95, -v232, v103 quad_perm:[0,0,0,0] row_mask:0xf bank_mask:0xf
	v_fmac_f32_dpp v110, -v232, v105 quad_perm:[1,1,1,1] row_mask:0xf bank_mask:0xf
	v_fmac_f32_dpp v111, -v232, v104 quad_perm:[2,2,2,2] row_mask:0xf bank_mask:0xf
	v_fmac_f32_dpp v112, -v232, v102 quad_perm:[3,3,3,3] row_mask:0xf bank_mask:0xf
	v_fmac_f32_dpp v95, -v233, v101 quad_perm:[0,0,0,0] row_mask:0xf bank_mask:0xf
	v_fmac_f32_dpp v110, -v233, v99 quad_perm:[1,1,1,1] row_mask:0xf bank_mask:0xf
	v_fmac_f32_dpp v111, -v233, v97 quad_perm:[2,2,2,2] row_mask:0xf bank_mask:0xf
	ds_read2_b32 v[232:233], v251 offset0:8 offset1:12
	v_add_f32_e32 v95, v95, v110
	v_add_f32_e32 v111, v111, v112
	v_add_f32_e32 v95, v95, v111
	s_waitcnt lgkmcnt(7)
	v_fmac_f32_dpp v93, -v234, v4 quad_perm:[0,0,0,0] row_mask:0xf bank_mask:0xf
	v_mul_f32_dpp v110, -v234, v2 quad_perm:[1,1,1,1] row_mask:0xf bank_mask:0xf
	v_mul_f32_dpp v111, -v234, v3 quad_perm:[2,2,2,2] row_mask:0xf bank_mask:0xf
	v_mul_f32_dpp v112, -v234, v5 quad_perm:[3,3,3,3] row_mask:0xf bank_mask:0xf
	v_fmac_f32_dpp v93, -v235, v6 quad_perm:[0,0,0,0] row_mask:0xf bank_mask:0xf
	v_fmac_f32_dpp v110, -v235, v7 quad_perm:[1,1,1,1] row_mask:0xf bank_mask:0xf
	v_fmac_f32_dpp v111, -v235, v8 quad_perm:[2,2,2,2] row_mask:0xf bank_mask:0xf
	v_fmac_f32_dpp v112, -v235, v9 quad_perm:[3,3,3,3] row_mask:0xf bank_mask:0xf
	ds_read2_b32 v[234:235], v251 offset0:16 offset1:20
	s_waitcnt lgkmcnt(7)
	v_fmac_f32_dpp v93, -v236, v10 quad_perm:[0,0,0,0] row_mask:0xf bank_mask:0xf
	v_fmac_f32_dpp v110, -v236, v12 quad_perm:[1,1,1,1] row_mask:0xf bank_mask:0xf
	v_fmac_f32_dpp v111, -v236, v13 quad_perm:[2,2,2,2] row_mask:0xf bank_mask:0xf
	v_fmac_f32_dpp v112, -v236, v14 quad_perm:[3,3,3,3] row_mask:0xf bank_mask:0xf
	v_fmac_f32_dpp v93, -v237, v15 quad_perm:[0,0,0,0] row_mask:0xf bank_mask:0xf
	v_fmac_f32_dpp v110, -v237, v17 quad_perm:[1,1,1,1] row_mask:0xf bank_mask:0xf
	v_fmac_f32_dpp v111, -v237, v18 quad_perm:[2,2,2,2] row_mask:0xf bank_mask:0xf
	v_fmac_f32_dpp v112, -v237, v19 quad_perm:[3,3,3,3] row_mask:0xf bank_mask:0xf
	ds_read2_b32 v[236:237], v251 offset0:24 offset1:28
	s_waitcnt lgkmcnt(7)
	v_fmac_f32_dpp v93, -v238, v21 quad_perm:[0,0,0,0] row_mask:0xf bank_mask:0xf
	v_fmac_f32_dpp v110, -v238, v22 quad_perm:[1,1,1,1] row_mask:0xf bank_mask:0xf
	v_fmac_f32_dpp v111, -v238, v23 quad_perm:[2,2,2,2] row_mask:0xf bank_mask:0xf
	v_fmac_f32_dpp v112, -v238, v25 quad_perm:[3,3,3,3] row_mask:0xf bank_mask:0xf
	v_fmac_f32_dpp v93, -v239, v26 quad_perm:[0,0,0,0] row_mask:0xf bank_mask:0xf
	v_fmac_f32_dpp v110, -v239, v28 quad_perm:[1,1,1,1] row_mask:0xf bank_mask:0xf
	v_fmac_f32_dpp v111, -v239, v29 quad_perm:[2,2,2,2] row_mask:0xf bank_mask:0xf
	v_fmac_f32_dpp v112, -v239, v31 quad_perm:[3,3,3,3] row_mask:0xf bank_mask:0xf
	ds_read2_b32 v[238:239], v251 offset0:32 offset1:36
	s_waitcnt lgkmcnt(7)
	v_fmac_f32_dpp v93, -v240, v32 quad_perm:[0,0,0,0] row_mask:0xf bank_mask:0xf
	v_fmac_f32_dpp v110, -v240, v43 quad_perm:[1,1,1,1] row_mask:0xf bank_mask:0xf
	v_fmac_f32_dpp v111, -v240, v47 quad_perm:[2,2,2,2] row_mask:0xf bank_mask:0xf
	v_fmac_f32_dpp v112, -v240, v50 quad_perm:[3,3,3,3] row_mask:0xf bank_mask:0xf
	v_fmac_f32_dpp v93, -v241, v52 quad_perm:[0,0,0,0] row_mask:0xf bank_mask:0xf
	v_fmac_f32_dpp v110, -v241, v81 quad_perm:[1,1,1,1] row_mask:0xf bank_mask:0xf
	v_fmac_f32_dpp v111, -v241, v82 quad_perm:[2,2,2,2] row_mask:0xf bank_mask:0xf
	v_fmac_f32_dpp v112, -v241, v84 quad_perm:[3,3,3,3] row_mask:0xf bank_mask:0xf
	ds_read2_b32 v[240:241], v251 offset0:40 offset1:44
	s_waitcnt lgkmcnt(7)
; DI void phase_gdn_c1(const Ctx& c) {
;     ...
; #pragma unroll
;       for (int i = 1; i < 64; ++i) {
;         float s0 = sol[i], s1 = 0.f, s2 = 0.f, s3 = 0.f;
; #pragma unroll
;         for (int m = 0; m < i; ++m) {
;           const float t_ = Am[i * 68 + m] * sol[m];
;           if ((m & 3) == 0) s0 -= t_; else if ((m & 3) == 1) s1 -= t_; else if ((m & 3) == 2) s2 -= t_; else s3 -= t_;
;         }
;         sol[i] = (s0 + s1) + (s2 + s3);
;       }
	v_fmac_f32_dpp v93, -v242, v86 quad_perm:[0,0,0,0] row_mask:0xf bank_mask:0xf
	v_fmac_f32_dpp v110, -v242, v88 quad_perm:[1,1,1,1] row_mask:0xf bank_mask:0xf
	v_fmac_f32_dpp v111, -v242, v90 quad_perm:[2,2,2,2] row_mask:0xf bank_mask:0xf
	v_fmac_f32_dpp v112, -v242, v92 quad_perm:[3,3,3,3] row_mask:0xf bank_mask:0xf
	v_fmac_f32_dpp v93, -v243, v94 quad_perm:[0,0,0,0] row_mask:0xf bank_mask:0xf
	v_fmac_f32_dpp v110, -v243, v96 quad_perm:[1,1,1,1] row_mask:0xf bank_mask:0xf
	v_fmac_f32_dpp v111, -v243, v98 quad_perm:[2,2,2,2] row_mask:0xf bank_mask:0xf
	v_fmac_f32_dpp v112, -v243, v100 quad_perm:[3,3,3,3] row_mask:0xf bank_mask:0xf
	ds_read2_b32 v[242:243], v251 offset0:48 offset1:48
	s_waitcnt lgkmcnt(7)
	v_fmac_f32_dpp v93, -v244, v103 quad_perm:[0,0,0,0] row_mask:0xf bank_mask:0xf
	v_fmac_f32_dpp v110, -v244, v105 quad_perm:[1,1,1,1] row_mask:0xf bank_mask:0xf
	v_fmac_f32_dpp v111, -v244, v104 quad_perm:[2,2,2,2] row_mask:0xf bank_mask:0xf
	v_fmac_f32_dpp v112, -v244, v102 quad_perm:[3,3,3,3] row_mask:0xf bank_mask:0xf
	v_fmac_f32_dpp v93, -v245, v101 quad_perm:[0,0,0,0] row_mask:0xf bank_mask:0xf
	v_fmac_f32_dpp v110, -v245, v99 quad_perm:[1,1,1,1] row_mask:0xf bank_mask:0xf
	v_fmac_f32_dpp v111, -v245, v97 quad_perm:[2,2,2,2] row_mask:0xf bank_mask:0xf
	v_fmac_f32_dpp v112, -v245, v95 quad_perm:[3,3,3,3] row_mask:0xf bank_mask:0xf
	v_add_u32_e32 v251, 0x110, v251
	ds_read2_b32 v[244:245], v251 offset0:0 offset1:4
	v_add_f32_e32 v93, v93, v110
	v_add_f32_e32 v111, v111, v112
	v_add_f32_e32 v93, v93, v111
	s_waitcnt lgkmcnt(7)
	v_fmac_f32_dpp v91, -v230, v4 quad_perm:[0,0,0,0] row_mask:0xf bank_mask:0xf
	v_mul_f32_dpp v110, -v230, v2 quad_perm:[1,1,1,1] row_mask:0xf bank_mask:0xf
	v_mul_f32_dpp v111, -v230, v3 quad_perm:[2,2,2,2] row_mask:0xf bank_mask:0xf
	v_mul_f32_dpp v112, -v230, v5 quad_perm:[3,3,3,3] row_mask:0xf bank_mask:0xf
	v_fmac_f32_dpp v91, -v231, v6 quad_perm:[0,0,0,0] row_mask:0xf bank_mask:0xf
	v_fmac_f32_dpp v110, -v231, v7 quad_perm:[1,1,1,1] row_mask:0xf bank_mask:0xf
	v_fmac_f32_dpp v111, -v231, v8 quad_perm:[2,2,2,2] row_mask:0xf bank_mask:0xf
	v_fmac_f32_dpp v112, -v231, v9 quad_perm:[3,3,3,3] row_mask:0xf bank_mask:0xf
	ds_read2_b32 v[230:231], v251 offset0:8 offset1:12
	s_waitcnt lgkmcnt(7)
	v_fmac_f32_dpp v91, -v232, v10 quad_perm:[0,0,0,0] row_mask:0xf bank_mask:0xf
	v_fmac_f32_dpp v110, -v232, v12 quad_perm:[1,1,1,1] row_mask:0xf bank_mask:0xf
	v_fmac_f32_dpp v111, -v232, v13 quad_perm:[2,2,2,2] row_mask:0xf bank_mask:0xf
	v_fmac_f32_dpp v112, -v232, v14 quad_perm:[3,3,3,3] row_mask:0xf bank_mask:0xf
	v_fmac_f32_dpp v91, -v233, v15 quad_perm:[0,0,0,0] row_mask:0xf bank_mask:0xf
	v_fmac_f32_dpp v110, -v233, v17 quad_perm:[1,1,1,1] row_mask:0xf bank_mask:0xf
	v_fmac_f32_dpp v111, -v233, v18 quad_perm:[2,2,2,2] row_mask:0xf bank_mask:0xf
	v_fmac_f32_dpp v112, -v233, v19 quad_perm:[3,3,3,3] row_mask:0xf bank_mask:0xf
	ds_read2_b32 v[232:233], v251 offset0:16 offset1:20
	s_waitcnt lgkmcnt(7)
	v_fmac_f32_dpp v91, -v234, v21 quad_perm:[0,0,0,0] row_mask:0xf bank_mask:0xf
	v_fmac_f32_dpp v110, -v234, v22 quad_perm:[1,1,1,1] row_mask:0xf bank_mask:0xf
	v_fmac_f32_dpp v111, -v234, v23 quad_perm:[2,2,2,2] row_mask:0xf bank_mask:0xf
	v_fmac_f32_dpp v112, -v234, v25 quad_perm:[3,3,3,3] row_mask:0xf bank_mask:0xf
	v_fmac_f32_dpp v91, -v235, v26 quad_perm:[0,0,0,0] row_mask:0xf bank_mask:0xf
	v_fmac_f32_dpp v110, -v235, v28 quad_perm:[1,1,1,1] row_mask:0xf bank_mask:0xf
	v_fmac_f32_dpp v111, -v235, v29 quad_perm:[2,2,2,2] row_mask:0xf bank_mask:0xf
	v_fmac_f32_dpp v112, -v235, v31 quad_perm:[3,3,3,3] row_mask:0xf bank_mask:0xf
	ds_read2_b32 v[234:235], v251 offset0:24 offset1:28
	s_waitcnt lgkmcnt(7)
	v_fmac_f32_dpp v91, -v236, v32 quad_perm:[0,0,0,0] row_mask:0xf bank_mask:0xf
	v_fmac_f32_dpp v110, -v236, v43 quad_perm:[1,1,1,1] row_mask:0xf bank_mask:0xf
	v_fmac_f32_dpp v111, -v236, v47 quad_perm:[2,2,2,2] row_mask:0xf bank_mask:0xf
	v_fmac_f32_dpp v112, -v236, v50 quad_perm:[3,3,3,3] row_mask:0xf bank_mask:0xf
	v_fmac_f32_dpp v91, -v237, v52 quad_perm:[0,0,0,0] row_mask:0xf bank_mask:0xf
	v_fmac_f32_dpp v110, -v237, v81 quad_perm:[1,1,1,1] row_mask:0xf bank_mask:0xf
	v_fmac_f32_dpp v111, -v237, v82 quad_perm:[2,2,2,2] row_mask:0xf bank_mask:0xf
	v_fmac_f32_dpp v112, -v237, v84 quad_perm:[3,3,3,3] row_mask:0xf bank_mask:0xf
	ds_read2_b32 v[236:237], v251 offset0:32 offset1:36
	s_waitcnt lgkmcnt(7)
	v_fmac_f32_dpp v91, -v238, v86 quad_perm:[0,0,0,0] row_mask:0xf bank_mask:0xf
	v_fmac_f32_dpp v110, -v238, v88 quad_perm:[1,1,1,1] row_mask:0xf bank_mask:0xf
	v_fmac_f32_dpp v111, -v238, v90 quad_perm:[2,2,2,2] row_mask:0xf bank_mask:0xf
	v_fmac_f32_dpp v112, -v238, v92 quad_perm:[3,3,3,3] row_mask:0xf bank_mask:0xf
	v_fmac_f32_dpp v91, -v239, v94 quad_perm:[0,0,0,0] row_mask:0xf bank_mask:0xf
	v_fmac_f32_dpp v110, -v239, v96 quad_perm:[1,1,1,1] row_mask:0xf bank_mask:0xf
	v_fmac_f32_dpp v111, -v239, v98 quad_perm:[2,2,2,2] row_mask:0xf bank_mask:0xf
	v_fmac_f32_dpp v112, -v239, v100 quad_perm:[3,3,3,3] row_mask:0xf bank_mask:0xf
	ds_read2_b32 v[238:239], v251 offset0:40 offset1:44
	s_waitcnt lgkmcnt(7)
	v_fmac_f32_dpp v91, -v240, v103 quad_perm:[0,0,0,0] row_mask:0xf bank_mask:0xf
	v_fmac_f32_dpp v110, -v240, v105 quad_perm:[1,1,1,1] row_mask:0xf bank_mask:0xf
	v_fmac_f32_dpp v111, -v240, v104 quad_perm:[2,2,2,2] row_mask:0xf bank_mask:0xf
	v_fmac_f32_dpp v112, -v240, v102 quad_perm:[3,3,3,3] row_mask:0xf bank_mask:0xf
	v_fmac_f32_dpp v91, -v241, v101 quad_perm:[0,0,0,0] row_mask:0xf bank_mask:0xf
	v_fmac_f32_dpp v110, -v241, v99 quad_perm:[1,1,1,1] row_mask:0xf bank_mask:0xf
	v_fmac_f32_dpp v111, -v241, v97 quad_perm:[2,2,2,2] row_mask:0xf bank_mask:0xf
	v_fmac_f32_dpp v112, -v241, v95 quad_perm:[3,3,3,3] row_mask:0xf bank_mask:0xf
	ds_read2_b32 v[240:241], v251 offset0:48 offset1:48
	s_waitcnt lgkmcnt(7)
; DI void phase_gdn_c1(const Ctx& c) {
;     ...
; #pragma unroll
;       for (int i = 1; i < 64; ++i) {
;         float s0 = sol[i], s1 = 0.f, s2 = 0.f, s3 = 0.f;
; #pragma unroll
;         for (int m = 0; m < i; ++m) {
;           const float t_ = Am[i * 68 + m] * sol[m];
;           if ((m & 3) == 0) s0 -= t_; else if ((m & 3) == 1) s1 -= t_; else if ((m & 3) == 2) s2 -= t_; else s3 -= t_;
;         }
;         sol[i] = (s0 + s1) + (s2 + s3);
;       }
	v_fmac_f32_dpp v91, -v242, v93 quad_perm:[0,0,0,0] row_mask:0xf bank_mask:0xf
	v_add_u32_e32 v251, 0x110, v251
	ds_read2_b32 v[242:243], v251 offset0:0 offset1:4
	v_add_f32_e32 v91, v91, v110
	v_add_f32_e32 v111, v111, v112
	v_add_f32_e32 v91, v91, v111
	s_waitcnt lgkmcnt(7)
	v_fmac_f32_dpp v89, -v244, v4 quad_perm:[0,0,0,0] row_mask:0xf bank_mask:0xf
	v_mul_f32_dpp v110, -v244, v2 quad_perm:[1,1,1,1] row_mask:0xf bank_mask:0xf
	v_mul_f32_dpp v111, -v244, v3 quad_perm:[2,2,2,2] row_mask:0xf bank_mask:0xf
	v_mul_f32_dpp v112, -v244, v5 quad_perm:[3,3,3,3] row_mask:0xf bank_mask:0xf
	v_fmac_f32_dpp v89, -v245, v6 quad_perm:[0,0,0,0] row_mask:0xf bank_mask:0xf
	v_fmac_f32_dpp v110, -v245, v7 quad_perm:[1,1,1,1] row_mask:0xf bank_mask:0xf
	v_fmac_f32_dpp v111, -v245, v8 quad_perm:[2,2,2,2] row_mask:0xf bank_mask:0xf
	v_fmac_f32_dpp v112, -v245, v9 quad_perm:[3,3,3,3] row_mask:0xf bank_mask:0xf
	ds_read2_b32 v[244:245], v251 offset0:8 offset1:12
	s_waitcnt lgkmcnt(7)
	v_fmac_f32_dpp v89, -v230, v10 quad_perm:[0,0,0,0] row_mask:0xf bank_mask:0xf
	v_fmac_f32_dpp v110, -v230, v12 quad_perm:[1,1,1,1] row_mask:0xf bank_mask:0xf
	v_fmac_f32_dpp v111, -v230, v13 quad_perm:[2,2,2,2] row_mask:0xf bank_mask:0xf
	v_fmac_f32_dpp v112, -v230, v14 quad_perm:[3,3,3,3] row_mask:0xf bank_mask:0xf
	v_fmac_f32_dpp v89, -v231, v15 quad_perm:[0,0,0,0] row_mask:0xf bank_mask:0xf
	v_fmac_f32_dpp v110, -v231, v17 quad_perm:[1,1,1,1] row_mask:0xf bank_mask:0xf
	v_fmac_f32_dpp v111, -v231, v18 quad_perm:[2,2,2,2] row_mask:0xf bank_mask:0xf
	v_fmac_f32_dpp v112, -v231, v19 quad_perm:[3,3,3,3] row_mask:0xf bank_mask:0xf
	ds_read2_b32 v[230:231], v251 offset0:16 offset1:20
	s_waitcnt lgkmcnt(7)
	v_fmac_f32_dpp v89, -v232, v21 quad_perm:[0,0,0,0] row_mask:0xf bank_mask:0xf
	v_fmac_f32_dpp v110, -v232, v22 quad_perm:[1,1,1,1] row_mask:0xf bank_mask:0xf
	v_fmac_f32_dpp v111, -v232, v23 quad_perm:[2,2,2,2] row_mask:0xf bank_mask:0xf
	v_fmac_f32_dpp v112, -v232, v25 quad_perm:[3,3,3,3] row_mask:0xf bank_mask:0xf
	v_fmac_f32_dpp v89, -v233, v26 quad_perm:[0,0,0,0] row_mask:0xf bank_mask:0xf
	v_fmac_f32_dpp v110, -v233, v28 quad_perm:[1,1,1,1] row_mask:0xf bank_mask:0xf
	v_fmac_f32_dpp v111, -v233, v29 quad_perm:[2,2,2,2] row_mask:0xf bank_mask:0xf
	v_fmac_f32_dpp v112, -v233, v31 quad_perm:[3,3,3,3] row_mask:0xf bank_mask:0xf
	ds_read2_b32 v[232:233], v251 offset0:24 offset1:28
	s_waitcnt lgkmcnt(7)
	v_fmac_f32_dpp v89, -v234, v32 quad_perm:[0,0,0,0] row_mask:0xf bank_mask:0xf
	v_fmac_f32_dpp v110, -v234, v43 quad_perm:[1,1,1,1] row_mask:0xf bank_mask:0xf
	v_fmac_f32_dpp v111, -v234, v47 quad_perm:[2,2,2,2] row_mask:0xf bank_mask:0xf
	v_fmac_f32_dpp v112, -v234, v50 quad_perm:[3,3,3,3] row_mask:0xf bank_mask:0xf
	v_fmac_f32_dpp v89, -v235, v52 quad_perm:[0,0,0,0] row_mask:0xf bank_mask:0xf
	v_fmac_f32_dpp v110, -v235, v81 quad_perm:[1,1,1,1] row_mask:0xf bank_mask:0xf
	v_fmac_f32_dpp v111, -v235, v82 quad_perm:[2,2,2,2] row_mask:0xf bank_mask:0xf
	v_fmac_f32_dpp v112, -v235, v84 quad_perm:[3,3,3,3] row_mask:0xf bank_mask:0xf
	ds_read2_b32 v[234:235], v251 offset0:32 offset1:36
	s_waitcnt lgkmcnt(7)
	v_fmac_f32_dpp v89, -v236, v86 quad_perm:[0,0,0,0] row_mask:0xf bank_mask:0xf
	v_fmac_f32_dpp v110, -v236, v88 quad_perm:[1,1,1,1] row_mask:0xf bank_mask:0xf
	v_fmac_f32_dpp v111, -v236, v90 quad_perm:[2,2,2,2] row_mask:0xf bank_mask:0xf
	v_fmac_f32_dpp v112, -v236, v92 quad_perm:[3,3,3,3] row_mask:0xf bank_mask:0xf
	v_fmac_f32_dpp v89, -v237, v94 quad_perm:[0,0,0,0] row_mask:0xf bank_mask:0xf
	v_fmac_f32_dpp v110, -v237, v96 quad_perm:[1,1,1,1] row_mask:0xf bank_mask:0xf
	v_fmac_f32_dpp v111, -v237, v98 quad_perm:[2,2,2,2] row_mask:0xf bank_mask:0xf
	v_fmac_f32_dpp v112, -v237, v100 quad_perm:[3,3,3,3] row_mask:0xf bank_mask:0xf
	ds_read2_b32 v[236:237], v251 offset0:40 offset1:44
	s_waitcnt lgkmcnt(7)
	v_fmac_f32_dpp v89, -v238, v103 quad_perm:[0,0,0,0] row_mask:0xf bank_mask:0xf
	v_fmac_f32_dpp v110, -v238, v105 quad_perm:[1,1,1,1] row_mask:0xf bank_mask:0xf
	v_fmac_f32_dpp v111, -v238, v104 quad_perm:[2,2,2,2] row_mask:0xf bank_mask:0xf
	v_fmac_f32_dpp v112, -v238, v102 quad_perm:[3,3,3,3] row_mask:0xf bank_mask:0xf
	v_fmac_f32_dpp v89, -v239, v101 quad_perm:[0,0,0,0] row_mask:0xf bank_mask:0xf
	v_fmac_f32_dpp v110, -v239, v99 quad_perm:[1,1,1,1] row_mask:0xf bank_mask:0xf
	v_fmac_f32_dpp v111, -v239, v97 quad_perm:[2,2,2,2] row_mask:0xf bank_mask:0xf
	v_fmac_f32_dpp v112, -v239, v95 quad_perm:[3,3,3,3] row_mask:0xf bank_mask:0xf
	ds_read2_b32 v[238:239], v251 offset0:48 offset1:48
	s_waitcnt lgkmcnt(7)
	v_fmac_f32_dpp v89, -v240, v93 quad_perm:[0,0,0,0] row_mask:0xf bank_mask:0xf
	v_fmac_f32_dpp v110, -v240, v91 quad_perm:[1,1,1,1] row_mask:0xf bank_mask:0xf
	v_add_u32_e32 v251, 0x110, v251
	ds_read2_b32 v[240:241], v251 offset0:0 offset1:4
	v_add_f32_e32 v89, v89, v110
	v_add_f32_e32 v111, v111, v112
	v_add_f32_e32 v89, v89, v111
	s_waitcnt lgkmcnt(7)
	v_fmac_f32_dpp v87, -v242, v4 quad_perm:[0,0,0,0] row_mask:0xf bank_mask:0xf
	v_mul_f32_dpp v110, -v242, v2 quad_perm:[1,1,1,1] row_mask:0xf bank_mask:0xf
	v_mul_f32_dpp v111, -v242, v3 quad_perm:[2,2,2,2] row_mask:0xf bank_mask:0xf
	v_mul_f32_dpp v112, -v242, v5 quad_perm:[3,3,3,3] row_mask:0xf bank_mask:0xf
	v_fmac_f32_dpp v87, -v243, v6 quad_perm:[0,0,0,0] row_mask:0xf bank_mask:0xf
	v_fmac_f32_dpp v110, -v243, v7 quad_perm:[1,1,1,1] row_mask:0xf bank_mask:0xf
	v_fmac_f32_dpp v111, -v243, v8 quad_perm:[2,2,2,2] row_mask:0xf bank_mask:0xf
	v_fmac_f32_dpp v112, -v243, v9 quad_perm:[3,3,3,3] row_mask:0xf bank_mask:0xf
	ds_read2_b32 v[242:243], v251 offset0:8 offset1:12
	s_waitcnt lgkmcnt(7)
; DI void phase_gdn_c1(const Ctx& c) {
;     ...
; #pragma unroll
;       for (int i = 1; i < 64; ++i) {
;         float s0 = sol[i], s1 = 0.f, s2 = 0.f, s3 = 0.f;
; #pragma unroll
;         for (int m = 0; m < i; ++m) {
;           const float t_ = Am[i * 68 + m] * sol[m];
;           if ((m & 3) == 0) s0 -= t_; else if ((m & 3) == 1) s1 -= t_; else if ((m & 3) == 2) s2 -= t_; else s3 -= t_;
;         }
;         sol[i] = (s0 + s1) + (s2 + s3);
;       }
	v_fmac_f32_dpp v87, -v244, v10 quad_perm:[0,0,0,0] row_mask:0xf bank_mask:0xf
	v_fmac_f32_dpp v110, -v244, v12 quad_perm:[1,1,1,1] row_mask:0xf bank_mask:0xf
	v_fmac_f32_dpp v111, -v244, v13 quad_perm:[2,2,2,2] row_mask:0xf bank_mask:0xf
	v_fmac_f32_dpp v112, -v244, v14 quad_perm:[3,3,3,3] row_mask:0xf bank_mask:0xf
	v_fmac_f32_dpp v87, -v245, v15 quad_perm:[0,0,0,0] row_mask:0xf bank_mask:0xf
	v_fmac_f32_dpp v110, -v245, v17 quad_perm:[1,1,1,1] row_mask:0xf bank_mask:0xf
	v_fmac_f32_dpp v111, -v245, v18 quad_perm:[2,2,2,2] row_mask:0xf bank_mask:0xf
	v_fmac_f32_dpp v112, -v245, v19 quad_perm:[3,3,3,3] row_mask:0xf bank_mask:0xf
	ds_read2_b32 v[244:245], v251 offset0:16 offset1:20
	s_waitcnt lgkmcnt(7)
	v_fmac_f32_dpp v87, -v230, v21 quad_perm:[0,0,0,0] row_mask:0xf bank_mask:0xf
	v_fmac_f32_dpp v110, -v230, v22 quad_perm:[1,1,1,1] row_mask:0xf bank_mask:0xf
	v_fmac_f32_dpp v111, -v230, v23 quad_perm:[2,2,2,2] row_mask:0xf bank_mask:0xf
	v_fmac_f32_dpp v112, -v230, v25 quad_perm:[3,3,3,3] row_mask:0xf bank_mask:0xf
	v_fmac_f32_dpp v87, -v231, v26 quad_perm:[0,0,0,0] row_mask:0xf bank_mask:0xf
	v_fmac_f32_dpp v110, -v231, v28 quad_perm:[1,1,1,1] row_mask:0xf bank_mask:0xf
	v_fmac_f32_dpp v111, -v231, v29 quad_perm:[2,2,2,2] row_mask:0xf bank_mask:0xf
	v_fmac_f32_dpp v112, -v231, v31 quad_perm:[3,3,3,3] row_mask:0xf bank_mask:0xf
	ds_read2_b32 v[230:231], v251 offset0:24 offset1:28
	s_waitcnt lgkmcnt(7)
	v_fmac_f32_dpp v87, -v232, v32 quad_perm:[0,0,0,0] row_mask:0xf bank_mask:0xf
	v_fmac_f32_dpp v110, -v232, v43 quad_perm:[1,1,1,1] row_mask:0xf bank_mask:0xf
	v_fmac_f32_dpp v111, -v232, v47 quad_perm:[2,2,2,2] row_mask:0xf bank_mask:0xf
	v_fmac_f32_dpp v112, -v232, v50 quad_perm:[3,3,3,3] row_mask:0xf bank_mask:0xf
	v_fmac_f32_dpp v87, -v233, v52 quad_perm:[0,0,0,0] row_mask:0xf bank_mask:0xf
	v_fmac_f32_dpp v110, -v233, v81 quad_perm:[1,1,1,1] row_mask:0xf bank_mask:0xf
	v_fmac_f32_dpp v111, -v233, v82 quad_perm:[2,2,2,2] row_mask:0xf bank_mask:0xf
	v_fmac_f32_dpp v112, -v233, v84 quad_perm:[3,3,3,3] row_mask:0xf bank_mask:0xf
	ds_read2_b32 v[232:233], v251 offset0:32 offset1:36
	s_waitcnt lgkmcnt(7)
	v_fmac_f32_dpp v87, -v234, v86 quad_perm:[0,0,0,0] row_mask:0xf bank_mask:0xf
	v_fmac_f32_dpp v110, -v234, v88 quad_perm:[1,1,1,1] row_mask:0xf bank_mask:0xf
	v_fmac_f32_dpp v111, -v234, v90 quad_perm:[2,2,2,2] row_mask:0xf bank_mask:0xf
	v_fmac_f32_dpp v112, -v234, v92 quad_perm:[3,3,3,3] row_mask:0xf bank_mask:0xf
	v_fmac_f32_dpp v87, -v235, v94 quad_perm:[0,0,0,0] row_mask:0xf bank_mask:0xf
	v_fmac_f32_dpp v110, -v235, v96 quad_perm:[1,1,1,1] row_mask:0xf bank_mask:0xf
	v_fmac_f32_dpp v111, -v235, v98 quad_perm:[2,2,2,2] row_mask:0xf bank_mask:0xf
	v_fmac_f32_dpp v112, -v235, v100 quad_perm:[3,3,3,3] row_mask:0xf bank_mask:0xf
	ds_read2_b32 v[234:235], v251 offset0:40 offset1:44
	s_waitcnt lgkmcnt(7)
	v_fmac_f32_dpp v87, -v236, v103 quad_perm:[0,0,0,0] row_mask:0xf bank_mask:0xf
	v_fmac_f32_dpp v110, -v236, v105 quad_perm:[1,1,1,1] row_mask:0xf bank_mask:0xf
	v_fmac_f32_dpp v111, -v236, v104 quad_perm:[2,2,2,2] row_mask:0xf bank_mask:0xf
	v_fmac_f32_dpp v112, -v236, v102 quad_perm:[3,3,3,3] row_mask:0xf bank_mask:0xf
	v_fmac_f32_dpp v87, -v237, v101 quad_perm:[0,0,0,0] row_mask:0xf bank_mask:0xf
	v_fmac_f32_dpp v110, -v237, v99 quad_perm:[1,1,1,1] row_mask:0xf bank_mask:0xf
	v_fmac_f32_dpp v111, -v237, v97 quad_perm:[2,2,2,2] row_mask:0xf bank_mask:0xf
	v_fmac_f32_dpp v112, -v237, v95 quad_perm:[3,3,3,3] row_mask:0xf bank_mask:0xf
	ds_read2_b32 v[236:237], v251 offset0:48 offset1:48
	s_waitcnt lgkmcnt(7)
	v_fmac_f32_dpp v87, -v238, v93 quad_perm:[0,0,0,0] row_mask:0xf bank_mask:0xf
	v_fmac_f32_dpp v110, -v238, v91 quad_perm:[1,1,1,1] row_mask:0xf bank_mask:0xf
	v_fmac_f32_dpp v111, -v238, v89 quad_perm:[2,2,2,2] row_mask:0xf bank_mask:0xf
	v_add_u32_e32 v251, 0x110, v251
	ds_read2_b32 v[238:239], v251 offset0:0 offset1:4
	v_add_f32_e32 v87, v87, v110
	v_add_f32_e32 v111, v111, v112
	v_add_f32_e32 v87, v87, v111
	s_waitcnt lgkmcnt(7)
	v_fmac_f32_dpp v85, -v240, v4 quad_perm:[0,0,0,0] row_mask:0xf bank_mask:0xf
	v_mul_f32_dpp v110, -v240, v2 quad_perm:[1,1,1,1] row_mask:0xf bank_mask:0xf
	v_mul_f32_dpp v111, -v240, v3 quad_perm:[2,2,2,2] row_mask:0xf bank_mask:0xf
	v_mul_f32_dpp v112, -v240, v5 quad_perm:[3,3,3,3] row_mask:0xf bank_mask:0xf
	v_fmac_f32_dpp v85, -v241, v6 quad_perm:[0,0,0,0] row_mask:0xf bank_mask:0xf
	v_fmac_f32_dpp v110, -v241, v7 quad_perm:[1,1,1,1] row_mask:0xf bank_mask:0xf
	v_fmac_f32_dpp v111, -v241, v8 quad_perm:[2,2,2,2] row_mask:0xf bank_mask:0xf
	v_fmac_f32_dpp v112, -v241, v9 quad_perm:[3,3,3,3] row_mask:0xf bank_mask:0xf
	ds_read2_b32 v[240:241], v251 offset0:8 offset1:12
	s_waitcnt lgkmcnt(7)
	v_fmac_f32_dpp v85, -v242, v10 quad_perm:[0,0,0,0] row_mask:0xf bank_mask:0xf
	v_fmac_f32_dpp v110, -v242, v12 quad_perm:[1,1,1,1] row_mask:0xf bank_mask:0xf
	v_fmac_f32_dpp v111, -v242, v13 quad_perm:[2,2,2,2] row_mask:0xf bank_mask:0xf
	v_fmac_f32_dpp v112, -v242, v14 quad_perm:[3,3,3,3] row_mask:0xf bank_mask:0xf
	v_fmac_f32_dpp v85, -v243, v15 quad_perm:[0,0,0,0] row_mask:0xf bank_mask:0xf
	v_fmac_f32_dpp v110, -v243, v17 quad_perm:[1,1,1,1] row_mask:0xf bank_mask:0xf
	v_fmac_f32_dpp v111, -v243, v18 quad_perm:[2,2,2,2] row_mask:0xf bank_mask:0xf
	v_fmac_f32_dpp v112, -v243, v19 quad_perm:[3,3,3,3] row_mask:0xf bank_mask:0xf
	ds_read2_b32 v[242:243], v251 offset0:16 offset1:20
	s_waitcnt lgkmcnt(7)
; DI void phase_gdn_c1(const Ctx& c) {
;     ...
; #pragma unroll
;       for (int i = 1; i < 64; ++i) {
;         float s0 = sol[i], s1 = 0.f, s2 = 0.f, s3 = 0.f;
; #pragma unroll
;         for (int m = 0; m < i; ++m) {
;           const float t_ = Am[i * 68 + m] * sol[m];
;           if ((m & 3) == 0) s0 -= t_; else if ((m & 3) == 1) s1 -= t_; else if ((m & 3) == 2) s2 -= t_; else s3 -= t_;
;         }
;         sol[i] = (s0 + s1) + (s2 + s3);
;       }
	v_fmac_f32_dpp v85, -v244, v21 quad_perm:[0,0,0,0] row_mask:0xf bank_mask:0xf
	v_fmac_f32_dpp v110, -v244, v22 quad_perm:[1,1,1,1] row_mask:0xf bank_mask:0xf
	v_fmac_f32_dpp v111, -v244, v23 quad_perm:[2,2,2,2] row_mask:0xf bank_mask:0xf
	v_fmac_f32_dpp v112, -v244, v25 quad_perm:[3,3,3,3] row_mask:0xf bank_mask:0xf
	v_fmac_f32_dpp v85, -v245, v26 quad_perm:[0,0,0,0] row_mask:0xf bank_mask:0xf
	v_fmac_f32_dpp v110, -v245, v28 quad_perm:[1,1,1,1] row_mask:0xf bank_mask:0xf
	v_fmac_f32_dpp v111, -v245, v29 quad_perm:[2,2,2,2] row_mask:0xf bank_mask:0xf
	v_fmac_f32_dpp v112, -v245, v31 quad_perm:[3,3,3,3] row_mask:0xf bank_mask:0xf
	ds_read2_b32 v[244:245], v251 offset0:24 offset1:28
	s_waitcnt lgkmcnt(7)
	v_fmac_f32_dpp v85, -v230, v32 quad_perm:[0,0,0,0] row_mask:0xf bank_mask:0xf
	v_fmac_f32_dpp v110, -v230, v43 quad_perm:[1,1,1,1] row_mask:0xf bank_mask:0xf
	v_fmac_f32_dpp v111, -v230, v47 quad_perm:[2,2,2,2] row_mask:0xf bank_mask:0xf
	v_fmac_f32_dpp v112, -v230, v50 quad_perm:[3,3,3,3] row_mask:0xf bank_mask:0xf
	v_fmac_f32_dpp v85, -v231, v52 quad_perm:[0,0,0,0] row_mask:0xf bank_mask:0xf
	v_fmac_f32_dpp v110, -v231, v81 quad_perm:[1,1,1,1] row_mask:0xf bank_mask:0xf
	v_fmac_f32_dpp v111, -v231, v82 quad_perm:[2,2,2,2] row_mask:0xf bank_mask:0xf
	v_fmac_f32_dpp v112, -v231, v84 quad_perm:[3,3,3,3] row_mask:0xf bank_mask:0xf
	ds_read2_b32 v[230:231], v251 offset0:32 offset1:36
	s_waitcnt lgkmcnt(7)
	v_fmac_f32_dpp v85, -v232, v86 quad_perm:[0,0,0,0] row_mask:0xf bank_mask:0xf
	v_fmac_f32_dpp v110, -v232, v88 quad_perm:[1,1,1,1] row_mask:0xf bank_mask:0xf
	v_fmac_f32_dpp v111, -v232, v90 quad_perm:[2,2,2,2] row_mask:0xf bank_mask:0xf
	v_fmac_f32_dpp v112, -v232, v92 quad_perm:[3,3,3,3] row_mask:0xf bank_mask:0xf
	v_fmac_f32_dpp v85, -v233, v94 quad_perm:[0,0,0,0] row_mask:0xf bank_mask:0xf
	v_fmac_f32_dpp v110, -v233, v96 quad_perm:[1,1,1,1] row_mask:0xf bank_mask:0xf
	v_fmac_f32_dpp v111, -v233, v98 quad_perm:[2,2,2,2] row_mask:0xf bank_mask:0xf
	v_fmac_f32_dpp v112, -v233, v100 quad_perm:[3,3,3,3] row_mask:0xf bank_mask:0xf
	ds_read2_b32 v[232:233], v251 offset0:40 offset1:44
	s_waitcnt lgkmcnt(7)
	v_fmac_f32_dpp v85, -v234, v103 quad_perm:[0,0,0,0] row_mask:0xf bank_mask:0xf
	v_fmac_f32_dpp v110, -v234, v105 quad_perm:[1,1,1,1] row_mask:0xf bank_mask:0xf
	v_fmac_f32_dpp v111, -v234, v104 quad_perm:[2,2,2,2] row_mask:0xf bank_mask:0xf
	v_fmac_f32_dpp v112, -v234, v102 quad_perm:[3,3,3,3] row_mask:0xf bank_mask:0xf
	v_fmac_f32_dpp v85, -v235, v101 quad_perm:[0,0,0,0] row_mask:0xf bank_mask:0xf
	v_fmac_f32_dpp v110, -v235, v99 quad_perm:[1,1,1,1] row_mask:0xf bank_mask:0xf
	v_fmac_f32_dpp v111, -v235, v97 quad_perm:[2,2,2,2] row_mask:0xf bank_mask:0xf
	v_fmac_f32_dpp v112, -v235, v95 quad_perm:[3,3,3,3] row_mask:0xf bank_mask:0xf
	ds_read2_b32 v[234:235], v251 offset0:48 offset1:52
	s_waitcnt lgkmcnt(7)
	v_fmac_f32_dpp v85, -v236, v93 quad_perm:[0,0,0,0] row_mask:0xf bank_mask:0xf
	v_fmac_f32_dpp v110, -v236, v91 quad_perm:[1,1,1,1] row_mask:0xf bank_mask:0xf
	v_fmac_f32_dpp v111, -v236, v89 quad_perm:[2,2,2,2] row_mask:0xf bank_mask:0xf
	v_fmac_f32_dpp v112, -v236, v87 quad_perm:[3,3,3,3] row_mask:0xf bank_mask:0xf
	v_add_u32_e32 v251, 0x110, v251
	ds_read2_b32 v[236:237], v251 offset0:0 offset1:4
	v_add_f32_e32 v85, v85, v110
	v_add_f32_e32 v111, v111, v112
	v_add_f32_e32 v85, v85, v111
	s_waitcnt lgkmcnt(7)
	v_fmac_f32_dpp v83, -v238, v4 quad_perm:[0,0,0,0] row_mask:0xf bank_mask:0xf
	v_mul_f32_dpp v110, -v238, v2 quad_perm:[1,1,1,1] row_mask:0xf bank_mask:0xf
	v_mul_f32_dpp v111, -v238, v3 quad_perm:[2,2,2,2] row_mask:0xf bank_mask:0xf
	v_mul_f32_dpp v112, -v238, v5 quad_perm:[3,3,3,3] row_mask:0xf bank_mask:0xf
	v_fmac_f32_dpp v83, -v239, v6 quad_perm:[0,0,0,0] row_mask:0xf bank_mask:0xf
	v_fmac_f32_dpp v110, -v239, v7 quad_perm:[1,1,1,1] row_mask:0xf bank_mask:0xf
	v_fmac_f32_dpp v111, -v239, v8 quad_perm:[2,2,2,2] row_mask:0xf bank_mask:0xf
	v_fmac_f32_dpp v112, -v239, v9 quad_perm:[3,3,3,3] row_mask:0xf bank_mask:0xf
	ds_read2_b32 v[238:239], v251 offset0:8 offset1:12
	s_waitcnt lgkmcnt(7)
	v_fmac_f32_dpp v83, -v240, v10 quad_perm:[0,0,0,0] row_mask:0xf bank_mask:0xf
	v_fmac_f32_dpp v110, -v240, v12 quad_perm:[1,1,1,1] row_mask:0xf bank_mask:0xf
	v_fmac_f32_dpp v111, -v240, v13 quad_perm:[2,2,2,2] row_mask:0xf bank_mask:0xf
	v_fmac_f32_dpp v112, -v240, v14 quad_perm:[3,3,3,3] row_mask:0xf bank_mask:0xf
	v_fmac_f32_dpp v83, -v241, v15 quad_perm:[0,0,0,0] row_mask:0xf bank_mask:0xf
	v_fmac_f32_dpp v110, -v241, v17 quad_perm:[1,1,1,1] row_mask:0xf bank_mask:0xf
	v_fmac_f32_dpp v111, -v241, v18 quad_perm:[2,2,2,2] row_mask:0xf bank_mask:0xf
	v_fmac_f32_dpp v112, -v241, v19 quad_perm:[3,3,3,3] row_mask:0xf bank_mask:0xf
	ds_read2_b32 v[240:241], v251 offset0:16 offset1:20
	s_waitcnt lgkmcnt(7)
	v_fmac_f32_dpp v83, -v242, v21 quad_perm:[0,0,0,0] row_mask:0xf bank_mask:0xf
	v_fmac_f32_dpp v110, -v242, v22 quad_perm:[1,1,1,1] row_mask:0xf bank_mask:0xf
	v_fmac_f32_dpp v111, -v242, v23 quad_perm:[2,2,2,2] row_mask:0xf bank_mask:0xf
	v_fmac_f32_dpp v112, -v242, v25 quad_perm:[3,3,3,3] row_mask:0xf bank_mask:0xf
	v_fmac_f32_dpp v83, -v243, v26 quad_perm:[0,0,0,0] row_mask:0xf bank_mask:0xf
	v_fmac_f32_dpp v110, -v243, v28 quad_perm:[1,1,1,1] row_mask:0xf bank_mask:0xf
	v_fmac_f32_dpp v111, -v243, v29 quad_perm:[2,2,2,2] row_mask:0xf bank_mask:0xf
	v_fmac_f32_dpp v112, -v243, v31 quad_perm:[3,3,3,3] row_mask:0xf bank_mask:0xf
	ds_read2_b32 v[242:243], v251 offset0:24 offset1:28
	s_waitcnt lgkmcnt(7)
; DI void phase_gdn_c1(const Ctx& c) {
;     ...
; #pragma unroll
;       for (int i = 1; i < 64; ++i) {
;         float s0 = sol[i], s1 = 0.f, s2 = 0.f, s3 = 0.f;
; #pragma unroll
;         for (int m = 0; m < i; ++m) {
;           const float t_ = Am[i * 68 + m] * sol[m];
;           if ((m & 3) == 0) s0 -= t_; else if ((m & 3) == 1) s1 -= t_; else if ((m & 3) == 2) s2 -= t_; else s3 -= t_;
;         }
;         sol[i] = (s0 + s1) + (s2 + s3);
;       }
	v_fmac_f32_dpp v83, -v244, v32 quad_perm:[0,0,0,0] row_mask:0xf bank_mask:0xf
	v_fmac_f32_dpp v110, -v244, v43 quad_perm:[1,1,1,1] row_mask:0xf bank_mask:0xf
	v_fmac_f32_dpp v111, -v244, v47 quad_perm:[2,2,2,2] row_mask:0xf bank_mask:0xf
	v_fmac_f32_dpp v112, -v244, v50 quad_perm:[3,3,3,3] row_mask:0xf bank_mask:0xf
	v_fmac_f32_dpp v83, -v245, v52 quad_perm:[0,0,0,0] row_mask:0xf bank_mask:0xf
	v_fmac_f32_dpp v110, -v245, v81 quad_perm:[1,1,1,1] row_mask:0xf bank_mask:0xf
	v_fmac_f32_dpp v111, -v245, v82 quad_perm:[2,2,2,2] row_mask:0xf bank_mask:0xf
	v_fmac_f32_dpp v112, -v245, v84 quad_perm:[3,3,3,3] row_mask:0xf bank_mask:0xf
	ds_read2_b32 v[244:245], v251 offset0:32 offset1:36
	s_waitcnt lgkmcnt(7)
	v_fmac_f32_dpp v83, -v230, v86 quad_perm:[0,0,0,0] row_mask:0xf bank_mask:0xf
	v_fmac_f32_dpp v110, -v230, v88 quad_perm:[1,1,1,1] row_mask:0xf bank_mask:0xf
	v_fmac_f32_dpp v111, -v230, v90 quad_perm:[2,2,2,2] row_mask:0xf bank_mask:0xf
	v_fmac_f32_dpp v112, -v230, v92 quad_perm:[3,3,3,3] row_mask:0xf bank_mask:0xf
	v_fmac_f32_dpp v83, -v231, v94 quad_perm:[0,0,0,0] row_mask:0xf bank_mask:0xf
	v_fmac_f32_dpp v110, -v231, v96 quad_perm:[1,1,1,1] row_mask:0xf bank_mask:0xf
	v_fmac_f32_dpp v111, -v231, v98 quad_perm:[2,2,2,2] row_mask:0xf bank_mask:0xf
	v_fmac_f32_dpp v112, -v231, v100 quad_perm:[3,3,3,3] row_mask:0xf bank_mask:0xf
	ds_read2_b32 v[230:231], v251 offset0:40 offset1:44
	s_waitcnt lgkmcnt(7)
	v_fmac_f32_dpp v83, -v232, v103 quad_perm:[0,0,0,0] row_mask:0xf bank_mask:0xf
	v_fmac_f32_dpp v110, -v232, v105 quad_perm:[1,1,1,1] row_mask:0xf bank_mask:0xf
	v_fmac_f32_dpp v111, -v232, v104 quad_perm:[2,2,2,2] row_mask:0xf bank_mask:0xf
	v_fmac_f32_dpp v112, -v232, v102 quad_perm:[3,3,3,3] row_mask:0xf bank_mask:0xf
	v_fmac_f32_dpp v83, -v233, v101 quad_perm:[0,0,0,0] row_mask:0xf bank_mask:0xf
	v_fmac_f32_dpp v110, -v233, v99 quad_perm:[1,1,1,1] row_mask:0xf bank_mask:0xf
	v_fmac_f32_dpp v111, -v233, v97 quad_perm:[2,2,2,2] row_mask:0xf bank_mask:0xf
	v_fmac_f32_dpp v112, -v233, v95 quad_perm:[3,3,3,3] row_mask:0xf bank_mask:0xf
	ds_read2_b32 v[232:233], v251 offset0:48 offset1:52
	s_waitcnt lgkmcnt(7)
	v_fmac_f32_dpp v83, -v234, v93 quad_perm:[0,0,0,0] row_mask:0xf bank_mask:0xf
	v_fmac_f32_dpp v110, -v234, v91 quad_perm:[1,1,1,1] row_mask:0xf bank_mask:0xf
	v_fmac_f32_dpp v111, -v234, v89 quad_perm:[2,2,2,2] row_mask:0xf bank_mask:0xf
	v_fmac_f32_dpp v112, -v234, v87 quad_perm:[3,3,3,3] row_mask:0xf bank_mask:0xf
	v_fmac_f32_dpp v83, -v235, v85 quad_perm:[0,0,0,0] row_mask:0xf bank_mask:0xf
	v_add_u32_e32 v251, 0x110, v251
	ds_read2_b32 v[234:235], v251 offset0:0 offset1:4
	v_add_f32_e32 v83, v83, v110
	v_add_f32_e32 v111, v111, v112
	v_add_f32_e32 v83, v83, v111
	s_waitcnt lgkmcnt(7)
	v_fmac_f32_dpp v53, -v236, v4 quad_perm:[0,0,0,0] row_mask:0xf bank_mask:0xf
	v_mul_f32_dpp v110, -v236, v2 quad_perm:[1,1,1,1] row_mask:0xf bank_mask:0xf
	v_mul_f32_dpp v111, -v236, v3 quad_perm:[2,2,2,2] row_mask:0xf bank_mask:0xf
	v_mul_f32_dpp v112, -v236, v5 quad_perm:[3,3,3,3] row_mask:0xf bank_mask:0xf
	v_fmac_f32_dpp v53, -v237, v6 quad_perm:[0,0,0,0] row_mask:0xf bank_mask:0xf
	v_fmac_f32_dpp v110, -v237, v7 quad_perm:[1,1,1,1] row_mask:0xf bank_mask:0xf
	v_fmac_f32_dpp v111, -v237, v8 quad_perm:[2,2,2,2] row_mask:0xf bank_mask:0xf
	v_fmac_f32_dpp v112, -v237, v9 quad_perm:[3,3,3,3] row_mask:0xf bank_mask:0xf
	ds_read2_b32 v[236:237], v251 offset0:8 offset1:12
	s_waitcnt lgkmcnt(7)
	v_fmac_f32_dpp v53, -v238, v10 quad_perm:[0,0,0,0] row_mask:0xf bank_mask:0xf
	v_fmac_f32_dpp v110, -v238, v12 quad_perm:[1,1,1,1] row_mask:0xf bank_mask:0xf
	v_fmac_f32_dpp v111, -v238, v13 quad_perm:[2,2,2,2] row_mask:0xf bank_mask:0xf
	v_fmac_f32_dpp v112, -v238, v14 quad_perm:[3,3,3,3] row_mask:0xf bank_mask:0xf
	v_fmac_f32_dpp v53, -v239, v15 quad_perm:[0,0,0,0] row_mask:0xf bank_mask:0xf
	v_fmac_f32_dpp v110, -v239, v17 quad_perm:[1,1,1,1] row_mask:0xf bank_mask:0xf
	v_fmac_f32_dpp v111, -v239, v18 quad_perm:[2,2,2,2] row_mask:0xf bank_mask:0xf
	v_fmac_f32_dpp v112, -v239, v19 quad_perm:[3,3,3,3] row_mask:0xf bank_mask:0xf
	ds_read2_b32 v[238:239], v251 offset0:16 offset1:20
	s_waitcnt lgkmcnt(7)
	v_fmac_f32_dpp v53, -v240, v21 quad_perm:[0,0,0,0] row_mask:0xf bank_mask:0xf
	v_fmac_f32_dpp v110, -v240, v22 quad_perm:[1,1,1,1] row_mask:0xf bank_mask:0xf
	v_fmac_f32_dpp v111, -v240, v23 quad_perm:[2,2,2,2] row_mask:0xf bank_mask:0xf
	v_fmac_f32_dpp v112, -v240, v25 quad_perm:[3,3,3,3] row_mask:0xf bank_mask:0xf
	v_fmac_f32_dpp v53, -v241, v26 quad_perm:[0,0,0,0] row_mask:0xf bank_mask:0xf
	v_fmac_f32_dpp v110, -v241, v28 quad_perm:[1,1,1,1] row_mask:0xf bank_mask:0xf
	v_fmac_f32_dpp v111, -v241, v29 quad_perm:[2,2,2,2] row_mask:0xf bank_mask:0xf
	v_fmac_f32_dpp v112, -v241, v31 quad_perm:[3,3,3,3] row_mask:0xf bank_mask:0xf
	ds_read2_b32 v[240:241], v251 offset0:24 offset1:28
	s_waitcnt lgkmcnt(7)
	v_fmac_f32_dpp v53, -v242, v32 quad_perm:[0,0,0,0] row_mask:0xf bank_mask:0xf
	v_fmac_f32_dpp v110, -v242, v43 quad_perm:[1,1,1,1] row_mask:0xf bank_mask:0xf
	v_fmac_f32_dpp v111, -v242, v47 quad_perm:[2,2,2,2] row_mask:0xf bank_mask:0xf
	v_fmac_f32_dpp v112, -v242, v50 quad_perm:[3,3,3,3] row_mask:0xf bank_mask:0xf
	v_fmac_f32_dpp v53, -v243, v52 quad_perm:[0,0,0,0] row_mask:0xf bank_mask:0xf
	v_fmac_f32_dpp v110, -v243, v81 quad_perm:[1,1,1,1] row_mask:0xf bank_mask:0xf
	v_fmac_f32_dpp v111, -v243, v82 quad_perm:[2,2,2,2] row_mask:0xf bank_mask:0xf
	v_fmac_f32_dpp v112, -v243, v84 quad_perm:[3,3,3,3] row_mask:0xf bank_mask:0xf
	ds_read2_b32 v[242:243], v251 offset0:32 offset1:36
	s_waitcnt lgkmcnt(7)
; DI void phase_gdn_c1(const Ctx& c) {
;     ...
; #pragma unroll
;       for (int i = 1; i < 64; ++i) {
;         float s0 = sol[i], s1 = 0.f, s2 = 0.f, s3 = 0.f;
; #pragma unroll
;         for (int m = 0; m < i; ++m) {
;           const float t_ = Am[i * 68 + m] * sol[m];
;           if ((m & 3) == 0) s0 -= t_; else if ((m & 3) == 1) s1 -= t_; else if ((m & 3) == 2) s2 -= t_; else s3 -= t_;
;         }
;         sol[i] = (s0 + s1) + (s2 + s3);
;       }
	v_fmac_f32_dpp v53, -v244, v86 quad_perm:[0,0,0,0] row_mask:0xf bank_mask:0xf
	v_fmac_f32_dpp v110, -v244, v88 quad_perm:[1,1,1,1] row_mask:0xf bank_mask:0xf
	v_fmac_f32_dpp v111, -v244, v90 quad_perm:[2,2,2,2] row_mask:0xf bank_mask:0xf
	v_fmac_f32_dpp v112, -v244, v92 quad_perm:[3,3,3,3] row_mask:0xf bank_mask:0xf
	v_fmac_f32_dpp v53, -v245, v94 quad_perm:[0,0,0,0] row_mask:0xf bank_mask:0xf
	v_fmac_f32_dpp v110, -v245, v96 quad_perm:[1,1,1,1] row_mask:0xf bank_mask:0xf
	v_fmac_f32_dpp v111, -v245, v98 quad_perm:[2,2,2,2] row_mask:0xf bank_mask:0xf
	v_fmac_f32_dpp v112, -v245, v100 quad_perm:[3,3,3,3] row_mask:0xf bank_mask:0xf
	ds_read2_b32 v[244:245], v251 offset0:40 offset1:44
	s_waitcnt lgkmcnt(7)
	v_fmac_f32_dpp v53, -v230, v103 quad_perm:[0,0,0,0] row_mask:0xf bank_mask:0xf
	v_fmac_f32_dpp v110, -v230, v105 quad_perm:[1,1,1,1] row_mask:0xf bank_mask:0xf
	v_fmac_f32_dpp v111, -v230, v104 quad_perm:[2,2,2,2] row_mask:0xf bank_mask:0xf
	v_fmac_f32_dpp v112, -v230, v102 quad_perm:[3,3,3,3] row_mask:0xf bank_mask:0xf
	v_fmac_f32_dpp v53, -v231, v101 quad_perm:[0,0,0,0] row_mask:0xf bank_mask:0xf
	v_fmac_f32_dpp v110, -v231, v99 quad_perm:[1,1,1,1] row_mask:0xf bank_mask:0xf
	v_fmac_f32_dpp v111, -v231, v97 quad_perm:[2,2,2,2] row_mask:0xf bank_mask:0xf
	v_fmac_f32_dpp v112, -v231, v95 quad_perm:[3,3,3,3] row_mask:0xf bank_mask:0xf
	ds_read2_b32 v[230:231], v251 offset0:48 offset1:52
	s_waitcnt lgkmcnt(7)
	v_fmac_f32_dpp v53, -v232, v93 quad_perm:[0,0,0,0] row_mask:0xf bank_mask:0xf
	v_fmac_f32_dpp v110, -v232, v91 quad_perm:[1,1,1,1] row_mask:0xf bank_mask:0xf
	v_fmac_f32_dpp v111, -v232, v89 quad_perm:[2,2,2,2] row_mask:0xf bank_mask:0xf
	v_fmac_f32_dpp v112, -v232, v87 quad_perm:[3,3,3,3] row_mask:0xf bank_mask:0xf
	v_fmac_f32_dpp v53, -v233, v85 quad_perm:[0,0,0,0] row_mask:0xf bank_mask:0xf
	v_fmac_f32_dpp v110, -v233, v83 quad_perm:[1,1,1,1] row_mask:0xf bank_mask:0xf
	v_add_u32_e32 v251, 0x110, v251
	ds_read2_b32 v[232:233], v251 offset0:0 offset1:4
	v_add_f32_e32 v53, v53, v110
	v_add_f32_e32 v111, v111, v112
	v_add_f32_e32 v53, v53, v111
	s_waitcnt lgkmcnt(7)
	v_fmac_f32_dpp v51, -v234, v4 quad_perm:[0,0,0,0] row_mask:0xf bank_mask:0xf
	v_mul_f32_dpp v110, -v234, v2 quad_perm:[1,1,1,1] row_mask:0xf bank_mask:0xf
	v_mul_f32_dpp v111, -v234, v3 quad_perm:[2,2,2,2] row_mask:0xf bank_mask:0xf
	v_mul_f32_dpp v112, -v234, v5 quad_perm:[3,3,3,3] row_mask:0xf bank_mask:0xf
	v_fmac_f32_dpp v51, -v235, v6 quad_perm:[0,0,0,0] row_mask:0xf bank_mask:0xf
	v_fmac_f32_dpp v110, -v235, v7 quad_perm:[1,1,1,1] row_mask:0xf bank_mask:0xf
	v_fmac_f32_dpp v111, -v235, v8 quad_perm:[2,2,2,2] row_mask:0xf bank_mask:0xf
	v_fmac_f32_dpp v112, -v235, v9 quad_perm:[3,3,3,3] row_mask:0xf bank_mask:0xf
	ds_read2_b32 v[234:235], v251 offset0:8 offset1:12
	s_waitcnt lgkmcnt(7)
	v_fmac_f32_dpp v51, -v236, v10 quad_perm:[0,0,0,0] row_mask:0xf bank_mask:0xf
	v_fmac_f32_dpp v110, -v236, v12 quad_perm:[1,1,1,1] row_mask:0xf bank_mask:0xf
	v_fmac_f32_dpp v111, -v236, v13 quad_perm:[2,2,2,2] row_mask:0xf bank_mask:0xf
	v_fmac_f32_dpp v112, -v236, v14 quad_perm:[3,3,3,3] row_mask:0xf bank_mask:0xf
	v_fmac_f32_dpp v51, -v237, v15 quad_perm:[0,0,0,0] row_mask:0xf bank_mask:0xf
	v_fmac_f32_dpp v110, -v237, v17 quad_perm:[1,1,1,1] row_mask:0xf bank_mask:0xf
	v_fmac_f32_dpp v111, -v237, v18 quad_perm:[2,2,2,2] row_mask:0xf bank_mask:0xf
	v_fmac_f32_dpp v112, -v237, v19 quad_perm:[3,3,3,3] row_mask:0xf bank_mask:0xf
	ds_read2_b32 v[236:237], v251 offset0:16 offset1:20
	s_waitcnt lgkmcnt(7)
	v_fmac_f32_dpp v51, -v238, v21 quad_perm:[0,0,0,0] row_mask:0xf bank_mask:0xf
	v_fmac_f32_dpp v110, -v238, v22 quad_perm:[1,1,1,1] row_mask:0xf bank_mask:0xf
	v_fmac_f32_dpp v111, -v238, v23 quad_perm:[2,2,2,2] row_mask:0xf bank_mask:0xf
	v_fmac_f32_dpp v112, -v238, v25 quad_perm:[3,3,3,3] row_mask:0xf bank_mask:0xf
	v_fmac_f32_dpp v51, -v239, v26 quad_perm:[0,0,0,0] row_mask:0xf bank_mask:0xf
	v_fmac_f32_dpp v110, -v239, v28 quad_perm:[1,1,1,1] row_mask:0xf bank_mask:0xf
	v_fmac_f32_dpp v111, -v239, v29 quad_perm:[2,2,2,2] row_mask:0xf bank_mask:0xf
	v_fmac_f32_dpp v112, -v239, v31 quad_perm:[3,3,3,3] row_mask:0xf bank_mask:0xf
	ds_read2_b32 v[238:239], v251 offset0:24 offset1:28
	s_waitcnt lgkmcnt(7)
	v_fmac_f32_dpp v51, -v240, v32 quad_perm:[0,0,0,0] row_mask:0xf bank_mask:0xf
	v_fmac_f32_dpp v110, -v240, v43 quad_perm:[1,1,1,1] row_mask:0xf bank_mask:0xf
	v_fmac_f32_dpp v111, -v240, v47 quad_perm:[2,2,2,2] row_mask:0xf bank_mask:0xf
	v_fmac_f32_dpp v112, -v240, v50 quad_perm:[3,3,3,3] row_mask:0xf bank_mask:0xf
	v_fmac_f32_dpp v51, -v241, v52 quad_perm:[0,0,0,0] row_mask:0xf bank_mask:0xf
	v_fmac_f32_dpp v110, -v241, v81 quad_perm:[1,1,1,1] row_mask:0xf bank_mask:0xf
	v_fmac_f32_dpp v111, -v241, v82 quad_perm:[2,2,2,2] row_mask:0xf bank_mask:0xf
	v_fmac_f32_dpp v112, -v241, v84 quad_perm:[3,3,3,3] row_mask:0xf bank_mask:0xf
	ds_read2_b32 v[240:241], v251 offset0:32 offset1:36
	s_waitcnt lgkmcnt(7)
	v_fmac_f32_dpp v51, -v242, v86 quad_perm:[0,0,0,0] row_mask:0xf bank_mask:0xf
	v_fmac_f32_dpp v110, -v242, v88 quad_perm:[1,1,1,1] row_mask:0xf bank_mask:0xf
	v_fmac_f32_dpp v111, -v242, v90 quad_perm:[2,2,2,2] row_mask:0xf bank_mask:0xf
	v_fmac_f32_dpp v112, -v242, v92 quad_perm:[3,3,3,3] row_mask:0xf bank_mask:0xf
	v_fmac_f32_dpp v51, -v243, v94 quad_perm:[0,0,0,0] row_mask:0xf bank_mask:0xf
	v_fmac_f32_dpp v110, -v243, v96 quad_perm:[1,1,1,1] row_mask:0xf bank_mask:0xf
	v_fmac_f32_dpp v111, -v243, v98 quad_perm:[2,2,2,2] row_mask:0xf bank_mask:0xf
	v_fmac_f32_dpp v112, -v243, v100 quad_perm:[3,3,3,3] row_mask:0xf bank_mask:0xf
	ds_read2_b32 v[242:243], v251 offset0:40 offset1:44
	s_waitcnt lgkmcnt(7)
; DI void phase_gdn_c1(const Ctx& c) {
;     ...
; #pragma unroll
;       for (int i = 1; i < 64; ++i) {
;         float s0 = sol[i], s1 = 0.f, s2 = 0.f, s3 = 0.f;
; #pragma unroll
;         for (int m = 0; m < i; ++m) {
;           const float t_ = Am[i * 68 + m] * sol[m];
;           if ((m & 3) == 0) s0 -= t_; else if ((m & 3) == 1) s1 -= t_; else if ((m & 3) == 2) s2 -= t_; else s3 -= t_;
;         }
;         sol[i] = (s0 + s1) + (s2 + s3);
;       }
	v_fmac_f32_dpp v51, -v244, v103 quad_perm:[0,0,0,0] row_mask:0xf bank_mask:0xf
	v_fmac_f32_dpp v110, -v244, v105 quad_perm:[1,1,1,1] row_mask:0xf bank_mask:0xf
	v_fmac_f32_dpp v111, -v244, v104 quad_perm:[2,2,2,2] row_mask:0xf bank_mask:0xf
	v_fmac_f32_dpp v112, -v244, v102 quad_perm:[3,3,3,3] row_mask:0xf bank_mask:0xf
	v_fmac_f32_dpp v51, -v245, v101 quad_perm:[0,0,0,0] row_mask:0xf bank_mask:0xf
	v_fmac_f32_dpp v110, -v245, v99 quad_perm:[1,1,1,1] row_mask:0xf bank_mask:0xf
	v_fmac_f32_dpp v111, -v245, v97 quad_perm:[2,2,2,2] row_mask:0xf bank_mask:0xf
	v_fmac_f32_dpp v112, -v245, v95 quad_perm:[3,3,3,3] row_mask:0xf bank_mask:0xf
	ds_read2_b32 v[244:245], v251 offset0:48 offset1:52
	s_waitcnt lgkmcnt(7)
	v_fmac_f32_dpp v51, -v230, v93 quad_perm:[0,0,0,0] row_mask:0xf bank_mask:0xf
	v_fmac_f32_dpp v110, -v230, v91 quad_perm:[1,1,1,1] row_mask:0xf bank_mask:0xf
	v_fmac_f32_dpp v111, -v230, v89 quad_perm:[2,2,2,2] row_mask:0xf bank_mask:0xf
	v_fmac_f32_dpp v112, -v230, v87 quad_perm:[3,3,3,3] row_mask:0xf bank_mask:0xf
	v_fmac_f32_dpp v51, -v231, v85 quad_perm:[0,0,0,0] row_mask:0xf bank_mask:0xf
	v_fmac_f32_dpp v110, -v231, v83 quad_perm:[1,1,1,1] row_mask:0xf bank_mask:0xf
	v_fmac_f32_dpp v111, -v231, v53 quad_perm:[2,2,2,2] row_mask:0xf bank_mask:0xf
	v_add_u32_e32 v251, 0x110, v251
	ds_read2_b32 v[230:231], v251 offset0:0 offset1:4
	v_add_f32_e32 v51, v51, v110
	v_add_f32_e32 v111, v111, v112
	v_add_f32_e32 v51, v51, v111
	s_waitcnt lgkmcnt(7)
	v_fmac_f32_dpp v45, -v232, v4 quad_perm:[0,0,0,0] row_mask:0xf bank_mask:0xf
	v_mul_f32_dpp v110, -v232, v2 quad_perm:[1,1,1,1] row_mask:0xf bank_mask:0xf
	v_mul_f32_dpp v111, -v232, v3 quad_perm:[2,2,2,2] row_mask:0xf bank_mask:0xf
	v_mul_f32_dpp v112, -v232, v5 quad_perm:[3,3,3,3] row_mask:0xf bank_mask:0xf
	v_fmac_f32_dpp v45, -v233, v6 quad_perm:[0,0,0,0] row_mask:0xf bank_mask:0xf
	v_fmac_f32_dpp v110, -v233, v7 quad_perm:[1,1,1,1] row_mask:0xf bank_mask:0xf
	v_fmac_f32_dpp v111, -v233, v8 quad_perm:[2,2,2,2] row_mask:0xf bank_mask:0xf
	v_fmac_f32_dpp v112, -v233, v9 quad_perm:[3,3,3,3] row_mask:0xf bank_mask:0xf
	ds_read2_b32 v[232:233], v251 offset0:8 offset1:12
	s_waitcnt lgkmcnt(7)
	v_fmac_f32_dpp v45, -v234, v10 quad_perm:[0,0,0,0] row_mask:0xf bank_mask:0xf
	v_fmac_f32_dpp v110, -v234, v12 quad_perm:[1,1,1,1] row_mask:0xf bank_mask:0xf
	v_fmac_f32_dpp v111, -v234, v13 quad_perm:[2,2,2,2] row_mask:0xf bank_mask:0xf
	v_fmac_f32_dpp v112, -v234, v14 quad_perm:[3,3,3,3] row_mask:0xf bank_mask:0xf
	v_fmac_f32_dpp v45, -v235, v15 quad_perm:[0,0,0,0] row_mask:0xf bank_mask:0xf
	v_fmac_f32_dpp v110, -v235, v17 quad_perm:[1,1,1,1] row_mask:0xf bank_mask:0xf
	v_fmac_f32_dpp v111, -v235, v18 quad_perm:[2,2,2,2] row_mask:0xf bank_mask:0xf
	v_fmac_f32_dpp v112, -v235, v19 quad_perm:[3,3,3,3] row_mask:0xf bank_mask:0xf
	ds_read2_b32 v[234:235], v251 offset0:16 offset1:20
	s_waitcnt lgkmcnt(7)
	v_fmac_f32_dpp v45, -v236, v21 quad_perm:[0,0,0,0] row_mask:0xf bank_mask:0xf
	v_fmac_f32_dpp v110, -v236, v22 quad_perm:[1,1,1,1] row_mask:0xf bank_mask:0xf
	v_fmac_f32_dpp v111, -v236, v23 quad_perm:[2,2,2,2] row_mask:0xf bank_mask:0xf
	v_fmac_f32_dpp v112, -v236, v25 quad_perm:[3,3,3,3] row_mask:0xf bank_mask:0xf
	v_fmac_f32_dpp v45, -v237, v26 quad_perm:[0,0,0,0] row_mask:0xf bank_mask:0xf
	v_fmac_f32_dpp v110, -v237, v28 quad_perm:[1,1,1,1] row_mask:0xf bank_mask:0xf
	v_fmac_f32_dpp v111, -v237, v29 quad_perm:[2,2,2,2] row_mask:0xf bank_mask:0xf
	v_fmac_f32_dpp v112, -v237, v31 quad_perm:[3,3,3,3] row_mask:0xf bank_mask:0xf
	ds_read2_b32 v[236:237], v251 offset0:24 offset1:28
	s_waitcnt lgkmcnt(7)
	v_fmac_f32_dpp v45, -v238, v32 quad_perm:[0,0,0,0] row_mask:0xf bank_mask:0xf
	v_fmac_f32_dpp v110, -v238, v43 quad_perm:[1,1,1,1] row_mask:0xf bank_mask:0xf
	v_fmac_f32_dpp v111, -v238, v47 quad_perm:[2,2,2,2] row_mask:0xf bank_mask:0xf
	v_fmac_f32_dpp v112, -v238, v50 quad_perm:[3,3,3,3] row_mask:0xf bank_mask:0xf
	v_fmac_f32_dpp v45, -v239, v52 quad_perm:[0,0,0,0] row_mask:0xf bank_mask:0xf
	v_fmac_f32_dpp v110, -v239, v81 quad_perm:[1,1,1,1] row_mask:0xf bank_mask:0xf
	v_fmac_f32_dpp v111, -v239, v82 quad_perm:[2,2,2,2] row_mask:0xf bank_mask:0xf
	v_fmac_f32_dpp v112, -v239, v84 quad_perm:[3,3,3,3] row_mask:0xf bank_mask:0xf
	ds_read2_b32 v[238:239], v251 offset0:32 offset1:36
	s_waitcnt lgkmcnt(7)
	v_fmac_f32_dpp v45, -v240, v86 quad_perm:[0,0,0,0] row_mask:0xf bank_mask:0xf
	v_fmac_f32_dpp v110, -v240, v88 quad_perm:[1,1,1,1] row_mask:0xf bank_mask:0xf
	v_fmac_f32_dpp v111, -v240, v90 quad_perm:[2,2,2,2] row_mask:0xf bank_mask:0xf
	v_fmac_f32_dpp v112, -v240, v92 quad_perm:[3,3,3,3] row_mask:0xf bank_mask:0xf
	v_fmac_f32_dpp v45, -v241, v94 quad_perm:[0,0,0,0] row_mask:0xf bank_mask:0xf
	v_fmac_f32_dpp v110, -v241, v96 quad_perm:[1,1,1,1] row_mask:0xf bank_mask:0xf
	v_fmac_f32_dpp v111, -v241, v98 quad_perm:[2,2,2,2] row_mask:0xf bank_mask:0xf
	v_fmac_f32_dpp v112, -v241, v100 quad_perm:[3,3,3,3] row_mask:0xf bank_mask:0xf
	ds_read2_b32 v[240:241], v251 offset0:40 offset1:44
	s_waitcnt lgkmcnt(7)
	v_fmac_f32_dpp v45, -v242, v103 quad_perm:[0,0,0,0] row_mask:0xf bank_mask:0xf
	v_fmac_f32_dpp v110, -v242, v105 quad_perm:[1,1,1,1] row_mask:0xf bank_mask:0xf
	v_fmac_f32_dpp v111, -v242, v104 quad_perm:[2,2,2,2] row_mask:0xf bank_mask:0xf
	v_fmac_f32_dpp v112, -v242, v102 quad_perm:[3,3,3,3] row_mask:0xf bank_mask:0xf
	v_fmac_f32_dpp v45, -v243, v101 quad_perm:[0,0,0,0] row_mask:0xf bank_mask:0xf
	v_fmac_f32_dpp v110, -v243, v99 quad_perm:[1,1,1,1] row_mask:0xf bank_mask:0xf
	v_fmac_f32_dpp v111, -v243, v97 quad_perm:[2,2,2,2] row_mask:0xf bank_mask:0xf
	v_fmac_f32_dpp v112, -v243, v95 quad_perm:[3,3,3,3] row_mask:0xf bank_mask:0xf
	ds_read2_b32 v[242:243], v251 offset0:48 offset1:52
	s_waitcnt lgkmcnt(7)
; DI void phase_gdn_c1(const Ctx& c) {
;     ...
; #pragma unroll
;       for (int i = 1; i < 64; ++i) {
;         float s0 = sol[i], s1 = 0.f, s2 = 0.f, s3 = 0.f;
; #pragma unroll
;         for (int m = 0; m < i; ++m) {
;           const float t_ = Am[i * 68 + m] * sol[m];
;           if ((m & 3) == 0) s0 -= t_; else if ((m & 3) == 1) s1 -= t_; else if ((m & 3) == 2) s2 -= t_; else s3 -= t_;
;         }
;         sol[i] = (s0 + s1) + (s2 + s3);
;       }
	v_fmac_f32_dpp v45, -v244, v93 quad_perm:[0,0,0,0] row_mask:0xf bank_mask:0xf
	v_fmac_f32_dpp v110, -v244, v91 quad_perm:[1,1,1,1] row_mask:0xf bank_mask:0xf
	v_fmac_f32_dpp v111, -v244, v89 quad_perm:[2,2,2,2] row_mask:0xf bank_mask:0xf
	v_fmac_f32_dpp v112, -v244, v87 quad_perm:[3,3,3,3] row_mask:0xf bank_mask:0xf
	v_fmac_f32_dpp v45, -v245, v85 quad_perm:[0,0,0,0] row_mask:0xf bank_mask:0xf
	v_fmac_f32_dpp v110, -v245, v83 quad_perm:[1,1,1,1] row_mask:0xf bank_mask:0xf
	v_fmac_f32_dpp v111, -v245, v53 quad_perm:[2,2,2,2] row_mask:0xf bank_mask:0xf
	v_fmac_f32_dpp v112, -v245, v51 quad_perm:[3,3,3,3] row_mask:0xf bank_mask:0xf
	ds_read2_b32 v[244:245], v251 offset0:56 offset1:56
	v_add_f32_e32 v45, v45, v110
	v_add_f32_e32 v111, v111, v112
	v_add_f32_e32 v45, v45, v111
	s_waitcnt lgkmcnt(7)
	v_fmac_f32_dpp v33, -v230, v4 quad_perm:[0,0,0,0] row_mask:0xf bank_mask:0xf
	v_mul_f32_dpp v110, -v230, v2 quad_perm:[1,1,1,1] row_mask:0xf bank_mask:0xf
	v_mul_f32_dpp v111, -v230, v3 quad_perm:[2,2,2,2] row_mask:0xf bank_mask:0xf
	v_mul_f32_dpp v112, -v230, v5 quad_perm:[3,3,3,3] row_mask:0xf bank_mask:0xf
	v_fmac_f32_dpp v33, -v231, v6 quad_perm:[0,0,0,0] row_mask:0xf bank_mask:0xf
	v_fmac_f32_dpp v110, -v231, v7 quad_perm:[1,1,1,1] row_mask:0xf bank_mask:0xf
	v_fmac_f32_dpp v111, -v231, v8 quad_perm:[2,2,2,2] row_mask:0xf bank_mask:0xf
	v_fmac_f32_dpp v112, -v231, v9 quad_perm:[3,3,3,3] row_mask:0xf bank_mask:0xf
	v_add_u32_e32 v251, 0x110, v251
	ds_read2_b32 v[230:231], v251 offset0:0 offset1:4
	s_waitcnt lgkmcnt(7)
	v_fmac_f32_dpp v33, -v232, v10 quad_perm:[0,0,0,0] row_mask:0xf bank_mask:0xf
	v_fmac_f32_dpp v110, -v232, v12 quad_perm:[1,1,1,1] row_mask:0xf bank_mask:0xf
	v_fmac_f32_dpp v111, -v232, v13 quad_perm:[2,2,2,2] row_mask:0xf bank_mask:0xf
	v_fmac_f32_dpp v112, -v232, v14 quad_perm:[3,3,3,3] row_mask:0xf bank_mask:0xf
	v_fmac_f32_dpp v33, -v233, v15 quad_perm:[0,0,0,0] row_mask:0xf bank_mask:0xf
	v_fmac_f32_dpp v110, -v233, v17 quad_perm:[1,1,1,1] row_mask:0xf bank_mask:0xf
	v_fmac_f32_dpp v111, -v233, v18 quad_perm:[2,2,2,2] row_mask:0xf bank_mask:0xf
	v_fmac_f32_dpp v112, -v233, v19 quad_perm:[3,3,3,3] row_mask:0xf bank_mask:0xf
	ds_read2_b32 v[232:233], v251 offset0:8 offset1:12
	s_waitcnt lgkmcnt(7)
	v_fmac_f32_dpp v33, -v234, v21 quad_perm:[0,0,0,0] row_mask:0xf bank_mask:0xf
	v_fmac_f32_dpp v110, -v234, v22 quad_perm:[1,1,1,1] row_mask:0xf bank_mask:0xf
	v_fmac_f32_dpp v111, -v234, v23 quad_perm:[2,2,2,2] row_mask:0xf bank_mask:0xf
	v_fmac_f32_dpp v112, -v234, v25 quad_perm:[3,3,3,3] row_mask:0xf bank_mask:0xf
	v_fmac_f32_dpp v33, -v235, v26 quad_perm:[0,0,0,0] row_mask:0xf bank_mask:0xf
	v_fmac_f32_dpp v110, -v235, v28 quad_perm:[1,1,1,1] row_mask:0xf bank_mask:0xf
	v_fmac_f32_dpp v111, -v235, v29 quad_perm:[2,2,2,2] row_mask:0xf bank_mask:0xf
	v_fmac_f32_dpp v112, -v235, v31 quad_perm:[3,3,3,3] row_mask:0xf bank_mask:0xf
	ds_read2_b32 v[234:235], v251 offset0:16 offset1:20
	s_waitcnt lgkmcnt(7)
	v_fmac_f32_dpp v33, -v236, v32 quad_perm:[0,0,0,0] row_mask:0xf bank_mask:0xf
	v_fmac_f32_dpp v110, -v236, v43 quad_perm:[1,1,1,1] row_mask:0xf bank_mask:0xf
	v_fmac_f32_dpp v111, -v236, v47 quad_perm:[2,2,2,2] row_mask:0xf bank_mask:0xf
	v_fmac_f32_dpp v112, -v236, v50 quad_perm:[3,3,3,3] row_mask:0xf bank_mask:0xf
	v_fmac_f32_dpp v33, -v237, v52 quad_perm:[0,0,0,0] row_mask:0xf bank_mask:0xf
	v_fmac_f32_dpp v110, -v237, v81 quad_perm:[1,1,1,1] row_mask:0xf bank_mask:0xf
	v_fmac_f32_dpp v111, -v237, v82 quad_perm:[2,2,2,2] row_mask:0xf bank_mask:0xf
	v_fmac_f32_dpp v112, -v237, v84 quad_perm:[3,3,3,3] row_mask:0xf bank_mask:0xf
	ds_read2_b32 v[236:237], v251 offset0:24 offset1:28
	s_waitcnt lgkmcnt(7)
	v_fmac_f32_dpp v33, -v238, v86 quad_perm:[0,0,0,0] row_mask:0xf bank_mask:0xf
	v_fmac_f32_dpp v110, -v238, v88 quad_perm:[1,1,1,1] row_mask:0xf bank_mask:0xf
	v_fmac_f32_dpp v111, -v238, v90 quad_perm:[2,2,2,2] row_mask:0xf bank_mask:0xf
	v_fmac_f32_dpp v112, -v238, v92 quad_perm:[3,3,3,3] row_mask:0xf bank_mask:0xf
	v_fmac_f32_dpp v33, -v239, v94 quad_perm:[0,0,0,0] row_mask:0xf bank_mask:0xf
	v_fmac_f32_dpp v110, -v239, v96 quad_perm:[1,1,1,1] row_mask:0xf bank_mask:0xf
	v_fmac_f32_dpp v111, -v239, v98 quad_perm:[2,2,2,2] row_mask:0xf bank_mask:0xf
	v_fmac_f32_dpp v112, -v239, v100 quad_perm:[3,3,3,3] row_mask:0xf bank_mask:0xf
	ds_read2_b32 v[238:239], v251 offset0:32 offset1:36
	s_waitcnt lgkmcnt(7)
	v_fmac_f32_dpp v33, -v240, v103 quad_perm:[0,0,0,0] row_mask:0xf bank_mask:0xf
	v_fmac_f32_dpp v110, -v240, v105 quad_perm:[1,1,1,1] row_mask:0xf bank_mask:0xf
	v_fmac_f32_dpp v111, -v240, v104 quad_perm:[2,2,2,2] row_mask:0xf bank_mask:0xf
	v_fmac_f32_dpp v112, -v240, v102 quad_perm:[3,3,3,3] row_mask:0xf bank_mask:0xf
	v_fmac_f32_dpp v33, -v241, v101 quad_perm:[0,0,0,0] row_mask:0xf bank_mask:0xf
	v_fmac_f32_dpp v110, -v241, v99 quad_perm:[1,1,1,1] row_mask:0xf bank_mask:0xf
	v_fmac_f32_dpp v111, -v241, v97 quad_perm:[2,2,2,2] row_mask:0xf bank_mask:0xf
	v_fmac_f32_dpp v112, -v241, v95 quad_perm:[3,3,3,3] row_mask:0xf bank_mask:0xf
	ds_read2_b32 v[240:241], v251 offset0:40 offset1:44
	s_waitcnt lgkmcnt(7)
	v_fmac_f32_dpp v33, -v242, v93 quad_perm:[0,0,0,0] row_mask:0xf bank_mask:0xf
	v_fmac_f32_dpp v110, -v242, v91 quad_perm:[1,1,1,1] row_mask:0xf bank_mask:0xf
	v_fmac_f32_dpp v111, -v242, v89 quad_perm:[2,2,2,2] row_mask:0xf bank_mask:0xf
	v_fmac_f32_dpp v112, -v242, v87 quad_perm:[3,3,3,3] row_mask:0xf bank_mask:0xf
	v_fmac_f32_dpp v33, -v243, v85 quad_perm:[0,0,0,0] row_mask:0xf bank_mask:0xf
	v_fmac_f32_dpp v110, -v243, v83 quad_perm:[1,1,1,1] row_mask:0xf bank_mask:0xf
	v_fmac_f32_dpp v111, -v243, v53 quad_perm:[2,2,2,2] row_mask:0xf bank_mask:0xf
	v_fmac_f32_dpp v112, -v243, v51 quad_perm:[3,3,3,3] row_mask:0xf bank_mask:0xf
	ds_read2_b32 v[242:243], v251 offset0:48 offset1:52
	s_waitcnt lgkmcnt(7)
; DI void phase_gdn_c1(const Ctx& c) {
;     ...
; #pragma unroll
;       for (int i = 1; i < 64; ++i) {
;         float s0 = sol[i], s1 = 0.f, s2 = 0.f, s3 = 0.f;
; #pragma unroll
;         for (int m = 0; m < i; ++m) {
;           const float t_ = Am[i * 68 + m] * sol[m];
;           if ((m & 3) == 0) s0 -= t_; else if ((m & 3) == 1) s1 -= t_; else if ((m & 3) == 2) s2 -= t_; else s3 -= t_;
;         }
;         sol[i] = (s0 + s1) + (s2 + s3);
;       }
	v_fmac_f32_dpp v33, -v244, v45 quad_perm:[0,0,0,0] row_mask:0xf bank_mask:0xf
	ds_read2_b32 v[244:245], v251 offset0:56 offset1:56
	v_add_f32_e32 v33, v33, v110
	v_add_f32_e32 v111, v111, v112
	v_add_f32_e32 v33, v33, v111
	s_waitcnt lgkmcnt(7)
	v_fmac_f32_dpp v30, -v230, v4 quad_perm:[0,0,0,0] row_mask:0xf bank_mask:0xf
	v_mul_f32_dpp v110, -v230, v2 quad_perm:[1,1,1,1] row_mask:0xf bank_mask:0xf
	v_mul_f32_dpp v111, -v230, v3 quad_perm:[2,2,2,2] row_mask:0xf bank_mask:0xf
	v_mul_f32_dpp v112, -v230, v5 quad_perm:[3,3,3,3] row_mask:0xf bank_mask:0xf
	v_fmac_f32_dpp v30, -v231, v6 quad_perm:[0,0,0,0] row_mask:0xf bank_mask:0xf
	v_fmac_f32_dpp v110, -v231, v7 quad_perm:[1,1,1,1] row_mask:0xf bank_mask:0xf
	v_fmac_f32_dpp v111, -v231, v8 quad_perm:[2,2,2,2] row_mask:0xf bank_mask:0xf
	v_fmac_f32_dpp v112, -v231, v9 quad_perm:[3,3,3,3] row_mask:0xf bank_mask:0xf
	v_add_u32_e32 v251, 0x110, v251
	ds_read2_b32 v[230:231], v251 offset0:0 offset1:4
	s_waitcnt lgkmcnt(7)
	v_fmac_f32_dpp v30, -v232, v10 quad_perm:[0,0,0,0] row_mask:0xf bank_mask:0xf
	v_fmac_f32_dpp v110, -v232, v12 quad_perm:[1,1,1,1] row_mask:0xf bank_mask:0xf
	v_fmac_f32_dpp v111, -v232, v13 quad_perm:[2,2,2,2] row_mask:0xf bank_mask:0xf
	v_fmac_f32_dpp v112, -v232, v14 quad_perm:[3,3,3,3] row_mask:0xf bank_mask:0xf
	v_fmac_f32_dpp v30, -v233, v15 quad_perm:[0,0,0,0] row_mask:0xf bank_mask:0xf
	v_fmac_f32_dpp v110, -v233, v17 quad_perm:[1,1,1,1] row_mask:0xf bank_mask:0xf
	v_fmac_f32_dpp v111, -v233, v18 quad_perm:[2,2,2,2] row_mask:0xf bank_mask:0xf
	v_fmac_f32_dpp v112, -v233, v19 quad_perm:[3,3,3,3] row_mask:0xf bank_mask:0xf
	ds_read2_b32 v[232:233], v251 offset0:8 offset1:12
	s_waitcnt lgkmcnt(7)
	v_fmac_f32_dpp v30, -v234, v21 quad_perm:[0,0,0,0] row_mask:0xf bank_mask:0xf
	v_fmac_f32_dpp v110, -v234, v22 quad_perm:[1,1,1,1] row_mask:0xf bank_mask:0xf
	v_fmac_f32_dpp v111, -v234, v23 quad_perm:[2,2,2,2] row_mask:0xf bank_mask:0xf
	v_fmac_f32_dpp v112, -v234, v25 quad_perm:[3,3,3,3] row_mask:0xf bank_mask:0xf
	v_fmac_f32_dpp v30, -v235, v26 quad_perm:[0,0,0,0] row_mask:0xf bank_mask:0xf
	v_fmac_f32_dpp v110, -v235, v28 quad_perm:[1,1,1,1] row_mask:0xf bank_mask:0xf
	v_fmac_f32_dpp v111, -v235, v29 quad_perm:[2,2,2,2] row_mask:0xf bank_mask:0xf
	v_fmac_f32_dpp v112, -v235, v31 quad_perm:[3,3,3,3] row_mask:0xf bank_mask:0xf
	ds_read2_b32 v[234:235], v251 offset0:16 offset1:20
	s_waitcnt lgkmcnt(7)
	v_fmac_f32_dpp v30, -v236, v32 quad_perm:[0,0,0,0] row_mask:0xf bank_mask:0xf
	v_fmac_f32_dpp v110, -v236, v43 quad_perm:[1,1,1,1] row_mask:0xf bank_mask:0xf
	v_fmac_f32_dpp v111, -v236, v47 quad_perm:[2,2,2,2] row_mask:0xf bank_mask:0xf
	v_fmac_f32_dpp v112, -v236, v50 quad_perm:[3,3,3,3] row_mask:0xf bank_mask:0xf
	v_fmac_f32_dpp v30, -v237, v52 quad_perm:[0,0,0,0] row_mask:0xf bank_mask:0xf
	v_fmac_f32_dpp v110, -v237, v81 quad_perm:[1,1,1,1] row_mask:0xf bank_mask:0xf
	v_fmac_f32_dpp v111, -v237, v82 quad_perm:[2,2,2,2] row_mask:0xf bank_mask:0xf
	v_fmac_f32_dpp v112, -v237, v84 quad_perm:[3,3,3,3] row_mask:0xf bank_mask:0xf
	ds_read2_b32 v[236:237], v251 offset0:24 offset1:28
	s_waitcnt lgkmcnt(7)
	v_fmac_f32_dpp v30, -v238, v86 quad_perm:[0,0,0,0] row_mask:0xf bank_mask:0xf
	v_fmac_f32_dpp v110, -v238, v88 quad_perm:[1,1,1,1] row_mask:0xf bank_mask:0xf
	v_fmac_f32_dpp v111, -v238, v90 quad_perm:[2,2,2,2] row_mask:0xf bank_mask:0xf
	v_fmac_f32_dpp v112, -v238, v92 quad_perm:[3,3,3,3] row_mask:0xf bank_mask:0xf
	v_fmac_f32_dpp v30, -v239, v94 quad_perm:[0,0,0,0] row_mask:0xf bank_mask:0xf
	v_fmac_f32_dpp v110, -v239, v96 quad_perm:[1,1,1,1] row_mask:0xf bank_mask:0xf
	v_fmac_f32_dpp v111, -v239, v98 quad_perm:[2,2,2,2] row_mask:0xf bank_mask:0xf
	v_fmac_f32_dpp v112, -v239, v100 quad_perm:[3,3,3,3] row_mask:0xf bank_mask:0xf
	ds_read2_b32 v[238:239], v251 offset0:32 offset1:36
	s_waitcnt lgkmcnt(7)
	v_fmac_f32_dpp v30, -v240, v103 quad_perm:[0,0,0,0] row_mask:0xf bank_mask:0xf
	v_fmac_f32_dpp v110, -v240, v105 quad_perm:[1,1,1,1] row_mask:0xf bank_mask:0xf
	v_fmac_f32_dpp v111, -v240, v104 quad_perm:[2,2,2,2] row_mask:0xf bank_mask:0xf
	v_fmac_f32_dpp v112, -v240, v102 quad_perm:[3,3,3,3] row_mask:0xf bank_mask:0xf
	v_fmac_f32_dpp v30, -v241, v101 quad_perm:[0,0,0,0] row_mask:0xf bank_mask:0xf
	v_fmac_f32_dpp v110, -v241, v99 quad_perm:[1,1,1,1] row_mask:0xf bank_mask:0xf
	v_fmac_f32_dpp v111, -v241, v97 quad_perm:[2,2,2,2] row_mask:0xf bank_mask:0xf
	v_fmac_f32_dpp v112, -v241, v95 quad_perm:[3,3,3,3] row_mask:0xf bank_mask:0xf
	ds_read2_b32 v[240:241], v251 offset0:40 offset1:44
	s_waitcnt lgkmcnt(7)
	v_fmac_f32_dpp v30, -v242, v93 quad_perm:[0,0,0,0] row_mask:0xf bank_mask:0xf
	v_fmac_f32_dpp v110, -v242, v91 quad_perm:[1,1,1,1] row_mask:0xf bank_mask:0xf
	v_fmac_f32_dpp v111, -v242, v89 quad_perm:[2,2,2,2] row_mask:0xf bank_mask:0xf
	v_fmac_f32_dpp v112, -v242, v87 quad_perm:[3,3,3,3] row_mask:0xf bank_mask:0xf
	v_fmac_f32_dpp v30, -v243, v85 quad_perm:[0,0,0,0] row_mask:0xf bank_mask:0xf
	v_fmac_f32_dpp v110, -v243, v83 quad_perm:[1,1,1,1] row_mask:0xf bank_mask:0xf
	v_fmac_f32_dpp v111, -v243, v53 quad_perm:[2,2,2,2] row_mask:0xf bank_mask:0xf
	v_fmac_f32_dpp v112, -v243, v51 quad_perm:[3,3,3,3] row_mask:0xf bank_mask:0xf
	ds_read2_b32 v[242:243], v251 offset0:48 offset1:52
	s_waitcnt lgkmcnt(7)
	v_fmac_f32_dpp v30, -v244, v45 quad_perm:[0,0,0,0] row_mask:0xf bank_mask:0xf
	v_fmac_f32_dpp v110, -v244, v33 quad_perm:[1,1,1,1] row_mask:0xf bank_mask:0xf
	ds_read2_b32 v[244:245], v251 offset0:56 offset1:56
	v_add_f32_e32 v30, v30, v110
	v_add_f32_e32 v111, v111, v112
	v_add_f32_e32 v30, v30, v111
	s_waitcnt lgkmcnt(7)
; DI void phase_gdn_c1(const Ctx& c) {
;     ...
; #pragma unroll
;       for (int i = 1; i < 64; ++i) {
;         float s0 = sol[i], s1 = 0.f, s2 = 0.f, s3 = 0.f;
; #pragma unroll
;         for (int m = 0; m < i; ++m) {
;           const float t_ = Am[i * 68 + m] * sol[m];
;           if ((m & 3) == 0) s0 -= t_; else if ((m & 3) == 1) s1 -= t_; else if ((m & 3) == 2) s2 -= t_; else s3 -= t_;
;         }
;         sol[i] = (s0 + s1) + (s2 + s3);
;       }
	v_fmac_f32_dpp v27, -v230, v4 quad_perm:[0,0,0,0] row_mask:0xf bank_mask:0xf
	v_mul_f32_dpp v110, -v230, v2 quad_perm:[1,1,1,1] row_mask:0xf bank_mask:0xf
	v_mul_f32_dpp v111, -v230, v3 quad_perm:[2,2,2,2] row_mask:0xf bank_mask:0xf
	v_mul_f32_dpp v112, -v230, v5 quad_perm:[3,3,3,3] row_mask:0xf bank_mask:0xf
	v_fmac_f32_dpp v27, -v231, v6 quad_perm:[0,0,0,0] row_mask:0xf bank_mask:0xf
	v_fmac_f32_dpp v110, -v231, v7 quad_perm:[1,1,1,1] row_mask:0xf bank_mask:0xf
	v_fmac_f32_dpp v111, -v231, v8 quad_perm:[2,2,2,2] row_mask:0xf bank_mask:0xf
	v_fmac_f32_dpp v112, -v231, v9 quad_perm:[3,3,3,3] row_mask:0xf bank_mask:0xf
	v_add_u32_e32 v251, 0x110, v251
	ds_read2_b32 v[230:231], v251 offset0:0 offset1:4
	s_waitcnt lgkmcnt(7)
	v_fmac_f32_dpp v27, -v232, v10 quad_perm:[0,0,0,0] row_mask:0xf bank_mask:0xf
	v_fmac_f32_dpp v110, -v232, v12 quad_perm:[1,1,1,1] row_mask:0xf bank_mask:0xf
	v_fmac_f32_dpp v111, -v232, v13 quad_perm:[2,2,2,2] row_mask:0xf bank_mask:0xf
	v_fmac_f32_dpp v112, -v232, v14 quad_perm:[3,3,3,3] row_mask:0xf bank_mask:0xf
	v_fmac_f32_dpp v27, -v233, v15 quad_perm:[0,0,0,0] row_mask:0xf bank_mask:0xf
	v_fmac_f32_dpp v110, -v233, v17 quad_perm:[1,1,1,1] row_mask:0xf bank_mask:0xf
	v_fmac_f32_dpp v111, -v233, v18 quad_perm:[2,2,2,2] row_mask:0xf bank_mask:0xf
	v_fmac_f32_dpp v112, -v233, v19 quad_perm:[3,3,3,3] row_mask:0xf bank_mask:0xf
	ds_read2_b32 v[232:233], v251 offset0:8 offset1:12
	s_waitcnt lgkmcnt(7)
	v_fmac_f32_dpp v27, -v234, v21 quad_perm:[0,0,0,0] row_mask:0xf bank_mask:0xf
	v_fmac_f32_dpp v110, -v234, v22 quad_perm:[1,1,1,1] row_mask:0xf bank_mask:0xf
	v_fmac_f32_dpp v111, -v234, v23 quad_perm:[2,2,2,2] row_mask:0xf bank_mask:0xf
	v_fmac_f32_dpp v112, -v234, v25 quad_perm:[3,3,3,3] row_mask:0xf bank_mask:0xf
	v_fmac_f32_dpp v27, -v235, v26 quad_perm:[0,0,0,0] row_mask:0xf bank_mask:0xf
	v_fmac_f32_dpp v110, -v235, v28 quad_perm:[1,1,1,1] row_mask:0xf bank_mask:0xf
	v_fmac_f32_dpp v111, -v235, v29 quad_perm:[2,2,2,2] row_mask:0xf bank_mask:0xf
	v_fmac_f32_dpp v112, -v235, v31 quad_perm:[3,3,3,3] row_mask:0xf bank_mask:0xf
	ds_read2_b32 v[234:235], v251 offset0:16 offset1:20
	s_waitcnt lgkmcnt(7)
	v_fmac_f32_dpp v27, -v236, v32 quad_perm:[0,0,0,0] row_mask:0xf bank_mask:0xf
	v_fmac_f32_dpp v110, -v236, v43 quad_perm:[1,1,1,1] row_mask:0xf bank_mask:0xf
	v_fmac_f32_dpp v111, -v236, v47 quad_perm:[2,2,2,2] row_mask:0xf bank_mask:0xf
	v_fmac_f32_dpp v112, -v236, v50 quad_perm:[3,3,3,3] row_mask:0xf bank_mask:0xf
	v_fmac_f32_dpp v27, -v237, v52 quad_perm:[0,0,0,0] row_mask:0xf bank_mask:0xf
	v_fmac_f32_dpp v110, -v237, v81 quad_perm:[1,1,1,1] row_mask:0xf bank_mask:0xf
	v_fmac_f32_dpp v111, -v237, v82 quad_perm:[2,2,2,2] row_mask:0xf bank_mask:0xf
	v_fmac_f32_dpp v112, -v237, v84 quad_perm:[3,3,3,3] row_mask:0xf bank_mask:0xf
	ds_read2_b32 v[236:237], v251 offset0:24 offset1:28
	s_waitcnt lgkmcnt(7)
	v_fmac_f32_dpp v27, -v238, v86 quad_perm:[0,0,0,0] row_mask:0xf bank_mask:0xf
	v_fmac_f32_dpp v110, -v238, v88 quad_perm:[1,1,1,1] row_mask:0xf bank_mask:0xf
	v_fmac_f32_dpp v111, -v238, v90 quad_perm:[2,2,2,2] row_mask:0xf bank_mask:0xf
	v_fmac_f32_dpp v112, -v238, v92 quad_perm:[3,3,3,3] row_mask:0xf bank_mask:0xf
	v_fmac_f32_dpp v27, -v239, v94 quad_perm:[0,0,0,0] row_mask:0xf bank_mask:0xf
	v_fmac_f32_dpp v110, -v239, v96 quad_perm:[1,1,1,1] row_mask:0xf bank_mask:0xf
	v_fmac_f32_dpp v111, -v239, v98 quad_perm:[2,2,2,2] row_mask:0xf bank_mask:0xf
	v_fmac_f32_dpp v112, -v239, v100 quad_perm:[3,3,3,3] row_mask:0xf bank_mask:0xf
	ds_read2_b32 v[238:239], v251 offset0:32 offset1:36
	s_waitcnt lgkmcnt(7)
	v_fmac_f32_dpp v27, -v240, v103 quad_perm:[0,0,0,0] row_mask:0xf bank_mask:0xf
	v_fmac_f32_dpp v110, -v240, v105 quad_perm:[1,1,1,1] row_mask:0xf bank_mask:0xf
	v_fmac_f32_dpp v111, -v240, v104 quad_perm:[2,2,2,2] row_mask:0xf bank_mask:0xf
	v_fmac_f32_dpp v112, -v240, v102 quad_perm:[3,3,3,3] row_mask:0xf bank_mask:0xf
	v_fmac_f32_dpp v27, -v241, v101 quad_perm:[0,0,0,0] row_mask:0xf bank_mask:0xf
	v_fmac_f32_dpp v110, -v241, v99 quad_perm:[1,1,1,1] row_mask:0xf bank_mask:0xf
	v_fmac_f32_dpp v111, -v241, v97 quad_perm:[2,2,2,2] row_mask:0xf bank_mask:0xf
	v_fmac_f32_dpp v112, -v241, v95 quad_perm:[3,3,3,3] row_mask:0xf bank_mask:0xf
	ds_read2_b32 v[240:241], v251 offset0:40 offset1:44
	s_waitcnt lgkmcnt(7)
	v_fmac_f32_dpp v27, -v242, v93 quad_perm:[0,0,0,0] row_mask:0xf bank_mask:0xf
	v_fmac_f32_dpp v110, -v242, v91 quad_perm:[1,1,1,1] row_mask:0xf bank_mask:0xf
	v_fmac_f32_dpp v111, -v242, v89 quad_perm:[2,2,2,2] row_mask:0xf bank_mask:0xf
	v_fmac_f32_dpp v112, -v242, v87 quad_perm:[3,3,3,3] row_mask:0xf bank_mask:0xf
	v_fmac_f32_dpp v27, -v243, v85 quad_perm:[0,0,0,0] row_mask:0xf bank_mask:0xf
	v_fmac_f32_dpp v110, -v243, v83 quad_perm:[1,1,1,1] row_mask:0xf bank_mask:0xf
	v_fmac_f32_dpp v111, -v243, v53 quad_perm:[2,2,2,2] row_mask:0xf bank_mask:0xf
	v_fmac_f32_dpp v112, -v243, v51 quad_perm:[3,3,3,3] row_mask:0xf bank_mask:0xf
	ds_read2_b32 v[242:243], v251 offset0:48 offset1:52
	s_waitcnt lgkmcnt(7)
	v_fmac_f32_dpp v27, -v244, v45 quad_perm:[0,0,0,0] row_mask:0xf bank_mask:0xf
	v_fmac_f32_dpp v110, -v244, v33 quad_perm:[1,1,1,1] row_mask:0xf bank_mask:0xf
	v_fmac_f32_dpp v111, -v244, v30 quad_perm:[2,2,2,2] row_mask:0xf bank_mask:0xf
	ds_read2_b32 v[244:245], v251 offset0:56 offset1:56
	v_add_f32_e32 v27, v27, v110
	v_add_f32_e32 v111, v111, v112
	v_add_f32_e32 v27, v27, v111
	s_waitcnt lgkmcnt(7)
; DI void phase_gdn_c1(const Ctx& c) {
;     ...
; #pragma unroll
;       for (int i = 1; i < 64; ++i) {
;         float s0 = sol[i], s1 = 0.f, s2 = 0.f, s3 = 0.f;
; #pragma unroll
;         for (int m = 0; m < i; ++m) {
;           const float t_ = Am[i * 68 + m] * sol[m];
;           if ((m & 3) == 0) s0 -= t_; else if ((m & 3) == 1) s1 -= t_; else if ((m & 3) == 2) s2 -= t_; else s3 -= t_;
;         }
;         sol[i] = (s0 + s1) + (s2 + s3);
;       }
	v_fmac_f32_dpp v24, -v230, v4 quad_perm:[0,0,0,0] row_mask:0xf bank_mask:0xf
	v_mul_f32_dpp v110, -v230, v2 quad_perm:[1,1,1,1] row_mask:0xf bank_mask:0xf
	v_mul_f32_dpp v111, -v230, v3 quad_perm:[2,2,2,2] row_mask:0xf bank_mask:0xf
	v_mul_f32_dpp v112, -v230, v5 quad_perm:[3,3,3,3] row_mask:0xf bank_mask:0xf
	v_fmac_f32_dpp v24, -v231, v6 quad_perm:[0,0,0,0] row_mask:0xf bank_mask:0xf
	v_fmac_f32_dpp v110, -v231, v7 quad_perm:[1,1,1,1] row_mask:0xf bank_mask:0xf
	v_fmac_f32_dpp v111, -v231, v8 quad_perm:[2,2,2,2] row_mask:0xf bank_mask:0xf
	v_fmac_f32_dpp v112, -v231, v9 quad_perm:[3,3,3,3] row_mask:0xf bank_mask:0xf
	v_add_u32_e32 v251, 0x110, v251
	ds_read2_b32 v[230:231], v251 offset0:0 offset1:4
	s_waitcnt lgkmcnt(7)
	v_fmac_f32_dpp v24, -v232, v10 quad_perm:[0,0,0,0] row_mask:0xf bank_mask:0xf
	v_fmac_f32_dpp v110, -v232, v12 quad_perm:[1,1,1,1] row_mask:0xf bank_mask:0xf
	v_fmac_f32_dpp v111, -v232, v13 quad_perm:[2,2,2,2] row_mask:0xf bank_mask:0xf
	v_fmac_f32_dpp v112, -v232, v14 quad_perm:[3,3,3,3] row_mask:0xf bank_mask:0xf
	v_fmac_f32_dpp v24, -v233, v15 quad_perm:[0,0,0,0] row_mask:0xf bank_mask:0xf
	v_fmac_f32_dpp v110, -v233, v17 quad_perm:[1,1,1,1] row_mask:0xf bank_mask:0xf
	v_fmac_f32_dpp v111, -v233, v18 quad_perm:[2,2,2,2] row_mask:0xf bank_mask:0xf
	v_fmac_f32_dpp v112, -v233, v19 quad_perm:[3,3,3,3] row_mask:0xf bank_mask:0xf
	ds_read2_b32 v[232:233], v251 offset0:8 offset1:12
	s_waitcnt lgkmcnt(7)
	v_fmac_f32_dpp v24, -v234, v21 quad_perm:[0,0,0,0] row_mask:0xf bank_mask:0xf
	v_fmac_f32_dpp v110, -v234, v22 quad_perm:[1,1,1,1] row_mask:0xf bank_mask:0xf
	v_fmac_f32_dpp v111, -v234, v23 quad_perm:[2,2,2,2] row_mask:0xf bank_mask:0xf
	v_fmac_f32_dpp v112, -v234, v25 quad_perm:[3,3,3,3] row_mask:0xf bank_mask:0xf
	v_fmac_f32_dpp v24, -v235, v26 quad_perm:[0,0,0,0] row_mask:0xf bank_mask:0xf
	v_fmac_f32_dpp v110, -v235, v28 quad_perm:[1,1,1,1] row_mask:0xf bank_mask:0xf
	v_fmac_f32_dpp v111, -v235, v29 quad_perm:[2,2,2,2] row_mask:0xf bank_mask:0xf
	v_fmac_f32_dpp v112, -v235, v31 quad_perm:[3,3,3,3] row_mask:0xf bank_mask:0xf
	ds_read2_b32 v[234:235], v251 offset0:16 offset1:20
	s_waitcnt lgkmcnt(7)
	v_fmac_f32_dpp v24, -v236, v32 quad_perm:[0,0,0,0] row_mask:0xf bank_mask:0xf
	v_fmac_f32_dpp v110, -v236, v43 quad_perm:[1,1,1,1] row_mask:0xf bank_mask:0xf
	v_fmac_f32_dpp v111, -v236, v47 quad_perm:[2,2,2,2] row_mask:0xf bank_mask:0xf
	v_fmac_f32_dpp v112, -v236, v50 quad_perm:[3,3,3,3] row_mask:0xf bank_mask:0xf
	v_fmac_f32_dpp v24, -v237, v52 quad_perm:[0,0,0,0] row_mask:0xf bank_mask:0xf
	v_fmac_f32_dpp v110, -v237, v81 quad_perm:[1,1,1,1] row_mask:0xf bank_mask:0xf
	v_fmac_f32_dpp v111, -v237, v82 quad_perm:[2,2,2,2] row_mask:0xf bank_mask:0xf
	v_fmac_f32_dpp v112, -v237, v84 quad_perm:[3,3,3,3] row_mask:0xf bank_mask:0xf
	ds_read2_b32 v[236:237], v251 offset0:24 offset1:28
	s_waitcnt lgkmcnt(7)
	v_fmac_f32_dpp v24, -v238, v86 quad_perm:[0,0,0,0] row_mask:0xf bank_mask:0xf
	v_fmac_f32_dpp v110, -v238, v88 quad_perm:[1,1,1,1] row_mask:0xf bank_mask:0xf
	v_fmac_f32_dpp v111, -v238, v90 quad_perm:[2,2,2,2] row_mask:0xf bank_mask:0xf
	v_fmac_f32_dpp v112, -v238, v92 quad_perm:[3,3,3,3] row_mask:0xf bank_mask:0xf
	v_fmac_f32_dpp v24, -v239, v94 quad_perm:[0,0,0,0] row_mask:0xf bank_mask:0xf
	v_fmac_f32_dpp v110, -v239, v96 quad_perm:[1,1,1,1] row_mask:0xf bank_mask:0xf
	v_fmac_f32_dpp v111, -v239, v98 quad_perm:[2,2,2,2] row_mask:0xf bank_mask:0xf
	v_fmac_f32_dpp v112, -v239, v100 quad_perm:[3,3,3,3] row_mask:0xf bank_mask:0xf
	ds_read2_b32 v[238:239], v251 offset0:32 offset1:36
	s_waitcnt lgkmcnt(7)
	v_fmac_f32_dpp v24, -v240, v103 quad_perm:[0,0,0,0] row_mask:0xf bank_mask:0xf
	v_fmac_f32_dpp v110, -v240, v105 quad_perm:[1,1,1,1] row_mask:0xf bank_mask:0xf
	v_fmac_f32_dpp v111, -v240, v104 quad_perm:[2,2,2,2] row_mask:0xf bank_mask:0xf
	v_fmac_f32_dpp v112, -v240, v102 quad_perm:[3,3,3,3] row_mask:0xf bank_mask:0xf
	v_fmac_f32_dpp v24, -v241, v101 quad_perm:[0,0,0,0] row_mask:0xf bank_mask:0xf
	v_fmac_f32_dpp v110, -v241, v99 quad_perm:[1,1,1,1] row_mask:0xf bank_mask:0xf
	v_fmac_f32_dpp v111, -v241, v97 quad_perm:[2,2,2,2] row_mask:0xf bank_mask:0xf
	v_fmac_f32_dpp v112, -v241, v95 quad_perm:[3,3,3,3] row_mask:0xf bank_mask:0xf
	ds_read2_b32 v[240:241], v251 offset0:40 offset1:44
	s_waitcnt lgkmcnt(7)
	v_fmac_f32_dpp v24, -v242, v93 quad_perm:[0,0,0,0] row_mask:0xf bank_mask:0xf
	v_fmac_f32_dpp v110, -v242, v91 quad_perm:[1,1,1,1] row_mask:0xf bank_mask:0xf
	v_fmac_f32_dpp v111, -v242, v89 quad_perm:[2,2,2,2] row_mask:0xf bank_mask:0xf
	v_fmac_f32_dpp v112, -v242, v87 quad_perm:[3,3,3,3] row_mask:0xf bank_mask:0xf
	v_fmac_f32_dpp v24, -v243, v85 quad_perm:[0,0,0,0] row_mask:0xf bank_mask:0xf
	v_fmac_f32_dpp v110, -v243, v83 quad_perm:[1,1,1,1] row_mask:0xf bank_mask:0xf
	v_fmac_f32_dpp v111, -v243, v53 quad_perm:[2,2,2,2] row_mask:0xf bank_mask:0xf
	v_fmac_f32_dpp v112, -v243, v51 quad_perm:[3,3,3,3] row_mask:0xf bank_mask:0xf
	ds_read2_b32 v[242:243], v251 offset0:48 offset1:52
	s_waitcnt lgkmcnt(7)
	v_fmac_f32_dpp v24, -v244, v45 quad_perm:[0,0,0,0] row_mask:0xf bank_mask:0xf
	v_fmac_f32_dpp v110, -v244, v33 quad_perm:[1,1,1,1] row_mask:0xf bank_mask:0xf
	v_fmac_f32_dpp v111, -v244, v30 quad_perm:[2,2,2,2] row_mask:0xf bank_mask:0xf
	v_fmac_f32_dpp v112, -v244, v27 quad_perm:[3,3,3,3] row_mask:0xf bank_mask:0xf
	ds_read2_b32 v[244:245], v251 offset0:56 offset1:60
	v_add_f32_e32 v24, v24, v110
	v_add_f32_e32 v111, v111, v112
	v_add_f32_e32 v24, v24, v111
	s_waitcnt lgkmcnt(7)
; DI void phase_gdn_c1(const Ctx& c) {
;     ...
; #pragma unroll
;       for (int i = 1; i < 64; ++i) {
;         float s0 = sol[i], s1 = 0.f, s2 = 0.f, s3 = 0.f;
; #pragma unroll
;         for (int m = 0; m < i; ++m) {
;           const float t_ = Am[i * 68 + m] * sol[m];
;           if ((m & 3) == 0) s0 -= t_; else if ((m & 3) == 1) s1 -= t_; else if ((m & 3) == 2) s2 -= t_; else s3 -= t_;
;         }
;         sol[i] = (s0 + s1) + (s2 + s3);
;       }
	v_fmac_f32_dpp v20, -v230, v4 quad_perm:[0,0,0,0] row_mask:0xf bank_mask:0xf
	v_mul_f32_dpp v110, -v230, v2 quad_perm:[1,1,1,1] row_mask:0xf bank_mask:0xf
	v_mul_f32_dpp v111, -v230, v3 quad_perm:[2,2,2,2] row_mask:0xf bank_mask:0xf
	v_mul_f32_dpp v112, -v230, v5 quad_perm:[3,3,3,3] row_mask:0xf bank_mask:0xf
	v_fmac_f32_dpp v20, -v231, v6 quad_perm:[0,0,0,0] row_mask:0xf bank_mask:0xf
	v_fmac_f32_dpp v110, -v231, v7 quad_perm:[1,1,1,1] row_mask:0xf bank_mask:0xf
	v_fmac_f32_dpp v111, -v231, v8 quad_perm:[2,2,2,2] row_mask:0xf bank_mask:0xf
	v_fmac_f32_dpp v112, -v231, v9 quad_perm:[3,3,3,3] row_mask:0xf bank_mask:0xf
	v_add_u32_e32 v251, 0x110, v251
	ds_read2_b32 v[230:231], v251 offset0:0 offset1:4
	s_waitcnt lgkmcnt(7)
	v_fmac_f32_dpp v20, -v232, v10 quad_perm:[0,0,0,0] row_mask:0xf bank_mask:0xf
	v_fmac_f32_dpp v110, -v232, v12 quad_perm:[1,1,1,1] row_mask:0xf bank_mask:0xf
	v_fmac_f32_dpp v111, -v232, v13 quad_perm:[2,2,2,2] row_mask:0xf bank_mask:0xf
	v_fmac_f32_dpp v112, -v232, v14 quad_perm:[3,3,3,3] row_mask:0xf bank_mask:0xf
	v_fmac_f32_dpp v20, -v233, v15 quad_perm:[0,0,0,0] row_mask:0xf bank_mask:0xf
	v_fmac_f32_dpp v110, -v233, v17 quad_perm:[1,1,1,1] row_mask:0xf bank_mask:0xf
	v_fmac_f32_dpp v111, -v233, v18 quad_perm:[2,2,2,2] row_mask:0xf bank_mask:0xf
	v_fmac_f32_dpp v112, -v233, v19 quad_perm:[3,3,3,3] row_mask:0xf bank_mask:0xf
	ds_read2_b32 v[232:233], v251 offset0:8 offset1:12
	s_waitcnt lgkmcnt(7)
	v_fmac_f32_dpp v20, -v234, v21 quad_perm:[0,0,0,0] row_mask:0xf bank_mask:0xf
	v_fmac_f32_dpp v110, -v234, v22 quad_perm:[1,1,1,1] row_mask:0xf bank_mask:0xf
	v_fmac_f32_dpp v111, -v234, v23 quad_perm:[2,2,2,2] row_mask:0xf bank_mask:0xf
	v_fmac_f32_dpp v112, -v234, v25 quad_perm:[3,3,3,3] row_mask:0xf bank_mask:0xf
	v_fmac_f32_dpp v20, -v235, v26 quad_perm:[0,0,0,0] row_mask:0xf bank_mask:0xf
	v_fmac_f32_dpp v110, -v235, v28 quad_perm:[1,1,1,1] row_mask:0xf bank_mask:0xf
	v_fmac_f32_dpp v111, -v235, v29 quad_perm:[2,2,2,2] row_mask:0xf bank_mask:0xf
	v_fmac_f32_dpp v112, -v235, v31 quad_perm:[3,3,3,3] row_mask:0xf bank_mask:0xf
	ds_read2_b32 v[234:235], v251 offset0:16 offset1:20
	s_waitcnt lgkmcnt(7)
	v_fmac_f32_dpp v20, -v236, v32 quad_perm:[0,0,0,0] row_mask:0xf bank_mask:0xf
	v_fmac_f32_dpp v110, -v236, v43 quad_perm:[1,1,1,1] row_mask:0xf bank_mask:0xf
	v_fmac_f32_dpp v111, -v236, v47 quad_perm:[2,2,2,2] row_mask:0xf bank_mask:0xf
	v_fmac_f32_dpp v112, -v236, v50 quad_perm:[3,3,3,3] row_mask:0xf bank_mask:0xf
	v_fmac_f32_dpp v20, -v237, v52 quad_perm:[0,0,0,0] row_mask:0xf bank_mask:0xf
	v_fmac_f32_dpp v110, -v237, v81 quad_perm:[1,1,1,1] row_mask:0xf bank_mask:0xf
	v_fmac_f32_dpp v111, -v237, v82 quad_perm:[2,2,2,2] row_mask:0xf bank_mask:0xf
	v_fmac_f32_dpp v112, -v237, v84 quad_perm:[3,3,3,3] row_mask:0xf bank_mask:0xf
	ds_read2_b32 v[236:237], v251 offset0:24 offset1:28
	s_waitcnt lgkmcnt(7)
	v_fmac_f32_dpp v20, -v238, v86 quad_perm:[0,0,0,0] row_mask:0xf bank_mask:0xf
	v_fmac_f32_dpp v110, -v238, v88 quad_perm:[1,1,1,1] row_mask:0xf bank_mask:0xf
	v_fmac_f32_dpp v111, -v238, v90 quad_perm:[2,2,2,2] row_mask:0xf bank_mask:0xf
	v_fmac_f32_dpp v112, -v238, v92 quad_perm:[3,3,3,3] row_mask:0xf bank_mask:0xf
	v_fmac_f32_dpp v20, -v239, v94 quad_perm:[0,0,0,0] row_mask:0xf bank_mask:0xf
	v_fmac_f32_dpp v110, -v239, v96 quad_perm:[1,1,1,1] row_mask:0xf bank_mask:0xf
	v_fmac_f32_dpp v111, -v239, v98 quad_perm:[2,2,2,2] row_mask:0xf bank_mask:0xf
	v_fmac_f32_dpp v112, -v239, v100 quad_perm:[3,3,3,3] row_mask:0xf bank_mask:0xf
	ds_read2_b32 v[238:239], v251 offset0:32 offset1:36
	s_waitcnt lgkmcnt(7)
	v_fmac_f32_dpp v20, -v240, v103 quad_perm:[0,0,0,0] row_mask:0xf bank_mask:0xf
	v_fmac_f32_dpp v110, -v240, v105 quad_perm:[1,1,1,1] row_mask:0xf bank_mask:0xf
	v_fmac_f32_dpp v111, -v240, v104 quad_perm:[2,2,2,2] row_mask:0xf bank_mask:0xf
	v_fmac_f32_dpp v112, -v240, v102 quad_perm:[3,3,3,3] row_mask:0xf bank_mask:0xf
	v_fmac_f32_dpp v20, -v241, v101 quad_perm:[0,0,0,0] row_mask:0xf bank_mask:0xf
	v_fmac_f32_dpp v110, -v241, v99 quad_perm:[1,1,1,1] row_mask:0xf bank_mask:0xf
	v_fmac_f32_dpp v111, -v241, v97 quad_perm:[2,2,2,2] row_mask:0xf bank_mask:0xf
	v_fmac_f32_dpp v112, -v241, v95 quad_perm:[3,3,3,3] row_mask:0xf bank_mask:0xf
	ds_read2_b32 v[240:241], v251 offset0:40 offset1:44
	s_waitcnt lgkmcnt(7)
	v_fmac_f32_dpp v20, -v242, v93 quad_perm:[0,0,0,0] row_mask:0xf bank_mask:0xf
	v_fmac_f32_dpp v110, -v242, v91 quad_perm:[1,1,1,1] row_mask:0xf bank_mask:0xf
	v_fmac_f32_dpp v111, -v242, v89 quad_perm:[2,2,2,2] row_mask:0xf bank_mask:0xf
	v_fmac_f32_dpp v112, -v242, v87 quad_perm:[3,3,3,3] row_mask:0xf bank_mask:0xf
	v_fmac_f32_dpp v20, -v243, v85 quad_perm:[0,0,0,0] row_mask:0xf bank_mask:0xf
	v_fmac_f32_dpp v110, -v243, v83 quad_perm:[1,1,1,1] row_mask:0xf bank_mask:0xf
	v_fmac_f32_dpp v111, -v243, v53 quad_perm:[2,2,2,2] row_mask:0xf bank_mask:0xf
	v_fmac_f32_dpp v112, -v243, v51 quad_perm:[3,3,3,3] row_mask:0xf bank_mask:0xf
	ds_read2_b32 v[242:243], v251 offset0:48 offset1:52
	s_waitcnt lgkmcnt(7)
	v_fmac_f32_dpp v20, -v244, v45 quad_perm:[0,0,0,0] row_mask:0xf bank_mask:0xf
	v_fmac_f32_dpp v110, -v244, v33 quad_perm:[1,1,1,1] row_mask:0xf bank_mask:0xf
	v_fmac_f32_dpp v111, -v244, v30 quad_perm:[2,2,2,2] row_mask:0xf bank_mask:0xf
	v_fmac_f32_dpp v112, -v244, v27 quad_perm:[3,3,3,3] row_mask:0xf bank_mask:0xf
	v_fmac_f32_dpp v20, -v245, v24 quad_perm:[0,0,0,0] row_mask:0xf bank_mask:0xf
	ds_read2_b32 v[244:245], v251 offset0:56 offset1:60
	v_add_f32_e32 v20, v20, v110
	v_add_f32_e32 v111, v111, v112
	v_add_f32_e32 v20, v20, v111
	s_waitcnt lgkmcnt(7)
; DI void phase_gdn_c1(const Ctx& c) {
;     ...
; #pragma unroll
;       for (int i = 1; i < 64; ++i) {
;         float s0 = sol[i], s1 = 0.f, s2 = 0.f, s3 = 0.f;
; #pragma unroll
;         for (int m = 0; m < i; ++m) {
;           const float t_ = Am[i * 68 + m] * sol[m];
;           if ((m & 3) == 0) s0 -= t_; else if ((m & 3) == 1) s1 -= t_; else if ((m & 3) == 2) s2 -= t_; else s3 -= t_;
;         }
;         sol[i] = (s0 + s1) + (s2 + s3);
;       }
	v_fmac_f32_dpp v16, -v230, v4 quad_perm:[0,0,0,0] row_mask:0xf bank_mask:0xf
	v_mul_f32_dpp v110, -v230, v2 quad_perm:[1,1,1,1] row_mask:0xf bank_mask:0xf
	v_mul_f32_dpp v111, -v230, v3 quad_perm:[2,2,2,2] row_mask:0xf bank_mask:0xf
	v_mul_f32_dpp v112, -v230, v5 quad_perm:[3,3,3,3] row_mask:0xf bank_mask:0xf
	v_fmac_f32_dpp v16, -v231, v6 quad_perm:[0,0,0,0] row_mask:0xf bank_mask:0xf
	v_fmac_f32_dpp v110, -v231, v7 quad_perm:[1,1,1,1] row_mask:0xf bank_mask:0xf
	v_fmac_f32_dpp v111, -v231, v8 quad_perm:[2,2,2,2] row_mask:0xf bank_mask:0xf
	v_fmac_f32_dpp v112, -v231, v9 quad_perm:[3,3,3,3] row_mask:0xf bank_mask:0xf
	v_add_u32_e32 v251, 0x110, v251
	ds_read2_b32 v[230:231], v251 offset0:0 offset1:4
	s_waitcnt lgkmcnt(7)
	v_fmac_f32_dpp v16, -v232, v10 quad_perm:[0,0,0,0] row_mask:0xf bank_mask:0xf
	v_fmac_f32_dpp v110, -v232, v12 quad_perm:[1,1,1,1] row_mask:0xf bank_mask:0xf
	v_fmac_f32_dpp v111, -v232, v13 quad_perm:[2,2,2,2] row_mask:0xf bank_mask:0xf
	v_fmac_f32_dpp v112, -v232, v14 quad_perm:[3,3,3,3] row_mask:0xf bank_mask:0xf
	v_fmac_f32_dpp v16, -v233, v15 quad_perm:[0,0,0,0] row_mask:0xf bank_mask:0xf
	v_fmac_f32_dpp v110, -v233, v17 quad_perm:[1,1,1,1] row_mask:0xf bank_mask:0xf
	v_fmac_f32_dpp v111, -v233, v18 quad_perm:[2,2,2,2] row_mask:0xf bank_mask:0xf
	v_fmac_f32_dpp v112, -v233, v19 quad_perm:[3,3,3,3] row_mask:0xf bank_mask:0xf
	ds_read2_b32 v[232:233], v251 offset0:8 offset1:12
	s_waitcnt lgkmcnt(7)
	v_fmac_f32_dpp v16, -v234, v21 quad_perm:[0,0,0,0] row_mask:0xf bank_mask:0xf
	v_fmac_f32_dpp v110, -v234, v22 quad_perm:[1,1,1,1] row_mask:0xf bank_mask:0xf
	v_fmac_f32_dpp v111, -v234, v23 quad_perm:[2,2,2,2] row_mask:0xf bank_mask:0xf
	v_fmac_f32_dpp v112, -v234, v25 quad_perm:[3,3,3,3] row_mask:0xf bank_mask:0xf
	v_fmac_f32_dpp v16, -v235, v26 quad_perm:[0,0,0,0] row_mask:0xf bank_mask:0xf
	v_fmac_f32_dpp v110, -v235, v28 quad_perm:[1,1,1,1] row_mask:0xf bank_mask:0xf
	v_fmac_f32_dpp v111, -v235, v29 quad_perm:[2,2,2,2] row_mask:0xf bank_mask:0xf
	v_fmac_f32_dpp v112, -v235, v31 quad_perm:[3,3,3,3] row_mask:0xf bank_mask:0xf
	ds_read2_b32 v[234:235], v251 offset0:16 offset1:20
	s_waitcnt lgkmcnt(7)
	v_fmac_f32_dpp v16, -v236, v32 quad_perm:[0,0,0,0] row_mask:0xf bank_mask:0xf
	v_fmac_f32_dpp v110, -v236, v43 quad_perm:[1,1,1,1] row_mask:0xf bank_mask:0xf
	v_fmac_f32_dpp v111, -v236, v47 quad_perm:[2,2,2,2] row_mask:0xf bank_mask:0xf
	v_fmac_f32_dpp v112, -v236, v50 quad_perm:[3,3,3,3] row_mask:0xf bank_mask:0xf
	v_fmac_f32_dpp v16, -v237, v52 quad_perm:[0,0,0,0] row_mask:0xf bank_mask:0xf
	v_fmac_f32_dpp v110, -v237, v81 quad_perm:[1,1,1,1] row_mask:0xf bank_mask:0xf
	v_fmac_f32_dpp v111, -v237, v82 quad_perm:[2,2,2,2] row_mask:0xf bank_mask:0xf
	v_fmac_f32_dpp v112, -v237, v84 quad_perm:[3,3,3,3] row_mask:0xf bank_mask:0xf
	ds_read2_b32 v[236:237], v251 offset0:24 offset1:28
	s_waitcnt lgkmcnt(7)
	v_fmac_f32_dpp v16, -v238, v86 quad_perm:[0,0,0,0] row_mask:0xf bank_mask:0xf
	v_fmac_f32_dpp v110, -v238, v88 quad_perm:[1,1,1,1] row_mask:0xf bank_mask:0xf
	v_fmac_f32_dpp v111, -v238, v90 quad_perm:[2,2,2,2] row_mask:0xf bank_mask:0xf
	v_fmac_f32_dpp v112, -v238, v92 quad_perm:[3,3,3,3] row_mask:0xf bank_mask:0xf
	v_fmac_f32_dpp v16, -v239, v94 quad_perm:[0,0,0,0] row_mask:0xf bank_mask:0xf
	v_fmac_f32_dpp v110, -v239, v96 quad_perm:[1,1,1,1] row_mask:0xf bank_mask:0xf
	v_fmac_f32_dpp v111, -v239, v98 quad_perm:[2,2,2,2] row_mask:0xf bank_mask:0xf
	v_fmac_f32_dpp v112, -v239, v100 quad_perm:[3,3,3,3] row_mask:0xf bank_mask:0xf
	ds_read2_b32 v[238:239], v251 offset0:32 offset1:36
	s_waitcnt lgkmcnt(7)
	v_fmac_f32_dpp v16, -v240, v103 quad_perm:[0,0,0,0] row_mask:0xf bank_mask:0xf
	v_fmac_f32_dpp v110, -v240, v105 quad_perm:[1,1,1,1] row_mask:0xf bank_mask:0xf
	v_fmac_f32_dpp v111, -v240, v104 quad_perm:[2,2,2,2] row_mask:0xf bank_mask:0xf
	v_fmac_f32_dpp v112, -v240, v102 quad_perm:[3,3,3,3] row_mask:0xf bank_mask:0xf
	v_fmac_f32_dpp v16, -v241, v101 quad_perm:[0,0,0,0] row_mask:0xf bank_mask:0xf
	v_fmac_f32_dpp v110, -v241, v99 quad_perm:[1,1,1,1] row_mask:0xf bank_mask:0xf
	v_fmac_f32_dpp v111, -v241, v97 quad_perm:[2,2,2,2] row_mask:0xf bank_mask:0xf
	v_fmac_f32_dpp v112, -v241, v95 quad_perm:[3,3,3,3] row_mask:0xf bank_mask:0xf
	ds_read2_b32 v[240:241], v251 offset0:40 offset1:44
	s_waitcnt lgkmcnt(7)
	v_fmac_f32_dpp v16, -v242, v93 quad_perm:[0,0,0,0] row_mask:0xf bank_mask:0xf
	v_fmac_f32_dpp v110, -v242, v91 quad_perm:[1,1,1,1] row_mask:0xf bank_mask:0xf
	v_fmac_f32_dpp v111, -v242, v89 quad_perm:[2,2,2,2] row_mask:0xf bank_mask:0xf
	v_fmac_f32_dpp v112, -v242, v87 quad_perm:[3,3,3,3] row_mask:0xf bank_mask:0xf
	v_fmac_f32_dpp v16, -v243, v85 quad_perm:[0,0,0,0] row_mask:0xf bank_mask:0xf
	v_fmac_f32_dpp v110, -v243, v83 quad_perm:[1,1,1,1] row_mask:0xf bank_mask:0xf
	v_fmac_f32_dpp v111, -v243, v53 quad_perm:[2,2,2,2] row_mask:0xf bank_mask:0xf
	v_fmac_f32_dpp v112, -v243, v51 quad_perm:[3,3,3,3] row_mask:0xf bank_mask:0xf
	ds_read2_b32 v[242:243], v251 offset0:48 offset1:52
	s_waitcnt lgkmcnt(7)
	v_fmac_f32_dpp v16, -v244, v45 quad_perm:[0,0,0,0] row_mask:0xf bank_mask:0xf
	v_fmac_f32_dpp v110, -v244, v33 quad_perm:[1,1,1,1] row_mask:0xf bank_mask:0xf
	v_fmac_f32_dpp v111, -v244, v30 quad_perm:[2,2,2,2] row_mask:0xf bank_mask:0xf
	v_fmac_f32_dpp v112, -v244, v27 quad_perm:[3,3,3,3] row_mask:0xf bank_mask:0xf
	v_fmac_f32_dpp v16, -v245, v24 quad_perm:[0,0,0,0] row_mask:0xf bank_mask:0xf
	v_fmac_f32_dpp v110, -v245, v20 quad_perm:[1,1,1,1] row_mask:0xf bank_mask:0xf
	ds_read2_b32 v[244:245], v251 offset0:56 offset1:60
	v_add_f32_e32 v16, v16, v110
	v_add_f32_e32 v111, v111, v112
	v_add_f32_e32 v16, v16, v111
	s_waitcnt lgkmcnt(7)
; DI void phase_gdn_c1(const Ctx& c) {
;     ...
; #pragma unroll
;       for (int i = 1; i < 64; ++i) {
;         float s0 = sol[i], s1 = 0.f, s2 = 0.f, s3 = 0.f;
; #pragma unroll
;         for (int m = 0; m < i; ++m) {
;           const float t_ = Am[i * 68 + m] * sol[m];
;           if ((m & 3) == 0) s0 -= t_; else if ((m & 3) == 1) s1 -= t_; else if ((m & 3) == 2) s2 -= t_; else s3 -= t_;
;         }
;         sol[i] = (s0 + s1) + (s2 + s3);
;       }
	v_fmac_f32_dpp v11, -v230, v4 quad_perm:[0,0,0,0] row_mask:0xf bank_mask:0xf
	v_mul_f32_dpp v110, -v230, v2 quad_perm:[1,1,1,1] row_mask:0xf bank_mask:0xf
	v_mul_f32_dpp v111, -v230, v3 quad_perm:[2,2,2,2] row_mask:0xf bank_mask:0xf
	v_mul_f32_dpp v112, -v230, v5 quad_perm:[3,3,3,3] row_mask:0xf bank_mask:0xf
	v_fmac_f32_dpp v11, -v231, v6 quad_perm:[0,0,0,0] row_mask:0xf bank_mask:0xf
	v_fmac_f32_dpp v110, -v231, v7 quad_perm:[1,1,1,1] row_mask:0xf bank_mask:0xf
	v_fmac_f32_dpp v111, -v231, v8 quad_perm:[2,2,2,2] row_mask:0xf bank_mask:0xf
	v_fmac_f32_dpp v112, -v231, v9 quad_perm:[3,3,3,3] row_mask:0xf bank_mask:0xf
	s_waitcnt lgkmcnt(6)
	v_fmac_f32_dpp v11, -v232, v10 quad_perm:[0,0,0,0] row_mask:0xf bank_mask:0xf
	v_fmac_f32_dpp v110, -v232, v12 quad_perm:[1,1,1,1] row_mask:0xf bank_mask:0xf
	v_fmac_f32_dpp v111, -v232, v13 quad_perm:[2,2,2,2] row_mask:0xf bank_mask:0xf
	v_fmac_f32_dpp v112, -v232, v14 quad_perm:[3,3,3,3] row_mask:0xf bank_mask:0xf
	v_fmac_f32_dpp v11, -v233, v15 quad_perm:[0,0,0,0] row_mask:0xf bank_mask:0xf
	v_fmac_f32_dpp v110, -v233, v17 quad_perm:[1,1,1,1] row_mask:0xf bank_mask:0xf
	v_fmac_f32_dpp v111, -v233, v18 quad_perm:[2,2,2,2] row_mask:0xf bank_mask:0xf
	v_fmac_f32_dpp v112, -v233, v19 quad_perm:[3,3,3,3] row_mask:0xf bank_mask:0xf
	s_waitcnt lgkmcnt(5)
	v_fmac_f32_dpp v11, -v234, v21 quad_perm:[0,0,0,0] row_mask:0xf bank_mask:0xf
	v_fmac_f32_dpp v110, -v234, v22 quad_perm:[1,1,1,1] row_mask:0xf bank_mask:0xf
	v_fmac_f32_dpp v111, -v234, v23 quad_perm:[2,2,2,2] row_mask:0xf bank_mask:0xf
	v_fmac_f32_dpp v112, -v234, v25 quad_perm:[3,3,3,3] row_mask:0xf bank_mask:0xf
	v_fmac_f32_dpp v11, -v235, v26 quad_perm:[0,0,0,0] row_mask:0xf bank_mask:0xf
	v_fmac_f32_dpp v110, -v235, v28 quad_perm:[1,1,1,1] row_mask:0xf bank_mask:0xf
	v_fmac_f32_dpp v111, -v235, v29 quad_perm:[2,2,2,2] row_mask:0xf bank_mask:0xf
	v_fmac_f32_dpp v112, -v235, v31 quad_perm:[3,3,3,3] row_mask:0xf bank_mask:0xf
	s_waitcnt lgkmcnt(4)
	v_fmac_f32_dpp v11, -v236, v32 quad_perm:[0,0,0,0] row_mask:0xf bank_mask:0xf
	v_fmac_f32_dpp v110, -v236, v43 quad_perm:[1,1,1,1] row_mask:0xf bank_mask:0xf
	v_fmac_f32_dpp v111, -v236, v47 quad_perm:[2,2,2,2] row_mask:0xf bank_mask:0xf
	v_fmac_f32_dpp v112, -v236, v50 quad_perm:[3,3,3,3] row_mask:0xf bank_mask:0xf
	v_fmac_f32_dpp v11, -v237, v52 quad_perm:[0,0,0,0] row_mask:0xf bank_mask:0xf
	v_fmac_f32_dpp v110, -v237, v81 quad_perm:[1,1,1,1] row_mask:0xf bank_mask:0xf
	v_fmac_f32_dpp v111, -v237, v82 quad_perm:[2,2,2,2] row_mask:0xf bank_mask:0xf
	v_fmac_f32_dpp v112, -v237, v84 quad_perm:[3,3,3,3] row_mask:0xf bank_mask:0xf
	s_waitcnt lgkmcnt(3)
	v_fmac_f32_dpp v11, -v238, v86 quad_perm:[0,0,0,0] row_mask:0xf bank_mask:0xf
	v_fmac_f32_dpp v110, -v238, v88 quad_perm:[1,1,1,1] row_mask:0xf bank_mask:0xf
	v_fmac_f32_dpp v111, -v238, v90 quad_perm:[2,2,2,2] row_mask:0xf bank_mask:0xf
	v_fmac_f32_dpp v112, -v238, v92 quad_perm:[3,3,3,3] row_mask:0xf bank_mask:0xf
	v_fmac_f32_dpp v11, -v239, v94 quad_perm:[0,0,0,0] row_mask:0xf bank_mask:0xf
	v_fmac_f32_dpp v110, -v239, v96 quad_perm:[1,1,1,1] row_mask:0xf bank_mask:0xf
	v_fmac_f32_dpp v111, -v239, v98 quad_perm:[2,2,2,2] row_mask:0xf bank_mask:0xf
	v_fmac_f32_dpp v112, -v239, v100 quad_perm:[3,3,3,3] row_mask:0xf bank_mask:0xf
	s_waitcnt lgkmcnt(2)
	v_fmac_f32_dpp v11, -v240, v103 quad_perm:[0,0,0,0] row_mask:0xf bank_mask:0xf
	v_fmac_f32_dpp v110, -v240, v105 quad_perm:[1,1,1,1] row_mask:0xf bank_mask:0xf
	v_fmac_f32_dpp v111, -v240, v104 quad_perm:[2,2,2,2] row_mask:0xf bank_mask:0xf
	v_fmac_f32_dpp v112, -v240, v102 quad_perm:[3,3,3,3] row_mask:0xf bank_mask:0xf
	v_fmac_f32_dpp v11, -v241, v101 quad_perm:[0,0,0,0] row_mask:0xf bank_mask:0xf
	v_fmac_f32_dpp v110, -v241, v99 quad_perm:[1,1,1,1] row_mask:0xf bank_mask:0xf
	v_fmac_f32_dpp v111, -v241, v97 quad_perm:[2,2,2,2] row_mask:0xf bank_mask:0xf
	v_fmac_f32_dpp v112, -v241, v95 quad_perm:[3,3,3,3] row_mask:0xf bank_mask:0xf
	s_waitcnt lgkmcnt(1)
	v_fmac_f32_dpp v11, -v242, v93 quad_perm:[0,0,0,0] row_mask:0xf bank_mask:0xf
	v_fmac_f32_dpp v110, -v242, v91 quad_perm:[1,1,1,1] row_mask:0xf bank_mask:0xf
	v_fmac_f32_dpp v111, -v242, v89 quad_perm:[2,2,2,2] row_mask:0xf bank_mask:0xf
	v_fmac_f32_dpp v112, -v242, v87 quad_perm:[3,3,3,3] row_mask:0xf bank_mask:0xf
	v_fmac_f32_dpp v11, -v243, v85 quad_perm:[0,0,0,0] row_mask:0xf bank_mask:0xf
	v_fmac_f32_dpp v110, -v243, v83 quad_perm:[1,1,1,1] row_mask:0xf bank_mask:0xf
	v_fmac_f32_dpp v111, -v243, v53 quad_perm:[2,2,2,2] row_mask:0xf bank_mask:0xf
	v_fmac_f32_dpp v112, -v243, v51 quad_perm:[3,3,3,3] row_mask:0xf bank_mask:0xf
	s_waitcnt lgkmcnt(0)
; DI void phase_gdn_c1(const Ctx& c) {
;     ...
; #pragma unroll
;       for (int i = 1; i < 64; ++i) {
;         float s0 = sol[i], s1 = 0.f, s2 = 0.f, s3 = 0.f;
; #pragma unroll
;         for (int m = 0; m < i; ++m) {
;           const float t_ = Am[i * 68 + m] * sol[m];
;           if ((m & 3) == 0) s0 -= t_; else if ((m & 3) == 1) s1 -= t_; else if ((m & 3) == 2) s2 -= t_; else s3 -= t_;
;         }
;         sol[i] = (s0 + s1) + (s2 + s3);
;       }
;       bf16* dst = ((ht < 128) ? CU : CW) + (size_t)item * 8192 + cc;
; #pragma unroll
;       for (int i = 0; i < 64; ++i) dst[i * 128] = f2bf(sol[i]);
;     }
;     if (ht < 64) GC[(size_t)item * 64 + ht] = gcs[ht];
	v_fmac_f32_dpp v11, -v244, v45 quad_perm:[0,0,0,0] row_mask:0xf bank_mask:0xf
	v_fmac_f32_dpp v110, -v244, v33 quad_perm:[1,1,1,1] row_mask:0xf bank_mask:0xf
	v_fmac_f32_dpp v111, -v244, v30 quad_perm:[2,2,2,2] row_mask:0xf bank_mask:0xf
	v_fmac_f32_dpp v112, -v244, v27 quad_perm:[3,3,3,3] row_mask:0xf bank_mask:0xf
	v_fmac_f32_dpp v11, -v245, v24 quad_perm:[0,0,0,0] row_mask:0xf bank_mask:0xf
	v_fmac_f32_dpp v110, -v245, v20 quad_perm:[1,1,1,1] row_mask:0xf bank_mask:0xf
	v_fmac_f32_dpp v111, -v245, v16 quad_perm:[2,2,2,2] row_mask:0xf bank_mask:0xf
	v_add_f32_e32 v11, v11, v110
	v_add_f32_e32 v111, v111, v112
	v_add_f32_e32 v11, v11, v111
	v_lshlrev_b64 v[106:107], 14, v[48:49]
	v_lshl_add_u64 v[106:107], v[36:37], 0, v[106:107]
	v_cvt_pk_bf16_f32 v2, v2, s0
	global_store_short v[106:107], v2, off offset:256
	v_cvt_pk_bf16_f32 v2, v3, s0
	global_store_short v[106:107], v2, off offset:512
	v_cvt_pk_bf16_f32 v2, v5, s0
	global_store_short v[106:107], v2, off offset:768
	v_cvt_pk_bf16_f32 v2, v6, s0
	global_store_short v[106:107], v2, off offset:1024
	v_cvt_pk_bf16_f32 v2, v7, s0
	global_store_short v[106:107], v2, off offset:1280
	v_cvt_pk_bf16_f32 v2, v8, s0
	global_store_short v[106:107], v2, off offset:1536
	v_cvt_pk_bf16_f32 v2, v9, s0
	global_store_short v[106:107], v2, off offset:1792
	v_cvt_pk_bf16_f32 v2, v10, s0
	global_store_short v[106:107], v2, off offset:2048
	v_cvt_pk_bf16_f32 v2, v12, s0
	global_store_short v[106:107], v2, off offset:2304
	v_cvt_pk_bf16_f32 v2, v13, s0
	global_store_short v[106:107], v2, off offset:2560
	v_cvt_pk_bf16_f32 v2, v14, s0
	global_store_short v[106:107], v2, off offset:2816
	v_cvt_pk_bf16_f32 v2, v15, s0
	global_store_short v[106:107], v2, off offset:3072
	v_cvt_pk_bf16_f32 v2, v17, s0
	global_store_short v[106:107], v2, off offset:3328
	v_cvt_pk_bf16_f32 v2, v18, s0
	global_store_short v[106:107], v2, off offset:3584
	v_cvt_pk_bf16_f32 v2, v19, s0
	global_store_short v[106:107], v2, off offset:3840
	v_add_co_u32_e64 v2, s[90:91], s38, v106
	v_cvt_pk_bf16_f32 v4, v4, s0
	s_nop 0
	v_addc_co_u32_e64 v3, s[90:91], 0, v107, s[90:91]
	s_movk_i32 s38, 0x2000
	global_store_short v[106:107], v4, off
	v_add_co_u32_e64 v4, s[90:91], s38, v106
	v_cvt_pk_bf16_f32 v6, v21, s0
	s_nop 0
	v_addc_co_u32_e64 v5, s[90:91], 0, v107, s[90:91]
	global_store_short v[4:5], v6, off offset:-4096
	v_cvt_pk_bf16_f32 v6, v22, s0
	global_store_short v[2:3], v6, off offset:256
	v_cvt_pk_bf16_f32 v6, v23, s0
	global_store_short v[2:3], v6, off offset:512
	v_cvt_pk_bf16_f32 v6, v25, s0
	global_store_short v[2:3], v6, off offset:768
	v_cvt_pk_bf16_f32 v6, v26, s0
	global_store_short v[2:3], v6, off offset:1024
	v_cvt_pk_bf16_f32 v6, v28, s0
	global_store_short v[2:3], v6, off offset:1280
	v_cvt_pk_bf16_f32 v6, v29, s0
	global_store_short v[2:3], v6, off offset:1536
	v_cvt_pk_bf16_f32 v6, v31, s0
	global_store_short v[2:3], v6, off offset:1792
	v_cvt_pk_bf16_f32 v6, v32, s0
	global_store_short v[2:3], v6, off offset:2048
	v_cvt_pk_bf16_f32 v6, v43, s0
	global_store_short v[2:3], v6, off offset:2304
	v_cvt_pk_bf16_f32 v6, v47, s0
	global_store_short v[2:3], v6, off offset:2560
	v_cvt_pk_bf16_f32 v6, v50, s0
	global_store_short v[2:3], v6, off offset:2816
	v_cvt_pk_bf16_f32 v6, v52, s0
	global_store_short v[2:3], v6, off offset:3072
	v_cvt_pk_bf16_f32 v6, v81, s0
	global_store_short v[2:3], v6, off offset:3328
	v_cvt_pk_bf16_f32 v6, v82, s0
	global_store_short v[2:3], v6, off offset:3584
	v_cvt_pk_bf16_f32 v6, v84, s0
	global_store_short v[2:3], v6, off offset:3840
	v_cvt_pk_bf16_f32 v2, v86, s0
	global_store_short v[4:5], v2, off
	v_cvt_pk_bf16_f32 v2, v88, s0
	global_store_short v[4:5], v2, off offset:256
	v_cvt_pk_bf16_f32 v2, v90, s0
	global_store_short v[4:5], v2, off offset:512
	v_cvt_pk_bf16_f32 v2, v92, s0
	global_store_short v[4:5], v2, off offset:768
	v_cvt_pk_bf16_f32 v2, v94, s0
	global_store_short v[4:5], v2, off offset:1024
	v_cvt_pk_bf16_f32 v2, v96, s0
	global_store_short v[4:5], v2, off offset:1280
	v_cvt_pk_bf16_f32 v2, v98, s0
	global_store_short v[4:5], v2, off offset:1536
	v_cvt_pk_bf16_f32 v2, v100, s0
	global_store_short v[4:5], v2, off offset:1792
	v_cvt_pk_bf16_f32 v2, v103, s0
	global_store_short v[4:5], v2, off offset:2048
	v_cvt_pk_bf16_f32 v2, v105, s0
	global_store_short v[4:5], v2, off offset:2304
	v_cvt_pk_bf16_f32 v2, v104, s0
	global_store_short v[4:5], v2, off offset:2560
	v_cvt_pk_bf16_f32 v2, v102, s0
	global_store_short v[4:5], v2, off offset:2816
	v_cvt_pk_bf16_f32 v2, v101, s0
	global_store_short v[4:5], v2, off offset:3072
	v_cvt_pk_bf16_f32 v2, v99, s0
	global_store_short v[4:5], v2, off offset:3328
	v_cvt_pk_bf16_f32 v2, v97, s0
	global_store_short v[4:5], v2, off offset:3584
	v_cvt_pk_bf16_f32 v2, v95, s0
	s_movk_i32 s38, 0x3000
	global_store_short v[4:5], v2, off offset:3840
	v_add_co_u32_e64 v2, s[90:91], s38, v106
	v_cvt_pk_bf16_f32 v4, v93, s0
	s_nop 0
	v_addc_co_u32_e64 v3, s[90:91], 0, v107, s[90:91]
	global_store_short v[2:3], v4, off
	v_cvt_pk_bf16_f32 v4, v91, s0
	global_store_short v[2:3], v4, off offset:256
	v_cvt_pk_bf16_f32 v4, v89, s0
	global_store_short v[2:3], v4, off offset:512
	v_cvt_pk_bf16_f32 v4, v87, s0
	global_store_short v[2:3], v4, off offset:768
	v_cvt_pk_bf16_f32 v4, v85, s0
	global_store_short v[2:3], v4, off offset:1024
	v_cvt_pk_bf16_f32 v4, v83, s0
	global_store_short v[2:3], v4, off offset:1280
	v_cvt_pk_bf16_f32 v4, v53, s0
	global_store_short v[2:3], v4, off offset:1536
	v_cvt_pk_bf16_f32 v4, v51, s0
	global_store_short v[2:3], v4, off offset:1792
	v_cvt_pk_bf16_f32 v4, v45, s0
	global_store_short v[2:3], v4, off offset:2048
	v_cvt_pk_bf16_f32 v4, v33, s0
	global_store_short v[2:3], v4, off offset:2304
	v_cvt_pk_bf16_f32 v4, v30, s0
	global_store_short v[2:3], v4, off offset:2560
	v_cvt_pk_bf16_f32 v4, v27, s0
	global_store_short v[2:3], v4, off offset:2816
	v_cvt_pk_bf16_f32 v4, v24, s0
	global_store_short v[2:3], v4, off offset:3072
	v_cvt_pk_bf16_f32 v4, v20, s0
	global_store_short v[2:3], v4, off offset:3328
	v_cvt_pk_bf16_f32 v4, v16, s0
	global_store_short v[2:3], v4, off offset:3584
	v_cvt_pk_bf16_f32 v4, v11, s0
	global_store_short v[2:3], v4, off offset:3840
	s_and_saveexec_b64 s[38:39], s[34:35]
	s_cbranch_execz .LBB0_329
	ds_read_b32 v4, v58 offset:52224
	v_lshlrev_b64 v[2:3], 8, v[48:49]
	v_lshl_add_u64 v[2:3], v[38:39], 0, v[2:3]
	s_waitcnt lgkmcnt(0)
	global_store_dword v[2:3], v4, off
	s_branch .LBB0_329
